# filter_gen a3 quad-interleaved layout with coalesced dwordx4 loads; prep_weights/transpose store waits relaxed; prep_weights WinT tile prefetch
# speedup vs baseline: 1.0243x; 1.0036x over previous
; __device__ void ph_prep_weights(const Params& P, int layer, float* sl) {
;     unsigned char* ws = P.ws;
;     const bool odd = (layer & 1);
;     for (int t = blockIdx.x; t < 2880; t += gridDim.x) {
;         if (t < 2048) { const int nt_ = t >> 4, kt = t & 15, n0 = nt_ * 64; int sc = n0;
;             if (odd) { const int half = n0 >> 12, j = n0 & 4095; sc = (j >> 10) * 2048 + half * 1024 + (j & 1023); }
;             prep_tile(P.in[2] + (size_t)layer * 1024 * 8192, 8192, (bf16_t*)(ws + WS_WIN), 1024, n0, sc, kt * 64, sl); }
.LBB0_22:
	v_readlane_b32 s0, v252, 54
	v_readlane_b32 s1, v252, 55
	s_andn2_b64 vcc, exec, s[0:1]
	s_cbranch_vccnz .LBB0_38
	s_mov_b32 s62, s28
	s_lshl_b64 s[0:1], s[62:63], 22
	s_lshl_b64 s[6:7], s[62:63], 20
	s_lshl_b64 s[10:11], s[62:63], 23
	s_lshl_b64 s[26:27], s[62:63], 25
	s_add_u32 s0, s74, s0
	s_addc_u32 s1, s75, s1
	s_add_u32 s6, s70, s6
	v_readlane_b32 s40, v252, 2
	s_addc_u32 s7, s71, s7
	v_readlane_b32 s46, v252, 8
	v_readlane_b32 s47, v252, 9
	s_add_u32 s12, s46, s10
	v_readlane_b32 s44, v252, 6
	s_addc_u32 s14, s47, s11
	v_readlane_b32 s45, v252, 7
	s_add_u32 s15, s44, s26
	s_mov_b64 s[38:39], s[30:31]
	v_readlane_b32 s18, v252, 53
	s_addc_u32 s17, s45, s27
	v_readlane_b32 s23, v252, 52
	v_readlane_b32 s26, v255, 3
	v_readlane_b32 s27, v254, 15
	v_readlane_b32 s28, v255, 0
	v_readlane_b32 s29, v254, 14
	s_mov_b32 s30, s2
	v_readlane_b32 s19, v254, 63
	v_readlane_b32 s31, v255, 1
	v_readlane_b32 s35, v255, 2
	v_readlane_b32 s37, v255, 4
	v_readlane_b32 s41, v252, 3
	v_readlane_b32 s42, v252, 4
	v_readlane_b32 s43, v252, 5
	v_readlane_b32 s48, v252, 10
	v_readlane_b32 s49, v252, 11
	v_readlane_b32 s50, v252, 12
	v_readlane_b32 s51, v252, 13
	v_readlane_b32 s52, v252, 14
	v_readlane_b32 s53, v252, 15
	v_readlane_b32 s54, v252, 16
	v_readlane_b32 s55, v252, 17
	s_mov_b32 s100, 0
	s_branch .LBB0_25

; __device__ __forceinline__ unsigned cvt_pk_bf16(float lo, float hi) { unsigned r; asm volatile("v_cvt_pk_bf16_f32 %0, %1, %2" : "=v"(r) : "v"(lo), "v"(hi)); return r; }
; __device__ __forceinline__ int otid() { int t = threadIdx.x; asm volatile("" : "+v"(t)); return t; }
; __device__ __forceinline__ float4 ntld_f4(const void* p) { const ntf4_t v = __builtin_nontemporal_load((const ntf4_t*)p); return make_float4(v.x, v.y, v.z, v.w); }
; __device__ void prep_tile(const float* __restrict__ src, int srcld, bf16_t* __restrict__ dst, int K, int n0, int srccol0, int k0, float* sl) {
;     const int tid = otid();
; #pragma unroll
;     for (int i = 0; i < 2; ++i) { const int idx = tid + NT * i, kk = idx >> 4, c4 = idx & 15;
;         const float4 v = ntld_f4(src + (size_t)(k0 + kk) * srcld + srccol0 + c4 * 4);
;         float* d = sl + kk * 65 + c4 * 4; d[0] = v.x; d[1] = v.y; d[2] = v.z; d[3] = v.w; }
;     __syncthreads();
;     { const int n = tid >> 3, kg = tid & 7; float f[8];
; #pragma unroll
;       for (int j = 0; j < 8; ++j) f[j] = sl[(kg * 8 + j) * 65 + n];
;       uint4 w; w.x = pg8::cvt_pk_bf16(f[0], f[1]); w.y = pg8::cvt_pk_bf16(f[2], f[3]); w.z = pg8::cvt_pk_bf16(f[4], f[5]); w.w = pg8::cvt_pk_bf16(f[6], f[7]);
;       *(uint4*)(dst + (size_t)(n0 + n) * K + k0 + kg * 8) = w; }
;     __syncthreads();
; }
; __device__ void ph_prep_weights(const Params& P, int layer, float* sl) {
;     ...
;         else if (t < 2624) { const int q = t - 2560, nt_ = q >> 2, kt = q & 3;
;             prep_tile(P.in[19] + (size_t)layer * 256 * 1024, 1024, (bf16_t*)(ws + WS_PPROJ), 256, nt_ * 64, nt_ * 64, kt * 64, sl); }
;         else { const int q = t - 2624, nt_ = q >> 4, kt = q & 15;
;             prep_tile(P.in[21] + (size_t)layer * 1024 * 1024, 1024, (bf16_t*)(ws + WS_PGATE), 1024, nt_ * 64, nt_ * 64, kt * 64, sl); }
.LBB0_25:
	s_cmpk_gt_i32 s30, 0x7ff
	s_mov_b64 s[10:11], -1
	s_cbranch_scc0 .LBB0_35
	s_cmpk_gt_u32 s30, 0x9ff
	s_cbranch_scc0 .LBB0_32
	s_cmpk_gt_u32 s30, 0xa3f
	s_cbranch_scc0 .LBB0_29
	s_and_b32 s10, s29, 0x7fffffc0
	s_add_i32 s62, s10, 0xffffd700
	v_mov_b32_e32 v8, v195
	s_and_b32 s24, s27, 0x3c0
	s_lshl_b64 s[10:11], s[62:63], 2
	s_nop 0
	v_lshlrev_b32_e32 v0, 4, v8
	v_ashrrev_i32_e32 v11, 4, v8
	s_add_u32 s10, s0, s10
	v_and_b32_e32 v192, 0xf0, v0
	v_add_u32_e32 v0, s24, v11
	v_add_u32_e32 v6, 0x200, v8
	s_addc_u32 s11, s1, s11
	v_ashrrev_i32_e32 v1, 31, v0
	v_ashrrev_i32_e32 v14, 4, v6
	v_lshl_add_u64 v[4:5], s[10:11], 0, v[192:193]
	v_lshlrev_b64 v[0:1], 12, v[0:1]
	v_add_u32_e32 v6, s24, v14
	v_lshl_add_u64 v[0:1], v[4:5], 0, v[0:1]
	v_ashrrev_i32_e32 v7, 31, v6
	global_load_dwordx4 v[0:3], v[0:1], off nt
	v_lshlrev_b64 v[6:7], 12, v[6:7]
	v_lshl_add_u64 v[4:5], v[4:5], 0, v[6:7]
	global_load_dwordx4 v[4:7], v[4:5], off nt
	v_ashrrev_i32_e32 v9, 3, v8
	v_lshlrev_b32_e32 v8, 3, v8
	v_and_b32_e32 v15, 56, v8
	v_add_u32_e32 v8, s62, v9
	v_add_u32_e32 v10, 0, v192
	s_lshl_b32 s62, s24, 1
	s_movk_i32 s24, 0x104
	v_lshlrev_b32_e32 v16, 2, v9
	v_mul_u32_u24_e32 v17, 0x104, v15
	v_mad_u64_u32 v[12:13], s[10:11], v11, s24, v[10:11]
	v_mad_u64_u32 v[10:11], s[10:11], v14, s24, v[10:11]
	v_add3_u32 v11, 0, v16, v17
	v_ashrrev_i32_e32 v9, 31, v8
	v_add_u32_e32 v13, 0x400, v11
	v_readlane_b32 s10, v254, 49
	v_lshlrev_b64 v[8:9], 11, v[8:9]
	v_readlane_b32 s11, v254, 50
	v_lshlrev_b32_e32 v192, 1, v15
	s_waitcnt vmcnt(1)
	ds_write2_b32 v12, v0, v1 offset1:1
	ds_write2_b32 v12, v2, v3 offset0:2 offset1:3
	s_waitcnt vmcnt(0)
	ds_write2_b32 v10, v4, v5 offset1:1
	ds_write2_b32 v10, v6, v7 offset0:2 offset1:3
	s_waitcnt lgkmcnt(0)
	s_barrier
	ds_read2_b32 v[0:1], v11 offset1:65
	ds_read2_b32 v[2:3], v11 offset0:130 offset1:195
	ds_read2_b32 v[4:5], v13 offset0:4 offset1:69
	ds_read2_b32 v[6:7], v13 offset0:134 offset1:199
	v_lshl_add_u64 v[8:9], s[10:11], 0, v[8:9]
	v_lshl_add_u64 v[8:9], v[8:9], 0, s[62:63]
	v_lshl_add_u64 v[8:9], v[8:9], 0, v[192:193]
	s_waitcnt lgkmcnt(3)
	v_cvt_pk_bf16_f32 v0, v0, v1
	s_waitcnt lgkmcnt(2)
	v_cvt_pk_bf16_f32 v1, v2, v3
	s_waitcnt lgkmcnt(1)
	v_cvt_pk_bf16_f32 v2, v4, v5
	s_waitcnt lgkmcnt(0)
	v_cvt_pk_bf16_f32 v3, v6, v7
	global_store_dwordx4 v[8:9], v[0:3], off
	s_barrier
	s_mov_b64 s[10:11], 0
.LBB0_29:
	s_andn2_b64 vcc, exec, s[10:11]
	s_cbranch_vccnz .LBB0_31
	s_and_b32 s10, s28, 0xffc0
	s_add_i32 s62, s10, 0xffff6000
	v_mov_b32_e32 v8, v195
	s_and_b32 s24, s27, 0xc0
	s_lshl_b64 s[10:11], s[62:63], 2
	s_nop 0
	v_lshlrev_b32_e32 v0, 4, v8
	v_ashrrev_i32_e32 v11, 4, v8
	s_add_u32 s10, s6, s10
	v_and_b32_e32 v192, 0xf0, v0
	v_add_u32_e32 v0, s24, v11
	v_add_u32_e32 v6, 0x200, v8
	s_addc_u32 s11, s7, s11
	v_ashrrev_i32_e32 v1, 31, v0
	v_ashrrev_i32_e32 v14, 4, v6
	v_lshl_add_u64 v[4:5], s[10:11], 0, v[192:193]
	v_lshlrev_b64 v[0:1], 12, v[0:1]
	v_add_u32_e32 v6, s24, v14
	v_lshl_add_u64 v[0:1], v[4:5], 0, v[0:1]
	v_ashrrev_i32_e32 v7, 31, v6
	global_load_dwordx4 v[0:3], v[0:1], off nt
	v_lshlrev_b64 v[6:7], 12, v[6:7]
	v_lshl_add_u64 v[4:5], v[4:5], 0, v[6:7]
	global_load_dwordx4 v[4:7], v[4:5], off nt
	v_ashrrev_i32_e32 v9, 3, v8
	v_lshlrev_b32_e32 v8, 3, v8
	v_and_b32_e32 v15, 56, v8
	v_add_u32_e32 v8, s62, v9
	v_add_u32_e32 v10, 0, v192
	s_lshl_b32 s62, s24, 1
	s_movk_i32 s24, 0x104
	v_lshlrev_b32_e32 v16, 2, v9
	v_mul_u32_u24_e32 v17, 0x104, v15
	v_mad_u64_u32 v[12:13], s[10:11], v11, s24, v[10:11]
	v_mad_u64_u32 v[10:11], s[10:11], v14, s24, v[10:11]
	v_add3_u32 v11, 0, v16, v17
	v_ashrrev_i32_e32 v9, 31, v8
	v_add_u32_e32 v13, 0x400, v11
	v_readlane_b32 s10, v252, 46
	v_lshlrev_b64 v[8:9], 9, v[8:9]
	v_readlane_b32 s11, v252, 47
	v_lshlrev_b32_e32 v192, 1, v15
	s_waitcnt vmcnt(1)
	ds_write2_b32 v12, v0, v1 offset1:1
	ds_write2_b32 v12, v2, v3 offset0:2 offset1:3
	s_waitcnt vmcnt(0)
	ds_write2_b32 v10, v4, v5 offset1:1
	ds_write2_b32 v10, v6, v7 offset0:2 offset1:3
	s_waitcnt lgkmcnt(0)
	s_barrier
	ds_read2_b32 v[0:1], v11 offset1:65
	ds_read2_b32 v[2:3], v11 offset0:130 offset1:195
	ds_read2_b32 v[4:5], v13 offset0:4 offset1:69
	ds_read2_b32 v[6:7], v13 offset0:134 offset1:199
	v_lshl_add_u64 v[8:9], s[10:11], 0, v[8:9]
	v_lshl_add_u64 v[8:9], v[8:9], 0, s[62:63]
	v_lshl_add_u64 v[8:9], v[8:9], 0, v[192:193]
	s_waitcnt lgkmcnt(3)
	v_cvt_pk_bf16_f32 v0, v0, v1
	s_waitcnt lgkmcnt(2)
	v_cvt_pk_bf16_f32 v1, v2, v3
	s_waitcnt lgkmcnt(1)
	v_cvt_pk_bf16_f32 v2, v4, v5
	s_waitcnt lgkmcnt(0)
	v_cvt_pk_bf16_f32 v3, v6, v7
	global_store_dwordx4 v[8:9], v[0:3], off
	s_barrier

; __device__ __forceinline__ unsigned cvt_pk_bf16(float lo, float hi) { unsigned r; asm volatile("v_cvt_pk_bf16_f32 %0, %1, %2" : "=v"(r) : "v"(lo), "v"(hi)); return r; }
; __device__ __forceinline__ int otid() { int t = threadIdx.x; asm volatile("" : "+v"(t)); return t; }
; __device__ __forceinline__ float4 ntld_f4(const void* p) { const ntf4_t v = __builtin_nontemporal_load((const ntf4_t*)p); return make_float4(v.x, v.y, v.z, v.w); }
; __device__ void prep_tile(const float* __restrict__ src, int srcld, bf16_t* __restrict__ dst, int K, int n0, int srccol0, int k0, float* sl) {
;     const int tid = otid();
; #pragma unroll
;     for (int i = 0; i < 2; ++i) { const int idx = tid + NT * i, kk = idx >> 4, c4 = idx & 15;
;         const float4 v = ntld_f4(src + (size_t)(k0 + kk) * srcld + srccol0 + c4 * 4);
;         float* d = sl + kk * 65 + c4 * 4; d[0] = v.x; d[1] = v.y; d[2] = v.z; d[3] = v.w; }
;     __syncthreads();
;     { const int n = tid >> 3, kg = tid & 7; float f[8];
; #pragma unroll
;       for (int j = 0; j < 8; ++j) f[j] = sl[(kg * 8 + j) * 65 + n];
;       uint4 w; w.x = pg8::cvt_pk_bf16(f[0], f[1]); w.y = pg8::cvt_pk_bf16(f[2], f[3]); w.z = pg8::cvt_pk_bf16(f[4], f[5]); w.w = pg8::cvt_pk_bf16(f[6], f[7]);
;       *(uint4*)(dst + (size_t)(n0 + n) * K + k0 + kg * 8) = w; }
;     __syncthreads();
; }
; __device__ void ph_prep_weights(const Params& P, int layer, float* sl) {
;     ...
;         else if (t < 2560) { const int q = t - 2048, nt_ = q >> 5, kt = q & 31;
;             prep_tile(P.in[3] + (size_t)layer * 2048 * 1024, 1024, (bf16_t*)(ws + WS_WOUT), 2048, nt_ * 64, nt_ * 64, kt * 64, sl); }
.LBB0_32:
	s_andn2_b64 vcc, exec, s[10:11]
	s_cbranch_vccnz .LBB0_34
	s_and_b32 s10, s26, 0x1fc0
	s_add_i32 s62, s10, 0xfffff000
	v_mov_b32_e32 v8, v195
	s_and_b32 s24, s27, 0x7c0
	s_lshl_b64 s[10:11], s[62:63], 2
	s_nop 0
	v_lshlrev_b32_e32 v0, 4, v8
	v_ashrrev_i32_e32 v11, 4, v8
	s_add_u32 s10, s12, s10
	v_and_b32_e32 v192, 0xf0, v0
	v_add_u32_e32 v0, s24, v11
	v_add_u32_e32 v6, 0x200, v8
	s_addc_u32 s11, s14, s11
	v_ashrrev_i32_e32 v1, 31, v0
	v_ashrrev_i32_e32 v14, 4, v6
	v_lshl_add_u64 v[4:5], s[10:11], 0, v[192:193]
	v_lshlrev_b64 v[0:1], 12, v[0:1]
	v_add_u32_e32 v6, s24, v14
	v_lshl_add_u64 v[0:1], v[4:5], 0, v[0:1]
	v_ashrrev_i32_e32 v7, 31, v6
	global_load_dwordx4 v[0:3], v[0:1], off nt
	v_lshlrev_b64 v[6:7], 12, v[6:7]
	v_lshl_add_u64 v[4:5], v[4:5], 0, v[6:7]
	global_load_dwordx4 v[4:7], v[4:5], off nt
	v_ashrrev_i32_e32 v9, 3, v8
	v_lshlrev_b32_e32 v8, 3, v8
	v_and_b32_e32 v15, 56, v8
	v_add_u32_e32 v8, s62, v9
	v_add_u32_e32 v10, 0, v192
	s_lshl_b32 s62, s24, 1
	s_movk_i32 s24, 0x104
	v_lshlrev_b32_e32 v16, 2, v9
	v_mul_u32_u24_e32 v17, 0x104, v15
	v_mad_u64_u32 v[12:13], s[10:11], v11, s24, v[10:11]
	v_mad_u64_u32 v[10:11], s[10:11], v14, s24, v[10:11]
	v_add3_u32 v11, 0, v16, v17
	v_ashrrev_i32_e32 v9, 31, v8
	v_add_u32_e32 v13, 0x400, v11
	v_readlane_b32 s10, v252, 44
	v_lshlrev_b64 v[8:9], 12, v[8:9]
	v_readlane_b32 s11, v252, 45
	v_lshlrev_b32_e32 v192, 1, v15
	s_waitcnt vmcnt(1)
	ds_write2_b32 v12, v0, v1 offset1:1
	ds_write2_b32 v12, v2, v3 offset0:2 offset1:3
	s_waitcnt vmcnt(0)
	ds_write2_b32 v10, v4, v5 offset1:1
	ds_write2_b32 v10, v6, v7 offset0:2 offset1:3
	s_waitcnt lgkmcnt(0)
	s_barrier
	ds_read2_b32 v[0:1], v11 offset1:65
	ds_read2_b32 v[2:3], v11 offset0:130 offset1:195
	ds_read2_b32 v[4:5], v13 offset0:4 offset1:69
	ds_read2_b32 v[6:7], v13 offset0:134 offset1:199
	v_lshl_add_u64 v[8:9], s[10:11], 0, v[8:9]
	v_lshl_add_u64 v[8:9], v[8:9], 0, s[62:63]
	v_lshl_add_u64 v[8:9], v[8:9], 0, v[192:193]
	s_waitcnt lgkmcnt(3)
	v_cvt_pk_bf16_f32 v0, v0, v1
	s_waitcnt lgkmcnt(2)
	v_cvt_pk_bf16_f32 v1, v2, v3
	s_waitcnt lgkmcnt(1)
	v_cvt_pk_bf16_f32 v2, v4, v5
	s_waitcnt lgkmcnt(0)
	v_cvt_pk_bf16_f32 v3, v6, v7
	global_store_dwordx4 v[8:9], v[0:3], off
	s_barrier

; __device__ __forceinline__ unsigned cvt_pk_bf16(float lo, float hi) { unsigned r; asm volatile("v_cvt_pk_bf16_f32 %0, %1, %2" : "=v"(r) : "v"(lo), "v"(hi)); return r; }
; __device__ __forceinline__ int otid() { int t = threadIdx.x; asm volatile("" : "+v"(t)); return t; }
; __device__ __forceinline__ float4 ntld_f4(const void* p) { const ntf4_t v = __builtin_nontemporal_load((const ntf4_t*)p); return make_float4(v.x, v.y, v.z, v.w); }
; __device__ void prep_tile(const float* __restrict__ src, int srcld, bf16_t* __restrict__ dst, int K, int n0, int srccol0, int k0, float* sl) {
;     const int tid = otid();
; #pragma unroll
;     for (int i = 0; i < 2; ++i) { const int idx = tid + NT * i, kk = idx >> 4, c4 = idx & 15;
;         const float4 v = ntld_f4(src + (size_t)(k0 + kk) * srcld + srccol0 + c4 * 4);
;         float* d = sl + kk * 65 + c4 * 4; d[0] = v.x; d[1] = v.y; d[2] = v.z; d[3] = v.w; }
;     __syncthreads();
;     { const int n = tid >> 3, kg = tid & 7; float f[8];
; #pragma unroll
;       for (int j = 0; j < 8; ++j) f[j] = sl[(kg * 8 + j) * 65 + n];
;       uint4 w; w.x = pg8::cvt_pk_bf16(f[0], f[1]); w.y = pg8::cvt_pk_bf16(f[2], f[3]); w.z = pg8::cvt_pk_bf16(f[4], f[5]); w.w = pg8::cvt_pk_bf16(f[6], f[7]);
;       *(uint4*)(dst + (size_t)(n0 + n) * K + k0 + kg * 8) = w; }
;     __syncthreads();
; }
; __device__ void ph_prep_weights(const Params& P, int layer, float* sl) {
;     ...
;         if (t < 2048) { const int nt_ = t >> 4, kt = t & 15, n0 = nt_ * 64; int sc = n0;
;             if (odd) { const int half = n0 >> 12, j = n0 & 4095; sc = (j >> 10) * 2048 + half * 1024 + (j & 1023); }
;             prep_tile(P.in[2] + (size_t)layer * 1024 * 8192, 8192, (bf16_t*)(ws + WS_WIN), 1024, n0, sc, kt * 64, sl); }
.LBB0_35:
	s_andn2_b64 vcc, exec, s[10:11]
	s_cbranch_vccnz .LBB0_24
	s_and_b32 s10, s23, 0x1800
	s_and_b32 s11, s30, 0xfffffc00
	s_add_i32 s10, s10, s11
	s_and_b32 s11, s29, 0x3c0
	s_or_b32 s25, s10, s11
	v_readlane_b32 s10, v255, 45
	s_and_b32 s24, s29, 0xffffffc0
	v_readlane_b32 s11, v255, 46
	s_and_b64 s[10:11], s[10:11], exec
	s_cselect_b32 s10, s24, s25
	v_mov_b32_e32 v8, v195
	s_ashr_i32 s11, s10, 31
	s_and_b32 s25, s27, 0x3c0
	s_lshl_b64 s[10:11], s[10:11], 2
	s_nop 0
	v_lshlrev_b32_e32 v0, 4, v8
	v_ashrrev_i32_e32 v11, 4, v8
	s_add_u32 s10, s15, s10
	v_and_b32_e32 v192, 0xf0, v0
	v_add_u32_e32 v0, s25, v11
	v_add_u32_e32 v6, 0x200, v8
	s_addc_u32 s11, s17, s11
	v_ashrrev_i32_e32 v1, 31, v0
	v_ashrrev_i32_e32 v14, 4, v6
	v_lshl_add_u64 v[4:5], s[10:11], 0, v[192:193]
	v_lshlrev_b64 v[0:1], 15, v[0:1]
	v_add_u32_e32 v6, s25, v14
	v_lshl_add_u64 v[0:1], v[4:5], 0, v[0:1]
	v_ashrrev_i32_e32 v7, 31, v6
	v_lshlrev_b64 v[6:7], 15, v[6:7]
	v_lshl_add_u64 v[4:5], v[4:5], 0, v[6:7]
	s_cmp_eq_u32 s100, 1
	s_cbranch_scc1 .Lpw_havepf
	global_load_dwordx4 v[20:23], v[0:1], off nt
	global_load_dwordx4 v[24:27], v[4:5], off nt
.Lpw_havepf:
	v_ashrrev_i32_e32 v9, 3, v8
	v_lshlrev_b32_e32 v8, 3, v8
	v_and_b32_e32 v15, 56, v8
	v_add_u32_e32 v8, s24, v9
	v_add_u32_e32 v10, 0, v192
	s_movk_i32 s24, 0x104
	v_lshlrev_b32_e32 v16, 2, v9
	v_mul_u32_u24_e32 v17, 0x104, v15
	v_mad_u64_u32 v[12:13], s[10:11], v11, s24, v[10:11]
	v_mad_u64_u32 v[10:11], s[10:11], v14, s24, v[10:11]
	v_add3_u32 v11, 0, v16, v17
	v_ashrrev_i32_e32 v9, 31, v8
	v_add_u32_e32 v13, 0x400, v11
	v_readlane_b32 s10, v252, 42
	v_lshlrev_b64 v[8:9], 11, v[8:9]
	v_readlane_b32 s11, v252, 43
	s_lshl_b32 s62, s25, 1
	v_lshlrev_b32_e32 v192, 1, v15
	v_lshl_add_u64 v[8:9], s[10:11], 0, v[8:9]
	v_lshl_add_u64 v[8:9], v[8:9], 0, s[62:63]
	v_lshl_add_u64 v[8:9], v[8:9], 0, v[192:193]
	s_cmp_eq_u32 s100, 1
	s_cbranch_scc1 .Lpw_w_pf
	s_waitcnt vmcnt(0)
	s_branch .Lpw_w_done
.Lpw_w_pf:
	s_waitcnt vmcnt(1)
.Lpw_w_done:
	ds_write2_b32 v12, v20, v21 offset1:1
	ds_write2_b32 v12, v22, v23 offset0:2 offset1:3
	ds_write2_b32 v10, v24, v25 offset1:1
	ds_write2_b32 v10, v26, v27 offset0:2 offset1:3
	s_waitcnt lgkmcnt(0)
	s_barrier
	s_add_i32 s101, s30, s22
	s_mov_b32 s100, 0
	s_cmpk_lt_i32 s101, 0x800
	s_cbranch_scc0 .Lpw_nopf
	s_add_i32 s10, s23, s18
	s_and_b32 s10, s10, 0x1800
	s_and_b32 s11, s101, 0xfffffc00
	s_add_i32 s10, s10, s11
	s_add_i32 s101, s29, s19
	s_and_b32 s11, s101, 0x3c0
	s_or_b32 s25, s10, s11
	v_readlane_b32 s10, v255, 45
	s_and_b32 s24, s101, 0xffffffc0
	v_readlane_b32 s11, v255, 46
	s_and_b64 s[10:11], s[10:11], exec
	s_cselect_b32 s10, s24, s25
	s_ashr_i32 s11, s10, 31
	s_add_i32 s25, s27, s35
	s_and_b32 s25, s25, 0x3c0
	s_lshl_b64 s[10:11], s[10:11], 2
	s_add_u32 s10, s15, s10
	s_addc_u32 s11, s17, s11
	v_lshlrev_b32_e32 v28, 4, v195
	v_and_b32_e32 v28, 0xf0, v28
	v_mov_b32_e32 v29, 0
	v_lshl_add_u64 v[30:31], s[10:11], 0, v[28:29]
	v_ashrrev_i32_e32 v32, 4, v195
	v_add_u32_e32 v32, s25, v32
	v_ashrrev_i32_e32 v33, 31, v32
	v_lshlrev_b64 v[32:33], 15, v[32:33]
	v_lshl_add_u64 v[32:33], v[30:31], 0, v[32:33]
	global_load_dwordx4 v[20:23], v[32:33], off nt
	v_add_u32_e32 v34, 0x200, v195
	v_ashrrev_i32_e32 v34, 4, v34
	v_add_u32_e32 v34, s25, v34
	v_ashrrev_i32_e32 v35, 31, v34
	v_lshlrev_b64 v[34:35], 15, v[34:35]
	v_lshl_add_u64 v[34:35], v[30:31], 0, v[34:35]
	global_load_dwordx4 v[24:27], v[34:35], off nt
	s_mov_b32 s100, 1
.Lpw_nopf:
	ds_read2_b32 v[0:1], v11 offset1:65
	ds_read2_b32 v[2:3], v11 offset0:130 offset1:195
	ds_read2_b32 v[4:5], v13 offset0:4 offset1:69
	ds_read2_b32 v[6:7], v13 offset0:134 offset1:199
	s_waitcnt lgkmcnt(3)
	v_cvt_pk_bf16_f32 v0, v0, v1
	s_waitcnt lgkmcnt(2)
	v_cvt_pk_bf16_f32 v1, v2, v3
	s_waitcnt lgkmcnt(1)
	v_cvt_pk_bf16_f32 v2, v4, v5
	s_waitcnt lgkmcnt(0)
	v_cvt_pk_bf16_f32 v3, v6, v7
	global_store_dwordx4 v[8:9], v[0:3], off
	s_barrier
	s_branch .LBB0_24

; __device__ void ph_filter_mlp(const Params& P, int j, float* __restrict__ a3) {
;     ...
;         a = sinf(fq * acc);
;         a3[pos * 64 + lane] = a;
.LBB0_44:
	s_or_b64 exec, exec, s[10:11]
	v_mul_f32_e32 v19, v18, v18
	v_fmamk_f32 v20, v19, 0xb94c1982, v227
	v_fmaak_f32 v20, v19, v20, 0xbe2aaa9d
	v_mul_f32_e32 v20, v19, v20
	v_fmac_f32_e32 v18, v18, v20
	v_fmamk_f32 v20, v19, 0x37d75334, v228
	v_fmaak_f32 v20, v19, v20, 0x3d2aabf7
	v_fmaak_f32 v20, v19, v20, 0xbf000004
	v_fma_f32 v19, v19, v20, 1.0
	v_and_b32_e32 v20, 1, v17
	v_lshlrev_b32_e32 v17, 30, v17
	v_cmp_eq_u32_e32 vcc, 0, v20
	v_and_b32_e32 v17, 0x80000000, v17
	v_xor_b32_e32 v7, v7, v6
	v_cndmask_b32_e32 v18, v19, v18, vcc
	v_xor_b32_e32 v7, v7, v17
	v_xor_b32_e32 v7, v7, v18
	v_cmp_class_f32_e64 vcc, v6, s14
	v_lshrrev_b32_e32 v6, 2, v9
	v_and_b32_e32 v19, 3, v9
	v_lshl_or_b32 v6, v6, 14, v19
	v_lshl_or_b32 v6, v8, 2, v6
	v_readlane_b32 s0, v252, 50
	v_add_u32_e32 v8, s12, v8
	v_cndmask_b32_e32 v17, v243, v7, vcc
	v_ashrrev_i32_e32 v7, 31, v6
	v_readlane_b32 s1, v252, 51
	v_cmp_lt_i32_e32 vcc, s9, v8
	s_or_b64 s[52:53], vcc, s[52:53]
	v_lshl_add_u64 v[6:7], v[6:7], 2, s[0:1]
	global_store_dword v[6:7], v17, off
	s_andn2_b64 exec, exec, s[52:53]
	s_cbranch_execz .LBB0_81

; __device__ void ph_filter_gen(const Params& P, int j, const float* __restrict__ a3, float* __restrict__ kf, float* sl) {
;     ...
;     for (int c = blockIdx.x; c < 1024; c += gridDim.x) {
;         if (tid < 256) { const int jj = tid >> 2, q = tid & 3; sw[tid] = w4[(size_t)jj * 4096 + q * 1024 + c]; }
;         __syncthreads();
;         const float delta = fabsf(min_decay + (float)c * ((max_decay - min_decay) / 1023.0f));
;         float hv[8][4]; float n0 = 0.f, n1 = 0.f;
; #pragma unroll
;         for (int i = 0; i < 8; ++i) { const int t = tid + NT * i; const float4* ar = (const float4*)(a3 + (size_t)t * 64);
;             float a0 = 0.f, a1 = 0.f, a2 = 0.f, a3v = 0.f;
; #pragma unroll 4
;             for (int jq = 0; jq < 16; ++jq) { const float4 av = ar[jq]; const float ae[4] = {av.x, av.y, av.z, av.w};
; #pragma unroll
;                 for (int e = 0; e < 4; ++e) { const float4 wv = *(const float4*)(sw + (jq * 4 + e) * 4); a0 += ae[e] * wv.x; a1 += ae[e] * wv.y; a2 += ae[e] * wv.z; a3v += ae[e] * wv.w; } }
.LBB0_220:
	s_or_b64 exec, exec, s[10:11]
	v_mov_b32_e32 v38, 0
	s_mov_b32 s0, 0
	s_mov_b64 s[14:15], 0
	v_mov_b32_e32 v39, v38
	v_mov_b32_e32 v36, v38
	v_mov_b32_e32 v37, v38
	s_waitcnt lgkmcnt(0)
	s_barrier
	v_lshlrev_b32_e32 v113, 2, v68
	s_add_u32 s100, s78, 0x1e800000
	s_addc_u32 s101, s79, 0
	global_load_dwordx4 v[116:119], v113, s[100:101]
	s_add_u32 s100, s100, 0x10000
	s_addc_u32 s101, s101, 0
	global_load_dwordx4 v[120:123], v113, s[100:101]
	s_add_u32 s100, s100, 0x10000
	s_addc_u32 s101, s101, 0
	global_load_dwordx4 v[124:127], v113, s[100:101]
	s_add_u32 s100, s100, 0x10000
	s_addc_u32 s101, s101, 0
	global_load_dwordx4 v[128:131], v113, s[100:101]
	s_add_u32 s100, s78, 0x1e840000
	s_addc_u32 s101, s79, 0
	global_load_dwordx4 v[132:135], v113, s[100:101]
	s_add_u32 s100, s100, 0x10000
	s_addc_u32 s101, s101, 0
	global_load_dwordx4 v[136:139], v113, s[100:101]
	s_add_u32 s100, s100, 0x10000
	s_addc_u32 s101, s101, 0
	global_load_dwordx4 v[140:143], v113, s[100:101]
	s_add_u32 s100, s100, 0x10000
	s_addc_u32 s101, s101, 0
	global_load_dwordx4 v[144:147], v113, s[100:101]
	s_add_u32 s100, s78, 0x1e880000
	s_addc_u32 s101, s79, 0
	global_load_dwordx4 v[148:151], v113, s[100:101]
	s_add_u32 s100, s100, 0x10000
	s_addc_u32 s101, s101, 0
	global_load_dwordx4 v[152:155], v113, s[100:101]
	s_add_u32 s100, s100, 0x10000
	s_addc_u32 s101, s101, 0
	global_load_dwordx4 v[156:159], v113, s[100:101]
	s_add_u32 s100, s100, 0x10000
	s_addc_u32 s101, s101, 0
	global_load_dwordx4 v[160:163], v113, s[100:101]
	s_add_u32 s100, s78, 0x1e8c0000
	s_addc_u32 s101, s79, 0
	global_load_dwordx4 v[164:167], v113, s[100:101]
	s_add_u32 s100, s100, 0x10000
	s_addc_u32 s101, s101, 0
	global_load_dwordx4 v[168:171], v113, s[100:101]
	s_add_u32 s100, s100, 0x10000
	s_addc_u32 s101, s101, 0
	global_load_dwordx4 v[172:175], v113, s[100:101]
	s_add_u32 s100, s100, 0x10000
	s_addc_u32 s101, s101, 0
	global_load_dwordx4 v[176:179], v113, s[100:101]
.LBB0_221:
	v_lshlrev_b32_e32 v113, 2, v68
	v_add_u32_e32 v113, 0x2000, v113
	s_waitcnt vmcnt(12)
	v_mov_b32_e32 v82, 0
	ds_read_b128 v[56:59], v82
	ds_read_b128 v[60:63], v82 offset:16
	ds_read_b128 v[64:67], v82 offset:32
	ds_read_b128 v[78:81], v82 offset:48
	s_waitcnt lgkmcnt(3)
	v_pk_fma_f32 v[38:39], v[116:117], v[56:57], v[38:39] op_sel_hi:[0,1,1]
	v_pk_fma_f32 v[36:37], v[116:117], v[58:59], v[36:37] op_sel_hi:[0,1,1]
	s_waitcnt lgkmcnt(2)
	v_pk_fma_f32 v[38:39], v[116:117], v[60:61], v[38:39] op_sel:[1,0,0]
	v_pk_fma_f32 v[36:37], v[116:117], v[62:63], v[36:37] op_sel:[1,0,0]
	s_waitcnt lgkmcnt(1)
	v_pk_fma_f32 v[38:39], v[118:119], v[64:65], v[38:39] op_sel_hi:[0,1,1]
	v_mov_b32_e32 v56, v119
	v_pk_fma_f32 v[36:37], v[118:119], v[66:67], v[36:37] op_sel_hi:[0,1,1]
	s_waitcnt lgkmcnt(0)
	v_pk_fma_f32 v[60:61], v[56:57], v[78:79], v[38:39] op_sel_hi:[0,1,1]
	v_pk_fma_f32 v[64:65], v[56:57], v[80:81], v[36:37] op_sel_hi:[0,1,1]
	ds_read_b128 v[36:39], v82 offset:64
	ds_read_b128 v[40:43], v82 offset:80
	ds_read_b128 v[56:59], v82 offset:96
	s_waitcnt lgkmcnt(2)
	v_pk_fma_f32 v[36:37], v[120:121], v[36:37], v[60:61] op_sel_hi:[0,1,1]
	ds_read_b128 v[60:63], v82 offset:112
	s_waitcnt lgkmcnt(2)
	v_pk_fma_f32 v[36:37], v[120:121], v[40:41], v[36:37] op_sel:[1,0,0]
	v_mov_b32_e32 v40, v123
	s_waitcnt lgkmcnt(1)
	v_pk_fma_f32 v[36:37], v[122:123], v[56:57], v[36:37] op_sel_hi:[0,1,1]
	s_waitcnt lgkmcnt(0)
	v_pk_fma_f32 v[56:57], v[40:41], v[60:61], v[36:37] op_sel_hi:[0,1,1]
	v_pk_fma_f32 v[36:37], v[120:121], v[38:39], v[64:65] op_sel_hi:[0,1,1]
	v_pk_fma_f32 v[36:37], v[120:121], v[42:43], v[36:37] op_sel:[1,0,0]
	s_nop 0
	v_pk_fma_f32 v[36:37], v[122:123], v[58:59], v[36:37] op_sel_hi:[0,1,1]
	v_pk_fma_f32 v[60:61], v[40:41], v[62:63], v[36:37] op_sel_hi:[0,1,1]
	ds_read_b128 v[36:39], v82 offset:128
	ds_read_b128 v[40:43], v82 offset:144
	ds_read_b128 v[52:55], v82 offset:160
	s_waitcnt lgkmcnt(2)
	v_pk_fma_f32 v[36:37], v[124:125], v[36:37], v[56:57] op_sel_hi:[0,1,1]
	ds_read_b128 v[56:59], v82 offset:176
	v_pk_fma_f32 v[38:39], v[124:125], v[38:39], v[60:61] op_sel_hi:[0,1,1]
	s_waitcnt lgkmcnt(2)
	v_pk_fma_f32 v[36:37], v[124:125], v[40:41], v[36:37] op_sel:[1,0,0]
	v_pk_fma_f32 v[38:39], v[124:125], v[42:43], v[38:39] op_sel:[1,0,0]
	s_waitcnt lgkmcnt(1)
	v_pk_fma_f32 v[36:37], v[126:127], v[52:53], v[36:37] op_sel_hi:[0,1,1]
	v_mov_b32_e32 v40, v127
	v_pk_fma_f32 v[38:39], v[126:127], v[54:55], v[38:39] op_sel_hi:[0,1,1]
	s_waitcnt lgkmcnt(0)
	v_pk_fma_f32 v[36:37], v[40:41], v[56:57], v[36:37] op_sel_hi:[0,1,1]
	v_pk_fma_f32 v[42:43], v[40:41], v[58:59], v[38:39] op_sel_hi:[0,1,1]
	ds_read_b128 v[38:41], v82 offset:192
	ds_read_b128 v[48:51], v82 offset:208
	ds_read_b128 v[52:55], v82 offset:224
	ds_read_b128 v[56:59], v82 offset:240
	s_waitcnt lgkmcnt(3)
	v_pk_fma_f32 v[36:37], v[128:129], v[38:39], v[36:37] op_sel_hi:[0,1,1]
	s_waitcnt lgkmcnt(2)
	v_pk_fma_f32 v[36:37], v[128:129], v[48:49], v[36:37] op_sel:[1,0,0]
	v_mov_b32_e32 v48, v131
	s_waitcnt lgkmcnt(1)
	v_pk_fma_f32 v[36:37], v[130:131], v[52:53], v[36:37] op_sel_hi:[0,1,1]
	s_waitcnt lgkmcnt(0)
	v_pk_fma_f32 v[38:39], v[48:49], v[56:57], v[36:37] op_sel_hi:[0,1,1]
	v_pk_fma_f32 v[36:37], v[128:129], v[40:41], v[42:43] op_sel_hi:[0,1,1]
	v_pk_fma_f32 v[36:37], v[128:129], v[50:51], v[36:37] op_sel:[1,0,0]
	s_nop 0
	v_pk_fma_f32 v[36:37], v[130:131], v[54:55], v[36:37] op_sel_hi:[0,1,1]
	v_pk_fma_f32 v[36:37], v[48:49], v[58:59], v[36:37] op_sel_hi:[0,1,1]
	s_add_u32 s100, s78, 0x1e800000
	s_addc_u32 s101, s79, 0
	global_load_dwordx4 v[116:119], v113, s[100:101]
	s_add_u32 s100, s100, 0x10000
	s_addc_u32 s101, s101, 0
	global_load_dwordx4 v[120:123], v113, s[100:101]
	s_add_u32 s100, s100, 0x10000
	s_addc_u32 s101, s101, 0
	global_load_dwordx4 v[124:127], v113, s[100:101]
	s_add_u32 s100, s100, 0x10000
	s_addc_u32 s101, s101, 0
	global_load_dwordx4 v[128:131], v113, s[100:101]
	s_waitcnt vmcnt(12)
; __device__ void ph_filter_gen(const Params& P, int j, const float* __restrict__ a3, float* __restrict__ kf, float* sl) {
;     ...
;         for (int i = 0; i < 8; ++i) { const int t = tid + NT * i; const float4* ar = (const float4*)(a3 + (size_t)t * 64);
;             float a0 = 0.f, a1 = 0.f, a2 = 0.f, a3v = 0.f;
; #pragma unroll 4
;             for (int jq = 0; jq < 16; ++jq) { const float4 av = ar[jq]; const float ae[4] = {av.x, av.y, av.z, av.w};
; #pragma unroll
;                 for (int e = 0; e < 4; ++e) { const float4 wv = *(const float4*)(sw + (jq * 4 + e) * 4); a0 += ae[e] * wv.x; a1 += ae[e] * wv.y; a2 += ae[e] * wv.z; a3v += ae[e] * wv.w; } }
	v_mov_b32_e32 v82, 0x100
	ds_read_b128 v[56:59], v82
	ds_read_b128 v[60:63], v82 offset:16
	ds_read_b128 v[64:67], v82 offset:32
	ds_read_b128 v[78:81], v82 offset:48
	s_waitcnt lgkmcnt(3)
	v_pk_fma_f32 v[38:39], v[132:133], v[56:57], v[38:39] op_sel_hi:[0,1,1]
	v_pk_fma_f32 v[36:37], v[132:133], v[58:59], v[36:37] op_sel_hi:[0,1,1]
	s_waitcnt lgkmcnt(2)
	v_pk_fma_f32 v[38:39], v[132:133], v[60:61], v[38:39] op_sel:[1,0,0]
	v_pk_fma_f32 v[36:37], v[132:133], v[62:63], v[36:37] op_sel:[1,0,0]
	s_waitcnt lgkmcnt(1)
	v_pk_fma_f32 v[38:39], v[134:135], v[64:65], v[38:39] op_sel_hi:[0,1,1]
	v_mov_b32_e32 v56, v135
	v_pk_fma_f32 v[36:37], v[134:135], v[66:67], v[36:37] op_sel_hi:[0,1,1]
	s_waitcnt lgkmcnt(0)
	v_pk_fma_f32 v[60:61], v[56:57], v[78:79], v[38:39] op_sel_hi:[0,1,1]
	v_pk_fma_f32 v[64:65], v[56:57], v[80:81], v[36:37] op_sel_hi:[0,1,1]
	ds_read_b128 v[36:39], v82 offset:64
	ds_read_b128 v[40:43], v82 offset:80
	ds_read_b128 v[56:59], v82 offset:96
	s_waitcnt lgkmcnt(2)
	v_pk_fma_f32 v[36:37], v[136:137], v[36:37], v[60:61] op_sel_hi:[0,1,1]
	ds_read_b128 v[60:63], v82 offset:112
	s_waitcnt lgkmcnt(2)
	v_pk_fma_f32 v[36:37], v[136:137], v[40:41], v[36:37] op_sel:[1,0,0]
	v_mov_b32_e32 v40, v139
	s_waitcnt lgkmcnt(1)
	v_pk_fma_f32 v[36:37], v[138:139], v[56:57], v[36:37] op_sel_hi:[0,1,1]
	s_waitcnt lgkmcnt(0)
	v_pk_fma_f32 v[56:57], v[40:41], v[60:61], v[36:37] op_sel_hi:[0,1,1]
	v_pk_fma_f32 v[36:37], v[136:137], v[38:39], v[64:65] op_sel_hi:[0,1,1]
	v_pk_fma_f32 v[36:37], v[136:137], v[42:43], v[36:37] op_sel:[1,0,0]
	s_nop 0
	v_pk_fma_f32 v[36:37], v[138:139], v[58:59], v[36:37] op_sel_hi:[0,1,1]
	v_pk_fma_f32 v[60:61], v[40:41], v[62:63], v[36:37] op_sel_hi:[0,1,1]
	ds_read_b128 v[36:39], v82 offset:128
	ds_read_b128 v[40:43], v82 offset:144
	ds_read_b128 v[52:55], v82 offset:160
	s_waitcnt lgkmcnt(2)
	v_pk_fma_f32 v[36:37], v[140:141], v[36:37], v[56:57] op_sel_hi:[0,1,1]
	ds_read_b128 v[56:59], v82 offset:176
	v_pk_fma_f32 v[38:39], v[140:141], v[38:39], v[60:61] op_sel_hi:[0,1,1]
	s_waitcnt lgkmcnt(2)
	v_pk_fma_f32 v[36:37], v[140:141], v[40:41], v[36:37] op_sel:[1,0,0]
	v_pk_fma_f32 v[38:39], v[140:141], v[42:43], v[38:39] op_sel:[1,0,0]
	s_waitcnt lgkmcnt(1)
	v_pk_fma_f32 v[36:37], v[142:143], v[52:53], v[36:37] op_sel_hi:[0,1,1]
	v_mov_b32_e32 v40, v143
	v_pk_fma_f32 v[38:39], v[142:143], v[54:55], v[38:39] op_sel_hi:[0,1,1]
	s_waitcnt lgkmcnt(0)
	v_pk_fma_f32 v[36:37], v[40:41], v[56:57], v[36:37] op_sel_hi:[0,1,1]
	v_pk_fma_f32 v[42:43], v[40:41], v[58:59], v[38:39] op_sel_hi:[0,1,1]
	ds_read_b128 v[38:41], v82 offset:192
	ds_read_b128 v[48:51], v82 offset:208
	ds_read_b128 v[52:55], v82 offset:224
	ds_read_b128 v[56:59], v82 offset:240
	s_waitcnt lgkmcnt(3)
	v_pk_fma_f32 v[36:37], v[144:145], v[38:39], v[36:37] op_sel_hi:[0,1,1]
	s_waitcnt lgkmcnt(2)
	v_pk_fma_f32 v[36:37], v[144:145], v[48:49], v[36:37] op_sel:[1,0,0]
	v_mov_b32_e32 v48, v147
	s_waitcnt lgkmcnt(1)
	v_pk_fma_f32 v[36:37], v[146:147], v[52:53], v[36:37] op_sel_hi:[0,1,1]
	s_waitcnt lgkmcnt(0)
	v_pk_fma_f32 v[38:39], v[48:49], v[56:57], v[36:37] op_sel_hi:[0,1,1]
	v_pk_fma_f32 v[36:37], v[144:145], v[40:41], v[42:43] op_sel_hi:[0,1,1]
	v_pk_fma_f32 v[36:37], v[144:145], v[50:51], v[36:37] op_sel:[1,0,0]
	s_nop 0
	v_pk_fma_f32 v[36:37], v[146:147], v[54:55], v[36:37] op_sel_hi:[0,1,1]
	v_pk_fma_f32 v[36:37], v[48:49], v[58:59], v[36:37] op_sel_hi:[0,1,1]
	s_add_u32 s100, s78, 0x1e840000
	s_addc_u32 s101, s79, 0
	global_load_dwordx4 v[132:135], v113, s[100:101]
	s_add_u32 s100, s100, 0x10000
	s_addc_u32 s101, s101, 0
	global_load_dwordx4 v[136:139], v113, s[100:101]
	s_add_u32 s100, s100, 0x10000
	s_addc_u32 s101, s101, 0
	global_load_dwordx4 v[140:143], v113, s[100:101]
	s_add_u32 s100, s100, 0x10000
	s_addc_u32 s101, s101, 0
	global_load_dwordx4 v[144:147], v113, s[100:101]
	s_waitcnt vmcnt(12)
	v_mov_b32_e32 v82, 0x200
	ds_read_b128 v[56:59], v82
	ds_read_b128 v[60:63], v82 offset:16
	ds_read_b128 v[64:67], v82 offset:32
	ds_read_b128 v[78:81], v82 offset:48
	s_waitcnt lgkmcnt(3)
	v_pk_fma_f32 v[38:39], v[148:149], v[56:57], v[38:39] op_sel_hi:[0,1,1]
	v_pk_fma_f32 v[36:37], v[148:149], v[58:59], v[36:37] op_sel_hi:[0,1,1]
	s_waitcnt lgkmcnt(2)
	v_pk_fma_f32 v[38:39], v[148:149], v[60:61], v[38:39] op_sel:[1,0,0]
	v_pk_fma_f32 v[36:37], v[148:149], v[62:63], v[36:37] op_sel:[1,0,0]
	s_waitcnt lgkmcnt(1)
	v_pk_fma_f32 v[38:39], v[150:151], v[64:65], v[38:39] op_sel_hi:[0,1,1]
	v_mov_b32_e32 v56, v151
	v_pk_fma_f32 v[36:37], v[150:151], v[66:67], v[36:37] op_sel_hi:[0,1,1]
	s_waitcnt lgkmcnt(0)
	v_pk_fma_f32 v[60:61], v[56:57], v[78:79], v[38:39] op_sel_hi:[0,1,1]
	v_pk_fma_f32 v[64:65], v[56:57], v[80:81], v[36:37] op_sel_hi:[0,1,1]
	ds_read_b128 v[36:39], v82 offset:64
	ds_read_b128 v[40:43], v82 offset:80
	ds_read_b128 v[56:59], v82 offset:96
	s_waitcnt lgkmcnt(2)
	v_pk_fma_f32 v[36:37], v[152:153], v[36:37], v[60:61] op_sel_hi:[0,1,1]
	ds_read_b128 v[60:63], v82 offset:112
	s_waitcnt lgkmcnt(2)
	v_pk_fma_f32 v[36:37], v[152:153], v[40:41], v[36:37] op_sel:[1,0,0]
	v_mov_b32_e32 v40, v155
	s_waitcnt lgkmcnt(1)
	v_pk_fma_f32 v[36:37], v[154:155], v[56:57], v[36:37] op_sel_hi:[0,1,1]
	s_waitcnt lgkmcnt(0)
	v_pk_fma_f32 v[56:57], v[40:41], v[60:61], v[36:37] op_sel_hi:[0,1,1]
	v_pk_fma_f32 v[36:37], v[152:153], v[38:39], v[64:65] op_sel_hi:[0,1,1]
	v_pk_fma_f32 v[36:37], v[152:153], v[42:43], v[36:37] op_sel:[1,0,0]
	s_nop 0
	v_pk_fma_f32 v[36:37], v[154:155], v[58:59], v[36:37] op_sel_hi:[0,1,1]
	v_pk_fma_f32 v[60:61], v[40:41], v[62:63], v[36:37] op_sel_hi:[0,1,1]
	ds_read_b128 v[36:39], v82 offset:128
	ds_read_b128 v[40:43], v82 offset:144
	ds_read_b128 v[52:55], v82 offset:160
	s_waitcnt lgkmcnt(2)
; __device__ void ph_filter_gen(const Params& P, int j, const float* __restrict__ a3, float* __restrict__ kf, float* sl) {
;     ...
;         for (int i = 0; i < 8; ++i) { const int t = tid + NT * i; const float4* ar = (const float4*)(a3 + (size_t)t * 64);
;             float a0 = 0.f, a1 = 0.f, a2 = 0.f, a3v = 0.f;
; #pragma unroll 4
;             for (int jq = 0; jq < 16; ++jq) { const float4 av = ar[jq]; const float ae[4] = {av.x, av.y, av.z, av.w};
; #pragma unroll
;                 for (int e = 0; e < 4; ++e) { const float4 wv = *(const float4*)(sw + (jq * 4 + e) * 4); a0 += ae[e] * wv.x; a1 += ae[e] * wv.y; a2 += ae[e] * wv.z; a3v += ae[e] * wv.w; } }
	v_pk_fma_f32 v[36:37], v[156:157], v[36:37], v[56:57] op_sel_hi:[0,1,1]
	ds_read_b128 v[56:59], v82 offset:176
	v_pk_fma_f32 v[38:39], v[156:157], v[38:39], v[60:61] op_sel_hi:[0,1,1]
	s_waitcnt lgkmcnt(2)
	v_pk_fma_f32 v[36:37], v[156:157], v[40:41], v[36:37] op_sel:[1,0,0]
	v_pk_fma_f32 v[38:39], v[156:157], v[42:43], v[38:39] op_sel:[1,0,0]
	s_waitcnt lgkmcnt(1)
	v_pk_fma_f32 v[36:37], v[158:159], v[52:53], v[36:37] op_sel_hi:[0,1,1]
	v_mov_b32_e32 v40, v159
	v_pk_fma_f32 v[38:39], v[158:159], v[54:55], v[38:39] op_sel_hi:[0,1,1]
	s_waitcnt lgkmcnt(0)
	v_pk_fma_f32 v[36:37], v[40:41], v[56:57], v[36:37] op_sel_hi:[0,1,1]
	v_pk_fma_f32 v[42:43], v[40:41], v[58:59], v[38:39] op_sel_hi:[0,1,1]
	ds_read_b128 v[38:41], v82 offset:192
	ds_read_b128 v[48:51], v82 offset:208
	ds_read_b128 v[52:55], v82 offset:224
	ds_read_b128 v[56:59], v82 offset:240
	s_waitcnt lgkmcnt(3)
	v_pk_fma_f32 v[36:37], v[160:161], v[38:39], v[36:37] op_sel_hi:[0,1,1]
	s_waitcnt lgkmcnt(2)
	v_pk_fma_f32 v[36:37], v[160:161], v[48:49], v[36:37] op_sel:[1,0,0]
	v_mov_b32_e32 v48, v163
	s_waitcnt lgkmcnt(1)
	v_pk_fma_f32 v[36:37], v[162:163], v[52:53], v[36:37] op_sel_hi:[0,1,1]
	s_waitcnt lgkmcnt(0)
	v_pk_fma_f32 v[38:39], v[48:49], v[56:57], v[36:37] op_sel_hi:[0,1,1]
	v_pk_fma_f32 v[36:37], v[160:161], v[40:41], v[42:43] op_sel_hi:[0,1,1]
	v_pk_fma_f32 v[36:37], v[160:161], v[50:51], v[36:37] op_sel:[1,0,0]
	s_nop 0
	v_pk_fma_f32 v[36:37], v[162:163], v[54:55], v[36:37] op_sel_hi:[0,1,1]
	v_pk_fma_f32 v[36:37], v[48:49], v[58:59], v[36:37] op_sel_hi:[0,1,1]
	s_add_u32 s100, s78, 0x1e880000
	s_addc_u32 s101, s79, 0
	global_load_dwordx4 v[148:151], v113, s[100:101]
	s_add_u32 s100, s100, 0x10000
	s_addc_u32 s101, s101, 0
	global_load_dwordx4 v[152:155], v113, s[100:101]
	s_add_u32 s100, s100, 0x10000
	s_addc_u32 s101, s101, 0
	global_load_dwordx4 v[156:159], v113, s[100:101]
	s_add_u32 s100, s100, 0x10000
	s_addc_u32 s101, s101, 0
	global_load_dwordx4 v[160:163], v113, s[100:101]
	s_waitcnt vmcnt(12)
	v_mov_b32_e32 v82, 0x300
	ds_read_b128 v[56:59], v82
	ds_read_b128 v[60:63], v82 offset:16
	ds_read_b128 v[64:67], v82 offset:32
	ds_read_b128 v[78:81], v82 offset:48
	s_waitcnt lgkmcnt(3)
	v_pk_fma_f32 v[38:39], v[164:165], v[56:57], v[38:39] op_sel_hi:[0,1,1]
	v_pk_fma_f32 v[36:37], v[164:165], v[58:59], v[36:37] op_sel_hi:[0,1,1]
	s_waitcnt lgkmcnt(2)
	v_pk_fma_f32 v[38:39], v[164:165], v[60:61], v[38:39] op_sel:[1,0,0]
	v_pk_fma_f32 v[36:37], v[164:165], v[62:63], v[36:37] op_sel:[1,0,0]
	s_waitcnt lgkmcnt(1)
	v_pk_fma_f32 v[38:39], v[166:167], v[64:65], v[38:39] op_sel_hi:[0,1,1]
	v_mov_b32_e32 v56, v167
	v_pk_fma_f32 v[36:37], v[166:167], v[66:67], v[36:37] op_sel_hi:[0,1,1]
	s_waitcnt lgkmcnt(0)
	v_pk_fma_f32 v[60:61], v[56:57], v[78:79], v[38:39] op_sel_hi:[0,1,1]
	v_pk_fma_f32 v[64:65], v[56:57], v[80:81], v[36:37] op_sel_hi:[0,1,1]
	ds_read_b128 v[36:39], v82 offset:64
	ds_read_b128 v[40:43], v82 offset:80
	ds_read_b128 v[56:59], v82 offset:96
	s_waitcnt lgkmcnt(2)
	v_pk_fma_f32 v[36:37], v[168:169], v[36:37], v[60:61] op_sel_hi:[0,1,1]
	ds_read_b128 v[60:63], v82 offset:112
	s_waitcnt lgkmcnt(2)
	v_pk_fma_f32 v[36:37], v[168:169], v[40:41], v[36:37] op_sel:[1,0,0]
	v_mov_b32_e32 v40, v171
	s_waitcnt lgkmcnt(1)
	v_pk_fma_f32 v[36:37], v[170:171], v[56:57], v[36:37] op_sel_hi:[0,1,1]
	s_waitcnt lgkmcnt(0)
	v_pk_fma_f32 v[56:57], v[40:41], v[60:61], v[36:37] op_sel_hi:[0,1,1]
	v_pk_fma_f32 v[36:37], v[168:169], v[38:39], v[64:65] op_sel_hi:[0,1,1]
	v_pk_fma_f32 v[36:37], v[168:169], v[42:43], v[36:37] op_sel:[1,0,0]
	s_nop 0
	v_pk_fma_f32 v[36:37], v[170:171], v[58:59], v[36:37] op_sel_hi:[0,1,1]
	v_pk_fma_f32 v[60:61], v[40:41], v[62:63], v[36:37] op_sel_hi:[0,1,1]
	ds_read_b128 v[36:39], v82 offset:128
	ds_read_b128 v[40:43], v82 offset:144
	ds_read_b128 v[52:55], v82 offset:160
	s_waitcnt lgkmcnt(2)
	v_pk_fma_f32 v[36:37], v[172:173], v[36:37], v[56:57] op_sel_hi:[0,1,1]
	ds_read_b128 v[56:59], v82 offset:176
	v_pk_fma_f32 v[38:39], v[172:173], v[38:39], v[60:61] op_sel_hi:[0,1,1]
	s_waitcnt lgkmcnt(2)
	v_pk_fma_f32 v[36:37], v[172:173], v[40:41], v[36:37] op_sel:[1,0,0]
	v_pk_fma_f32 v[38:39], v[172:173], v[42:43], v[38:39] op_sel:[1,0,0]
	s_waitcnt lgkmcnt(1)
	v_pk_fma_f32 v[36:37], v[174:175], v[52:53], v[36:37] op_sel_hi:[0,1,1]
	v_mov_b32_e32 v40, v175
	v_pk_fma_f32 v[38:39], v[174:175], v[54:55], v[38:39] op_sel_hi:[0,1,1]
	s_waitcnt lgkmcnt(0)
	v_pk_fma_f32 v[36:37], v[40:41], v[56:57], v[36:37] op_sel_hi:[0,1,1]
	v_pk_fma_f32 v[42:43], v[40:41], v[58:59], v[38:39] op_sel_hi:[0,1,1]
	ds_read_b128 v[38:41], v82 offset:192
	ds_read_b128 v[48:51], v82 offset:208
	ds_read_b128 v[52:55], v82 offset:224
	ds_read_b128 v[56:59], v82 offset:240
	s_waitcnt lgkmcnt(3)
	v_pk_fma_f32 v[36:37], v[176:177], v[38:39], v[36:37] op_sel_hi:[0,1,1]
	s_waitcnt lgkmcnt(2)
	v_pk_fma_f32 v[36:37], v[176:177], v[48:49], v[36:37] op_sel:[1,0,0]
	v_mov_b32_e32 v48, v179
	s_waitcnt lgkmcnt(1)
	v_pk_fma_f32 v[36:37], v[178:179], v[52:53], v[36:37] op_sel_hi:[0,1,1]
	s_waitcnt lgkmcnt(0)
	v_pk_fma_f32 v[38:39], v[48:49], v[56:57], v[36:37] op_sel_hi:[0,1,1]
	v_pk_fma_f32 v[36:37], v[176:177], v[40:41], v[42:43] op_sel_hi:[0,1,1]
	v_pk_fma_f32 v[36:37], v[176:177], v[50:51], v[36:37] op_sel:[1,0,0]
	s_nop 0
	v_pk_fma_f32 v[36:37], v[178:179], v[54:55], v[36:37] op_sel_hi:[0,1,1]
	v_pk_fma_f32 v[36:37], v[48:49], v[58:59], v[36:37] op_sel_hi:[0,1,1]
	s_add_u32 s100, s78, 0x1e8c0000
	s_addc_u32 s101, s79, 0
	global_load_dwordx4 v[164:167], v113, s[100:101]
	s_add_u32 s100, s100, 0x10000
	s_addc_u32 s101, s101, 0
	global_load_dwordx4 v[168:171], v113, s[100:101]
	s_add_u32 s100, s100, 0x10000
	s_addc_u32 s101, s101, 0
	global_load_dwordx4 v[172:175], v113, s[100:101]
	s_add_u32 s100, s100, 0x10000
	s_addc_u32 s101, s101, 0
	global_load_dwordx4 v[176:179], v113, s[100:101]
	v_mov_b32_e32 v42, 0
	s_mov_b32 s0, 0
	s_mov_b64 s[14:15], 0
	v_mov_b32_e32 v43, v42
	v_mov_b32_e32 v40, v42
	v_mov_b32_e32 v41, v42
; __device__ void ph_filter_gen(const Params& P, int j, const float* __restrict__ a3, float* __restrict__ kf, float* sl) {
;     ...
;         for (int i = 0; i < 8; ++i) { const int t = tid + NT * i; const float4* ar = (const float4*)(a3 + (size_t)t * 64);
;             float a0 = 0.f, a1 = 0.f, a2 = 0.f, a3v = 0.f;
; #pragma unroll 4
;             for (int jq = 0; jq < 16; ++jq) { const float4 av = ar[jq]; const float ae[4] = {av.x, av.y, av.z, av.w};
; #pragma unroll
;                 for (int e = 0; e < 4; ++e) { const float4 wv = *(const float4*)(sw + (jq * 4 + e) * 4); a0 += ae[e] * wv.x; a1 += ae[e] * wv.y; a2 += ae[e] * wv.z; a3v += ae[e] * wv.w; } }
.LBB0_223:
	v_lshlrev_b32_e32 v113, 2, v68
	v_add_u32_e32 v113, 0x4000, v113
	s_waitcnt vmcnt(12)
	v_mov_b32_e32 v86, 0
	ds_read_b128 v[60:63], v86
	ds_read_b128 v[64:67], v86 offset:16
	ds_read_b128 v[78:81], v86 offset:32
	ds_read_b128 v[82:85], v86 offset:48
	s_waitcnt lgkmcnt(3)
	v_pk_fma_f32 v[42:43], v[116:117], v[60:61], v[42:43] op_sel_hi:[0,1,1]
	v_pk_fma_f32 v[40:41], v[116:117], v[62:63], v[40:41] op_sel_hi:[0,1,1]
	s_waitcnt lgkmcnt(2)
	v_pk_fma_f32 v[42:43], v[116:117], v[64:65], v[42:43] op_sel:[1,0,0]
	v_pk_fma_f32 v[40:41], v[116:117], v[66:67], v[40:41] op_sel:[1,0,0]
	s_waitcnt lgkmcnt(1)
	v_pk_fma_f32 v[42:43], v[118:119], v[78:79], v[42:43] op_sel_hi:[0,1,1]
	v_mov_b32_e32 v60, v119
	v_pk_fma_f32 v[40:41], v[118:119], v[80:81], v[40:41] op_sel_hi:[0,1,1]
	s_waitcnt lgkmcnt(0)
	v_pk_fma_f32 v[64:65], v[60:61], v[82:83], v[42:43] op_sel_hi:[0,1,1]
	v_pk_fma_f32 v[78:79], v[60:61], v[84:85], v[40:41] op_sel_hi:[0,1,1]
	ds_read_b128 v[40:43], v86 offset:64
	ds_read_b128 v[44:47], v86 offset:80
	ds_read_b128 v[60:63], v86 offset:96
	s_waitcnt lgkmcnt(2)
	v_pk_fma_f32 v[40:41], v[120:121], v[40:41], v[64:65] op_sel_hi:[0,1,1]
	ds_read_b128 v[64:67], v86 offset:112
	s_waitcnt lgkmcnt(2)
	v_pk_fma_f32 v[40:41], v[120:121], v[44:45], v[40:41] op_sel:[1,0,0]
	v_mov_b32_e32 v44, v123
	s_waitcnt lgkmcnt(1)
	v_pk_fma_f32 v[40:41], v[122:123], v[60:61], v[40:41] op_sel_hi:[0,1,1]
	s_waitcnt lgkmcnt(0)
	v_pk_fma_f32 v[60:61], v[44:45], v[64:65], v[40:41] op_sel_hi:[0,1,1]
	v_pk_fma_f32 v[40:41], v[120:121], v[42:43], v[78:79] op_sel_hi:[0,1,1]
	v_pk_fma_f32 v[40:41], v[120:121], v[46:47], v[40:41] op_sel:[1,0,0]
	s_nop 0
	v_pk_fma_f32 v[40:41], v[122:123], v[62:63], v[40:41] op_sel_hi:[0,1,1]
	v_pk_fma_f32 v[64:65], v[44:45], v[66:67], v[40:41] op_sel_hi:[0,1,1]
	ds_read_b128 v[40:43], v86 offset:128
	ds_read_b128 v[44:47], v86 offset:144
	ds_read_b128 v[56:59], v86 offset:160
	s_waitcnt lgkmcnt(2)
	v_pk_fma_f32 v[40:41], v[124:125], v[40:41], v[60:61] op_sel_hi:[0,1,1]
	ds_read_b128 v[60:63], v86 offset:176
	v_pk_fma_f32 v[42:43], v[124:125], v[42:43], v[64:65] op_sel_hi:[0,1,1]
	s_waitcnt lgkmcnt(2)
	v_pk_fma_f32 v[40:41], v[124:125], v[44:45], v[40:41] op_sel:[1,0,0]
	v_pk_fma_f32 v[42:43], v[124:125], v[46:47], v[42:43] op_sel:[1,0,0]
	s_waitcnt lgkmcnt(1)
	v_pk_fma_f32 v[40:41], v[126:127], v[56:57], v[40:41] op_sel_hi:[0,1,1]
	v_mov_b32_e32 v44, v127
	v_pk_fma_f32 v[42:43], v[126:127], v[58:59], v[42:43] op_sel_hi:[0,1,1]
	s_waitcnt lgkmcnt(0)
	v_pk_fma_f32 v[40:41], v[44:45], v[60:61], v[40:41] op_sel_hi:[0,1,1]
	v_pk_fma_f32 v[46:47], v[44:45], v[62:63], v[42:43] op_sel_hi:[0,1,1]
	ds_read_b128 v[42:45], v86 offset:192
	ds_read_b128 v[52:55], v86 offset:208
	ds_read_b128 v[56:59], v86 offset:224
	ds_read_b128 v[60:63], v86 offset:240
	s_waitcnt lgkmcnt(3)
	v_pk_fma_f32 v[40:41], v[128:129], v[42:43], v[40:41] op_sel_hi:[0,1,1]
	s_waitcnt lgkmcnt(2)
	v_pk_fma_f32 v[40:41], v[128:129], v[52:53], v[40:41] op_sel:[1,0,0]
	v_mov_b32_e32 v52, v131
	s_waitcnt lgkmcnt(1)
	v_pk_fma_f32 v[40:41], v[130:131], v[56:57], v[40:41] op_sel_hi:[0,1,1]
	s_waitcnt lgkmcnt(0)
	v_pk_fma_f32 v[42:43], v[52:53], v[60:61], v[40:41] op_sel_hi:[0,1,1]
	v_pk_fma_f32 v[40:41], v[128:129], v[44:45], v[46:47] op_sel_hi:[0,1,1]
	v_pk_fma_f32 v[40:41], v[128:129], v[54:55], v[40:41] op_sel:[1,0,0]
	s_nop 0
	v_pk_fma_f32 v[40:41], v[130:131], v[58:59], v[40:41] op_sel_hi:[0,1,1]
	v_pk_fma_f32 v[40:41], v[52:53], v[62:63], v[40:41] op_sel_hi:[0,1,1]
	s_add_u32 s100, s78, 0x1e800000
	s_addc_u32 s101, s79, 0
	global_load_dwordx4 v[116:119], v113, s[100:101]
	s_add_u32 s100, s100, 0x10000
	s_addc_u32 s101, s101, 0
	global_load_dwordx4 v[120:123], v113, s[100:101]
	s_add_u32 s100, s100, 0x10000
	s_addc_u32 s101, s101, 0
	global_load_dwordx4 v[124:127], v113, s[100:101]
	s_add_u32 s100, s100, 0x10000
	s_addc_u32 s101, s101, 0
	global_load_dwordx4 v[128:131], v113, s[100:101]
	s_waitcnt vmcnt(12)
	v_mov_b32_e32 v86, 0x100
	ds_read_b128 v[60:63], v86
	ds_read_b128 v[64:67], v86 offset:16
	ds_read_b128 v[78:81], v86 offset:32
	ds_read_b128 v[82:85], v86 offset:48
	s_waitcnt lgkmcnt(3)
	v_pk_fma_f32 v[42:43], v[132:133], v[60:61], v[42:43] op_sel_hi:[0,1,1]
	v_pk_fma_f32 v[40:41], v[132:133], v[62:63], v[40:41] op_sel_hi:[0,1,1]
	s_waitcnt lgkmcnt(2)
	v_pk_fma_f32 v[42:43], v[132:133], v[64:65], v[42:43] op_sel:[1,0,0]
	v_pk_fma_f32 v[40:41], v[132:133], v[66:67], v[40:41] op_sel:[1,0,0]
	s_waitcnt lgkmcnt(1)
	v_pk_fma_f32 v[42:43], v[134:135], v[78:79], v[42:43] op_sel_hi:[0,1,1]
	v_mov_b32_e32 v60, v135
	v_pk_fma_f32 v[40:41], v[134:135], v[80:81], v[40:41] op_sel_hi:[0,1,1]
	s_waitcnt lgkmcnt(0)
	v_pk_fma_f32 v[64:65], v[60:61], v[82:83], v[42:43] op_sel_hi:[0,1,1]
	v_pk_fma_f32 v[78:79], v[60:61], v[84:85], v[40:41] op_sel_hi:[0,1,1]
	ds_read_b128 v[40:43], v86 offset:64
	ds_read_b128 v[44:47], v86 offset:80
	ds_read_b128 v[60:63], v86 offset:96
	s_waitcnt lgkmcnt(2)
	v_pk_fma_f32 v[40:41], v[136:137], v[40:41], v[64:65] op_sel_hi:[0,1,1]
	ds_read_b128 v[64:67], v86 offset:112
	s_waitcnt lgkmcnt(2)
	v_pk_fma_f32 v[40:41], v[136:137], v[44:45], v[40:41] op_sel:[1,0,0]
	v_mov_b32_e32 v44, v139
	s_waitcnt lgkmcnt(1)
	v_pk_fma_f32 v[40:41], v[138:139], v[60:61], v[40:41] op_sel_hi:[0,1,1]
	s_waitcnt lgkmcnt(0)
	v_pk_fma_f32 v[60:61], v[44:45], v[64:65], v[40:41] op_sel_hi:[0,1,1]
	v_pk_fma_f32 v[40:41], v[136:137], v[42:43], v[78:79] op_sel_hi:[0,1,1]
	v_pk_fma_f32 v[40:41], v[136:137], v[46:47], v[40:41] op_sel:[1,0,0]
	s_nop 0
	v_pk_fma_f32 v[40:41], v[138:139], v[62:63], v[40:41] op_sel_hi:[0,1,1]
	v_pk_fma_f32 v[64:65], v[44:45], v[66:67], v[40:41] op_sel_hi:[0,1,1]
	ds_read_b128 v[40:43], v86 offset:128
	ds_read_b128 v[44:47], v86 offset:144
	ds_read_b128 v[56:59], v86 offset:160
	s_waitcnt lgkmcnt(2)
; __device__ void ph_filter_gen(const Params& P, int j, const float* __restrict__ a3, float* __restrict__ kf, float* sl) {
;     ...
;         for (int i = 0; i < 8; ++i) { const int t = tid + NT * i; const float4* ar = (const float4*)(a3 + (size_t)t * 64);
;             float a0 = 0.f, a1 = 0.f, a2 = 0.f, a3v = 0.f;
; #pragma unroll 4
;             for (int jq = 0; jq < 16; ++jq) { const float4 av = ar[jq]; const float ae[4] = {av.x, av.y, av.z, av.w};
; #pragma unroll
;                 for (int e = 0; e < 4; ++e) { const float4 wv = *(const float4*)(sw + (jq * 4 + e) * 4); a0 += ae[e] * wv.x; a1 += ae[e] * wv.y; a2 += ae[e] * wv.z; a3v += ae[e] * wv.w; } }
	v_pk_fma_f32 v[40:41], v[140:141], v[40:41], v[60:61] op_sel_hi:[0,1,1]
	ds_read_b128 v[60:63], v86 offset:176
	v_pk_fma_f32 v[42:43], v[140:141], v[42:43], v[64:65] op_sel_hi:[0,1,1]
	s_waitcnt lgkmcnt(2)
	v_pk_fma_f32 v[40:41], v[140:141], v[44:45], v[40:41] op_sel:[1,0,0]
	v_pk_fma_f32 v[42:43], v[140:141], v[46:47], v[42:43] op_sel:[1,0,0]
	s_waitcnt lgkmcnt(1)
	v_pk_fma_f32 v[40:41], v[142:143], v[56:57], v[40:41] op_sel_hi:[0,1,1]
	v_mov_b32_e32 v44, v143
	v_pk_fma_f32 v[42:43], v[142:143], v[58:59], v[42:43] op_sel_hi:[0,1,1]
	s_waitcnt lgkmcnt(0)
	v_pk_fma_f32 v[40:41], v[44:45], v[60:61], v[40:41] op_sel_hi:[0,1,1]
	v_pk_fma_f32 v[46:47], v[44:45], v[62:63], v[42:43] op_sel_hi:[0,1,1]
	ds_read_b128 v[42:45], v86 offset:192
	ds_read_b128 v[52:55], v86 offset:208
	ds_read_b128 v[56:59], v86 offset:224
	ds_read_b128 v[60:63], v86 offset:240
	s_waitcnt lgkmcnt(3)
	v_pk_fma_f32 v[40:41], v[144:145], v[42:43], v[40:41] op_sel_hi:[0,1,1]
	s_waitcnt lgkmcnt(2)
	v_pk_fma_f32 v[40:41], v[144:145], v[52:53], v[40:41] op_sel:[1,0,0]
	v_mov_b32_e32 v52, v147
	s_waitcnt lgkmcnt(1)
	v_pk_fma_f32 v[40:41], v[146:147], v[56:57], v[40:41] op_sel_hi:[0,1,1]
	s_waitcnt lgkmcnt(0)
	v_pk_fma_f32 v[42:43], v[52:53], v[60:61], v[40:41] op_sel_hi:[0,1,1]
	v_pk_fma_f32 v[40:41], v[144:145], v[44:45], v[46:47] op_sel_hi:[0,1,1]
	v_pk_fma_f32 v[40:41], v[144:145], v[54:55], v[40:41] op_sel:[1,0,0]
	s_nop 0
	v_pk_fma_f32 v[40:41], v[146:147], v[58:59], v[40:41] op_sel_hi:[0,1,1]
	v_pk_fma_f32 v[40:41], v[52:53], v[62:63], v[40:41] op_sel_hi:[0,1,1]
	s_add_u32 s100, s78, 0x1e840000
	s_addc_u32 s101, s79, 0
	global_load_dwordx4 v[132:135], v113, s[100:101]
	s_add_u32 s100, s100, 0x10000
	s_addc_u32 s101, s101, 0
	global_load_dwordx4 v[136:139], v113, s[100:101]
	s_add_u32 s100, s100, 0x10000
	s_addc_u32 s101, s101, 0
	global_load_dwordx4 v[140:143], v113, s[100:101]
	s_add_u32 s100, s100, 0x10000
	s_addc_u32 s101, s101, 0
	global_load_dwordx4 v[144:147], v113, s[100:101]
	s_waitcnt vmcnt(12)
	v_mov_b32_e32 v86, 0x200
	ds_read_b128 v[60:63], v86
	ds_read_b128 v[64:67], v86 offset:16
	ds_read_b128 v[78:81], v86 offset:32
	ds_read_b128 v[82:85], v86 offset:48
	s_waitcnt lgkmcnt(3)
	v_pk_fma_f32 v[42:43], v[148:149], v[60:61], v[42:43] op_sel_hi:[0,1,1]
	v_pk_fma_f32 v[40:41], v[148:149], v[62:63], v[40:41] op_sel_hi:[0,1,1]
	s_waitcnt lgkmcnt(2)
	v_pk_fma_f32 v[42:43], v[148:149], v[64:65], v[42:43] op_sel:[1,0,0]
	v_pk_fma_f32 v[40:41], v[148:149], v[66:67], v[40:41] op_sel:[1,0,0]
	s_waitcnt lgkmcnt(1)
	v_pk_fma_f32 v[42:43], v[150:151], v[78:79], v[42:43] op_sel_hi:[0,1,1]
	v_mov_b32_e32 v60, v151
	v_pk_fma_f32 v[40:41], v[150:151], v[80:81], v[40:41] op_sel_hi:[0,1,1]
	s_waitcnt lgkmcnt(0)
	v_pk_fma_f32 v[64:65], v[60:61], v[82:83], v[42:43] op_sel_hi:[0,1,1]
	v_pk_fma_f32 v[78:79], v[60:61], v[84:85], v[40:41] op_sel_hi:[0,1,1]
	ds_read_b128 v[40:43], v86 offset:64
	ds_read_b128 v[44:47], v86 offset:80
	ds_read_b128 v[60:63], v86 offset:96
	s_waitcnt lgkmcnt(2)
	v_pk_fma_f32 v[40:41], v[152:153], v[40:41], v[64:65] op_sel_hi:[0,1,1]
	ds_read_b128 v[64:67], v86 offset:112
	s_waitcnt lgkmcnt(2)
	v_pk_fma_f32 v[40:41], v[152:153], v[44:45], v[40:41] op_sel:[1,0,0]
	v_mov_b32_e32 v44, v155
	s_waitcnt lgkmcnt(1)
	v_pk_fma_f32 v[40:41], v[154:155], v[60:61], v[40:41] op_sel_hi:[0,1,1]
	s_waitcnt lgkmcnt(0)
	v_pk_fma_f32 v[60:61], v[44:45], v[64:65], v[40:41] op_sel_hi:[0,1,1]
	v_pk_fma_f32 v[40:41], v[152:153], v[42:43], v[78:79] op_sel_hi:[0,1,1]
	v_pk_fma_f32 v[40:41], v[152:153], v[46:47], v[40:41] op_sel:[1,0,0]
	s_nop 0
	v_pk_fma_f32 v[40:41], v[154:155], v[62:63], v[40:41] op_sel_hi:[0,1,1]
	v_pk_fma_f32 v[64:65], v[44:45], v[66:67], v[40:41] op_sel_hi:[0,1,1]
	ds_read_b128 v[40:43], v86 offset:128
	ds_read_b128 v[44:47], v86 offset:144
	ds_read_b128 v[56:59], v86 offset:160
	s_waitcnt lgkmcnt(2)
	v_pk_fma_f32 v[40:41], v[156:157], v[40:41], v[60:61] op_sel_hi:[0,1,1]
	ds_read_b128 v[60:63], v86 offset:176
	v_pk_fma_f32 v[42:43], v[156:157], v[42:43], v[64:65] op_sel_hi:[0,1,1]
	s_waitcnt lgkmcnt(2)
	v_pk_fma_f32 v[40:41], v[156:157], v[44:45], v[40:41] op_sel:[1,0,0]
	v_pk_fma_f32 v[42:43], v[156:157], v[46:47], v[42:43] op_sel:[1,0,0]
	s_waitcnt lgkmcnt(1)
	v_pk_fma_f32 v[40:41], v[158:159], v[56:57], v[40:41] op_sel_hi:[0,1,1]
	v_mov_b32_e32 v44, v159
	v_pk_fma_f32 v[42:43], v[158:159], v[58:59], v[42:43] op_sel_hi:[0,1,1]
	s_waitcnt lgkmcnt(0)
	v_pk_fma_f32 v[40:41], v[44:45], v[60:61], v[40:41] op_sel_hi:[0,1,1]
	v_pk_fma_f32 v[46:47], v[44:45], v[62:63], v[42:43] op_sel_hi:[0,1,1]
	ds_read_b128 v[42:45], v86 offset:192
	ds_read_b128 v[52:55], v86 offset:208
	ds_read_b128 v[56:59], v86 offset:224
	ds_read_b128 v[60:63], v86 offset:240
	s_waitcnt lgkmcnt(3)
	v_pk_fma_f32 v[40:41], v[160:161], v[42:43], v[40:41] op_sel_hi:[0,1,1]
	s_waitcnt lgkmcnt(2)
	v_pk_fma_f32 v[40:41], v[160:161], v[52:53], v[40:41] op_sel:[1,0,0]
	v_mov_b32_e32 v52, v163
	s_waitcnt lgkmcnt(1)
	v_pk_fma_f32 v[40:41], v[162:163], v[56:57], v[40:41] op_sel_hi:[0,1,1]
	s_waitcnt lgkmcnt(0)
	v_pk_fma_f32 v[42:43], v[52:53], v[60:61], v[40:41] op_sel_hi:[0,1,1]
	v_pk_fma_f32 v[40:41], v[160:161], v[44:45], v[46:47] op_sel_hi:[0,1,1]
	v_pk_fma_f32 v[40:41], v[160:161], v[54:55], v[40:41] op_sel:[1,0,0]
	s_nop 0
	v_pk_fma_f32 v[40:41], v[162:163], v[58:59], v[40:41] op_sel_hi:[0,1,1]
	v_pk_fma_f32 v[40:41], v[52:53], v[62:63], v[40:41] op_sel_hi:[0,1,1]
	s_add_u32 s100, s78, 0x1e880000
	s_addc_u32 s101, s79, 0
	global_load_dwordx4 v[148:151], v113, s[100:101]
	s_add_u32 s100, s100, 0x10000
	s_addc_u32 s101, s101, 0
	global_load_dwordx4 v[152:155], v113, s[100:101]
	s_add_u32 s100, s100, 0x10000
	s_addc_u32 s101, s101, 0
	global_load_dwordx4 v[156:159], v113, s[100:101]
	s_add_u32 s100, s100, 0x10000
	s_addc_u32 s101, s101, 0
	global_load_dwordx4 v[160:163], v113, s[100:101]
	s_waitcnt vmcnt(12)
; __device__ void ph_filter_gen(const Params& P, int j, const float* __restrict__ a3, float* __restrict__ kf, float* sl) {
;     ...
;         for (int i = 0; i < 8; ++i) { const int t = tid + NT * i; const float4* ar = (const float4*)(a3 + (size_t)t * 64);
;             float a0 = 0.f, a1 = 0.f, a2 = 0.f, a3v = 0.f;
; #pragma unroll 4
;             for (int jq = 0; jq < 16; ++jq) { const float4 av = ar[jq]; const float ae[4] = {av.x, av.y, av.z, av.w};
; #pragma unroll
;                 for (int e = 0; e < 4; ++e) { const float4 wv = *(const float4*)(sw + (jq * 4 + e) * 4); a0 += ae[e] * wv.x; a1 += ae[e] * wv.y; a2 += ae[e] * wv.z; a3v += ae[e] * wv.w; } }
;             const float dec = expf(-((float)t / (float)(SEQ - 1)) * delta);
	v_mov_b32_e32 v86, 0x300
	ds_read_b128 v[60:63], v86
	ds_read_b128 v[64:67], v86 offset:16
	ds_read_b128 v[78:81], v86 offset:32
	ds_read_b128 v[82:85], v86 offset:48
	s_waitcnt lgkmcnt(3)
	v_pk_fma_f32 v[42:43], v[164:165], v[60:61], v[42:43] op_sel_hi:[0,1,1]
	v_pk_fma_f32 v[40:41], v[164:165], v[62:63], v[40:41] op_sel_hi:[0,1,1]
	s_waitcnt lgkmcnt(2)
	v_pk_fma_f32 v[42:43], v[164:165], v[64:65], v[42:43] op_sel:[1,0,0]
	v_pk_fma_f32 v[40:41], v[164:165], v[66:67], v[40:41] op_sel:[1,0,0]
	s_waitcnt lgkmcnt(1)
	v_pk_fma_f32 v[42:43], v[166:167], v[78:79], v[42:43] op_sel_hi:[0,1,1]
	v_mov_b32_e32 v60, v167
	v_pk_fma_f32 v[40:41], v[166:167], v[80:81], v[40:41] op_sel_hi:[0,1,1]
	s_waitcnt lgkmcnt(0)
	v_pk_fma_f32 v[64:65], v[60:61], v[82:83], v[42:43] op_sel_hi:[0,1,1]
	v_pk_fma_f32 v[78:79], v[60:61], v[84:85], v[40:41] op_sel_hi:[0,1,1]
	ds_read_b128 v[40:43], v86 offset:64
	ds_read_b128 v[44:47], v86 offset:80
	ds_read_b128 v[60:63], v86 offset:96
	s_waitcnt lgkmcnt(2)
	v_pk_fma_f32 v[40:41], v[168:169], v[40:41], v[64:65] op_sel_hi:[0,1,1]
	ds_read_b128 v[64:67], v86 offset:112
	s_waitcnt lgkmcnt(2)
	v_pk_fma_f32 v[40:41], v[168:169], v[44:45], v[40:41] op_sel:[1,0,0]
	v_mov_b32_e32 v44, v171
	s_waitcnt lgkmcnt(1)
	v_pk_fma_f32 v[40:41], v[170:171], v[60:61], v[40:41] op_sel_hi:[0,1,1]
	s_waitcnt lgkmcnt(0)
	v_pk_fma_f32 v[60:61], v[44:45], v[64:65], v[40:41] op_sel_hi:[0,1,1]
	v_pk_fma_f32 v[40:41], v[168:169], v[42:43], v[78:79] op_sel_hi:[0,1,1]
	v_pk_fma_f32 v[40:41], v[168:169], v[46:47], v[40:41] op_sel:[1,0,0]
	s_nop 0
	v_pk_fma_f32 v[40:41], v[170:171], v[62:63], v[40:41] op_sel_hi:[0,1,1]
	v_pk_fma_f32 v[64:65], v[44:45], v[66:67], v[40:41] op_sel_hi:[0,1,1]
	ds_read_b128 v[40:43], v86 offset:128
	ds_read_b128 v[44:47], v86 offset:144
	ds_read_b128 v[56:59], v86 offset:160
	s_waitcnt lgkmcnt(2)
	v_pk_fma_f32 v[40:41], v[172:173], v[40:41], v[60:61] op_sel_hi:[0,1,1]
	ds_read_b128 v[60:63], v86 offset:176
	v_pk_fma_f32 v[42:43], v[172:173], v[42:43], v[64:65] op_sel_hi:[0,1,1]
	s_waitcnt lgkmcnt(2)
	v_pk_fma_f32 v[40:41], v[172:173], v[44:45], v[40:41] op_sel:[1,0,0]
	v_pk_fma_f32 v[42:43], v[172:173], v[46:47], v[42:43] op_sel:[1,0,0]
	s_waitcnt lgkmcnt(1)
	v_pk_fma_f32 v[40:41], v[174:175], v[56:57], v[40:41] op_sel_hi:[0,1,1]
	v_mov_b32_e32 v44, v175
	v_pk_fma_f32 v[42:43], v[174:175], v[58:59], v[42:43] op_sel_hi:[0,1,1]
	s_waitcnt lgkmcnt(0)
	v_pk_fma_f32 v[40:41], v[44:45], v[60:61], v[40:41] op_sel_hi:[0,1,1]
	v_pk_fma_f32 v[46:47], v[44:45], v[62:63], v[42:43] op_sel_hi:[0,1,1]
	ds_read_b128 v[42:45], v86 offset:192
	ds_read_b128 v[52:55], v86 offset:208
	ds_read_b128 v[56:59], v86 offset:224
	ds_read_b128 v[60:63], v86 offset:240
	s_waitcnt lgkmcnt(3)
	v_pk_fma_f32 v[40:41], v[176:177], v[42:43], v[40:41] op_sel_hi:[0,1,1]
	s_waitcnt lgkmcnt(2)
	v_pk_fma_f32 v[40:41], v[176:177], v[52:53], v[40:41] op_sel:[1,0,0]
	v_mov_b32_e32 v52, v179
	s_waitcnt lgkmcnt(1)
	v_pk_fma_f32 v[40:41], v[178:179], v[56:57], v[40:41] op_sel_hi:[0,1,1]
	s_waitcnt lgkmcnt(0)
	v_pk_fma_f32 v[42:43], v[52:53], v[60:61], v[40:41] op_sel_hi:[0,1,1]
	v_pk_fma_f32 v[40:41], v[176:177], v[44:45], v[46:47] op_sel_hi:[0,1,1]
	v_pk_fma_f32 v[40:41], v[176:177], v[54:55], v[40:41] op_sel:[1,0,0]
	s_nop 0
	v_pk_fma_f32 v[40:41], v[178:179], v[58:59], v[40:41] op_sel_hi:[0,1,1]
	v_pk_fma_f32 v[40:41], v[52:53], v[62:63], v[40:41] op_sel_hi:[0,1,1]
	s_add_u32 s100, s78, 0x1e8c0000
	s_addc_u32 s101, s79, 0
	global_load_dwordx4 v[164:167], v113, s[100:101]
	s_add_u32 s100, s100, 0x10000
	s_addc_u32 s101, s101, 0
	global_load_dwordx4 v[168:171], v113, s[100:101]
	s_add_u32 s100, s100, 0x10000
	s_addc_u32 s101, s101, 0
	global_load_dwordx4 v[172:175], v113, s[100:101]
	s_add_u32 s100, s100, 0x10000
	s_addc_u32 s101, s101, 0
	global_load_dwordx4 v[176:179], v113, s[100:101]
	v_mov_b32_e32 v46, 0
	s_mov_b32 s0, 0
	s_mov_b64 s[14:15], 0
	v_mov_b32_e32 v47, v46
	v_mov_b32_e32 v44, v46
	v_mov_b32_e32 v45, v46
.LBB0_225:
	v_lshlrev_b32_e32 v113, 2, v68
	v_add_u32_e32 v113, 0x6000, v113
	s_waitcnt vmcnt(12)
	v_mov_b32_e32 v90, 0
	ds_read_b128 v[64:67], v90
	ds_read_b128 v[78:81], v90 offset:16
	ds_read_b128 v[82:85], v90 offset:32
	ds_read_b128 v[86:89], v90 offset:48
	s_waitcnt lgkmcnt(3)
	v_pk_fma_f32 v[46:47], v[116:117], v[64:65], v[46:47] op_sel_hi:[0,1,1]
	v_pk_fma_f32 v[44:45], v[116:117], v[66:67], v[44:45] op_sel_hi:[0,1,1]
	s_waitcnt lgkmcnt(2)
	v_pk_fma_f32 v[46:47], v[116:117], v[78:79], v[46:47] op_sel:[1,0,0]
	v_pk_fma_f32 v[44:45], v[116:117], v[80:81], v[44:45] op_sel:[1,0,0]
	s_waitcnt lgkmcnt(1)
	v_pk_fma_f32 v[46:47], v[118:119], v[82:83], v[46:47] op_sel_hi:[0,1,1]
	v_mov_b32_e32 v64, v119
	v_pk_fma_f32 v[44:45], v[118:119], v[84:85], v[44:45] op_sel_hi:[0,1,1]
	s_waitcnt lgkmcnt(0)
	v_pk_fma_f32 v[78:79], v[64:65], v[86:87], v[46:47] op_sel_hi:[0,1,1]
	v_pk_fma_f32 v[82:83], v[64:65], v[88:89], v[44:45] op_sel_hi:[0,1,1]
	ds_read_b128 v[44:47], v90 offset:64
	ds_read_b128 v[48:51], v90 offset:80
	ds_read_b128 v[64:67], v90 offset:96
	s_waitcnt lgkmcnt(2)
	v_pk_fma_f32 v[44:45], v[120:121], v[44:45], v[78:79] op_sel_hi:[0,1,1]
	ds_read_b128 v[78:81], v90 offset:112
	s_waitcnt lgkmcnt(2)
	v_pk_fma_f32 v[44:45], v[120:121], v[48:49], v[44:45] op_sel:[1,0,0]
	v_mov_b32_e32 v48, v123
	s_waitcnt lgkmcnt(1)
	v_pk_fma_f32 v[44:45], v[122:123], v[64:65], v[44:45] op_sel_hi:[0,1,1]
	s_waitcnt lgkmcnt(0)
; __device__ void ph_filter_gen(const Params& P, int j, const float* __restrict__ a3, float* __restrict__ kf, float* sl) {
;     ...
;         for (int i = 0; i < 8; ++i) { const int t = tid + NT * i; const float4* ar = (const float4*)(a3 + (size_t)t * 64);
;             float a0 = 0.f, a1 = 0.f, a2 = 0.f, a3v = 0.f;
; #pragma unroll 4
;             for (int jq = 0; jq < 16; ++jq) { const float4 av = ar[jq]; const float ae[4] = {av.x, av.y, av.z, av.w};
; #pragma unroll
;                 for (int e = 0; e < 4; ++e) { const float4 wv = *(const float4*)(sw + (jq * 4 + e) * 4); a0 += ae[e] * wv.x; a1 += ae[e] * wv.y; a2 += ae[e] * wv.z; a3v += ae[e] * wv.w; } }
	v_pk_fma_f32 v[64:65], v[48:49], v[78:79], v[44:45] op_sel_hi:[0,1,1]
	v_pk_fma_f32 v[44:45], v[120:121], v[46:47], v[82:83] op_sel_hi:[0,1,1]
	v_pk_fma_f32 v[44:45], v[120:121], v[50:51], v[44:45] op_sel:[1,0,0]
	s_nop 0
	v_pk_fma_f32 v[44:45], v[122:123], v[66:67], v[44:45] op_sel_hi:[0,1,1]
	v_pk_fma_f32 v[78:79], v[48:49], v[80:81], v[44:45] op_sel_hi:[0,1,1]
	ds_read_b128 v[44:47], v90 offset:128
	ds_read_b128 v[48:51], v90 offset:144
	ds_read_b128 v[60:63], v90 offset:160
	s_waitcnt lgkmcnt(2)
	v_pk_fma_f32 v[44:45], v[124:125], v[44:45], v[64:65] op_sel_hi:[0,1,1]
	ds_read_b128 v[64:67], v90 offset:176
	v_pk_fma_f32 v[46:47], v[124:125], v[46:47], v[78:79] op_sel_hi:[0,1,1]
	s_waitcnt lgkmcnt(2)
	v_pk_fma_f32 v[44:45], v[124:125], v[48:49], v[44:45] op_sel:[1,0,0]
	v_pk_fma_f32 v[46:47], v[124:125], v[50:51], v[46:47] op_sel:[1,0,0]
	s_waitcnt lgkmcnt(1)
	v_pk_fma_f32 v[44:45], v[126:127], v[60:61], v[44:45] op_sel_hi:[0,1,1]
	v_mov_b32_e32 v48, v127
	v_pk_fma_f32 v[46:47], v[126:127], v[62:63], v[46:47] op_sel_hi:[0,1,1]
	s_waitcnt lgkmcnt(0)
	v_pk_fma_f32 v[44:45], v[48:49], v[64:65], v[44:45] op_sel_hi:[0,1,1]
	v_pk_fma_f32 v[50:51], v[48:49], v[66:67], v[46:47] op_sel_hi:[0,1,1]
	ds_read_b128 v[46:49], v90 offset:192
	ds_read_b128 v[56:59], v90 offset:208
	ds_read_b128 v[60:63], v90 offset:224
	ds_read_b128 v[64:67], v90 offset:240
	s_waitcnt lgkmcnt(3)
	v_pk_fma_f32 v[44:45], v[128:129], v[46:47], v[44:45] op_sel_hi:[0,1,1]
	s_waitcnt lgkmcnt(2)
	v_pk_fma_f32 v[44:45], v[128:129], v[56:57], v[44:45] op_sel:[1,0,0]
	v_mov_b32_e32 v56, v131
	s_waitcnt lgkmcnt(1)
	v_pk_fma_f32 v[44:45], v[130:131], v[60:61], v[44:45] op_sel_hi:[0,1,1]
	s_waitcnt lgkmcnt(0)
	v_pk_fma_f32 v[46:47], v[56:57], v[64:65], v[44:45] op_sel_hi:[0,1,1]
	v_pk_fma_f32 v[44:45], v[128:129], v[48:49], v[50:51] op_sel_hi:[0,1,1]
	v_pk_fma_f32 v[44:45], v[128:129], v[58:59], v[44:45] op_sel:[1,0,0]
	s_nop 0
	v_pk_fma_f32 v[44:45], v[130:131], v[62:63], v[44:45] op_sel_hi:[0,1,1]
	v_pk_fma_f32 v[44:45], v[56:57], v[66:67], v[44:45] op_sel_hi:[0,1,1]
	s_add_u32 s100, s78, 0x1e800000
	s_addc_u32 s101, s79, 0
	global_load_dwordx4 v[116:119], v113, s[100:101]
	s_add_u32 s100, s100, 0x10000
	s_addc_u32 s101, s101, 0
	global_load_dwordx4 v[120:123], v113, s[100:101]
	s_add_u32 s100, s100, 0x10000
	s_addc_u32 s101, s101, 0
	global_load_dwordx4 v[124:127], v113, s[100:101]
	s_add_u32 s100, s100, 0x10000
	s_addc_u32 s101, s101, 0
	global_load_dwordx4 v[128:131], v113, s[100:101]
	s_waitcnt vmcnt(12)
	v_mov_b32_e32 v90, 0x100
	ds_read_b128 v[64:67], v90
	ds_read_b128 v[78:81], v90 offset:16
	ds_read_b128 v[82:85], v90 offset:32
	ds_read_b128 v[86:89], v90 offset:48
	s_waitcnt lgkmcnt(3)
	v_pk_fma_f32 v[46:47], v[132:133], v[64:65], v[46:47] op_sel_hi:[0,1,1]
	v_pk_fma_f32 v[44:45], v[132:133], v[66:67], v[44:45] op_sel_hi:[0,1,1]
	s_waitcnt lgkmcnt(2)
	v_pk_fma_f32 v[46:47], v[132:133], v[78:79], v[46:47] op_sel:[1,0,0]
	v_pk_fma_f32 v[44:45], v[132:133], v[80:81], v[44:45] op_sel:[1,0,0]
	s_waitcnt lgkmcnt(1)
	v_pk_fma_f32 v[46:47], v[134:135], v[82:83], v[46:47] op_sel_hi:[0,1,1]
	v_mov_b32_e32 v64, v135
	v_pk_fma_f32 v[44:45], v[134:135], v[84:85], v[44:45] op_sel_hi:[0,1,1]
	s_waitcnt lgkmcnt(0)
	v_pk_fma_f32 v[78:79], v[64:65], v[86:87], v[46:47] op_sel_hi:[0,1,1]
	v_pk_fma_f32 v[82:83], v[64:65], v[88:89], v[44:45] op_sel_hi:[0,1,1]
	ds_read_b128 v[44:47], v90 offset:64
	ds_read_b128 v[48:51], v90 offset:80
	ds_read_b128 v[64:67], v90 offset:96
	s_waitcnt lgkmcnt(2)
	v_pk_fma_f32 v[44:45], v[136:137], v[44:45], v[78:79] op_sel_hi:[0,1,1]
	ds_read_b128 v[78:81], v90 offset:112
	s_waitcnt lgkmcnt(2)
	v_pk_fma_f32 v[44:45], v[136:137], v[48:49], v[44:45] op_sel:[1,0,0]
	v_mov_b32_e32 v48, v139
	s_waitcnt lgkmcnt(1)
	v_pk_fma_f32 v[44:45], v[138:139], v[64:65], v[44:45] op_sel_hi:[0,1,1]
	s_waitcnt lgkmcnt(0)
	v_pk_fma_f32 v[64:65], v[48:49], v[78:79], v[44:45] op_sel_hi:[0,1,1]
	v_pk_fma_f32 v[44:45], v[136:137], v[46:47], v[82:83] op_sel_hi:[0,1,1]
	v_pk_fma_f32 v[44:45], v[136:137], v[50:51], v[44:45] op_sel:[1,0,0]
	s_nop 0
	v_pk_fma_f32 v[44:45], v[138:139], v[66:67], v[44:45] op_sel_hi:[0,1,1]
	v_pk_fma_f32 v[78:79], v[48:49], v[80:81], v[44:45] op_sel_hi:[0,1,1]
	ds_read_b128 v[44:47], v90 offset:128
	ds_read_b128 v[48:51], v90 offset:144
	ds_read_b128 v[60:63], v90 offset:160
	s_waitcnt lgkmcnt(2)
	v_pk_fma_f32 v[44:45], v[140:141], v[44:45], v[64:65] op_sel_hi:[0,1,1]
	ds_read_b128 v[64:67], v90 offset:176
	v_pk_fma_f32 v[46:47], v[140:141], v[46:47], v[78:79] op_sel_hi:[0,1,1]
	s_waitcnt lgkmcnt(2)
	v_pk_fma_f32 v[44:45], v[140:141], v[48:49], v[44:45] op_sel:[1,0,0]
	v_pk_fma_f32 v[46:47], v[140:141], v[50:51], v[46:47] op_sel:[1,0,0]
	s_waitcnt lgkmcnt(1)
	v_pk_fma_f32 v[44:45], v[142:143], v[60:61], v[44:45] op_sel_hi:[0,1,1]
	v_mov_b32_e32 v48, v143
	v_pk_fma_f32 v[46:47], v[142:143], v[62:63], v[46:47] op_sel_hi:[0,1,1]
	s_waitcnt lgkmcnt(0)
	v_pk_fma_f32 v[44:45], v[48:49], v[64:65], v[44:45] op_sel_hi:[0,1,1]
	v_pk_fma_f32 v[50:51], v[48:49], v[66:67], v[46:47] op_sel_hi:[0,1,1]
	ds_read_b128 v[46:49], v90 offset:192
	ds_read_b128 v[56:59], v90 offset:208
	ds_read_b128 v[60:63], v90 offset:224
	ds_read_b128 v[64:67], v90 offset:240
	s_waitcnt lgkmcnt(3)
	v_pk_fma_f32 v[44:45], v[144:145], v[46:47], v[44:45] op_sel_hi:[0,1,1]
	s_waitcnt lgkmcnt(2)
	v_pk_fma_f32 v[44:45], v[144:145], v[56:57], v[44:45] op_sel:[1,0,0]
	v_mov_b32_e32 v56, v147
	s_waitcnt lgkmcnt(1)
	v_pk_fma_f32 v[44:45], v[146:147], v[60:61], v[44:45] op_sel_hi:[0,1,1]
	s_waitcnt lgkmcnt(0)
; __device__ void ph_filter_gen(const Params& P, int j, const float* __restrict__ a3, float* __restrict__ kf, float* sl) {
;     ...
;         for (int i = 0; i < 8; ++i) { const int t = tid + NT * i; const float4* ar = (const float4*)(a3 + (size_t)t * 64);
;             float a0 = 0.f, a1 = 0.f, a2 = 0.f, a3v = 0.f;
; #pragma unroll 4
;             for (int jq = 0; jq < 16; ++jq) { const float4 av = ar[jq]; const float ae[4] = {av.x, av.y, av.z, av.w};
; #pragma unroll
;                 for (int e = 0; e < 4; ++e) { const float4 wv = *(const float4*)(sw + (jq * 4 + e) * 4); a0 += ae[e] * wv.x; a1 += ae[e] * wv.y; a2 += ae[e] * wv.z; a3v += ae[e] * wv.w; } }
	v_pk_fma_f32 v[46:47], v[56:57], v[64:65], v[44:45] op_sel_hi:[0,1,1]
	v_pk_fma_f32 v[44:45], v[144:145], v[48:49], v[50:51] op_sel_hi:[0,1,1]
	v_pk_fma_f32 v[44:45], v[144:145], v[58:59], v[44:45] op_sel:[1,0,0]
	s_nop 0
	v_pk_fma_f32 v[44:45], v[146:147], v[62:63], v[44:45] op_sel_hi:[0,1,1]
	v_pk_fma_f32 v[44:45], v[56:57], v[66:67], v[44:45] op_sel_hi:[0,1,1]
	s_add_u32 s100, s78, 0x1e840000
	s_addc_u32 s101, s79, 0
	global_load_dwordx4 v[132:135], v113, s[100:101]
	s_add_u32 s100, s100, 0x10000
	s_addc_u32 s101, s101, 0
	global_load_dwordx4 v[136:139], v113, s[100:101]
	s_add_u32 s100, s100, 0x10000
	s_addc_u32 s101, s101, 0
	global_load_dwordx4 v[140:143], v113, s[100:101]
	s_add_u32 s100, s100, 0x10000
	s_addc_u32 s101, s101, 0
	global_load_dwordx4 v[144:147], v113, s[100:101]
	s_waitcnt vmcnt(12)
	v_mov_b32_e32 v90, 0x200
	ds_read_b128 v[64:67], v90
	ds_read_b128 v[78:81], v90 offset:16
	ds_read_b128 v[82:85], v90 offset:32
	ds_read_b128 v[86:89], v90 offset:48
	s_waitcnt lgkmcnt(3)
	v_pk_fma_f32 v[46:47], v[148:149], v[64:65], v[46:47] op_sel_hi:[0,1,1]
	v_pk_fma_f32 v[44:45], v[148:149], v[66:67], v[44:45] op_sel_hi:[0,1,1]
	s_waitcnt lgkmcnt(2)
	v_pk_fma_f32 v[46:47], v[148:149], v[78:79], v[46:47] op_sel:[1,0,0]
	v_pk_fma_f32 v[44:45], v[148:149], v[80:81], v[44:45] op_sel:[1,0,0]
	s_waitcnt lgkmcnt(1)
	v_pk_fma_f32 v[46:47], v[150:151], v[82:83], v[46:47] op_sel_hi:[0,1,1]
	v_mov_b32_e32 v64, v151
	v_pk_fma_f32 v[44:45], v[150:151], v[84:85], v[44:45] op_sel_hi:[0,1,1]
	s_waitcnt lgkmcnt(0)
	v_pk_fma_f32 v[78:79], v[64:65], v[86:87], v[46:47] op_sel_hi:[0,1,1]
	v_pk_fma_f32 v[82:83], v[64:65], v[88:89], v[44:45] op_sel_hi:[0,1,1]
	ds_read_b128 v[44:47], v90 offset:64
	ds_read_b128 v[48:51], v90 offset:80
	ds_read_b128 v[64:67], v90 offset:96
	s_waitcnt lgkmcnt(2)
	v_pk_fma_f32 v[44:45], v[152:153], v[44:45], v[78:79] op_sel_hi:[0,1,1]
	ds_read_b128 v[78:81], v90 offset:112
	s_waitcnt lgkmcnt(2)
	v_pk_fma_f32 v[44:45], v[152:153], v[48:49], v[44:45] op_sel:[1,0,0]
	v_mov_b32_e32 v48, v155
	s_waitcnt lgkmcnt(1)
	v_pk_fma_f32 v[44:45], v[154:155], v[64:65], v[44:45] op_sel_hi:[0,1,1]
	s_waitcnt lgkmcnt(0)
	v_pk_fma_f32 v[64:65], v[48:49], v[78:79], v[44:45] op_sel_hi:[0,1,1]
	v_pk_fma_f32 v[44:45], v[152:153], v[46:47], v[82:83] op_sel_hi:[0,1,1]
	v_pk_fma_f32 v[44:45], v[152:153], v[50:51], v[44:45] op_sel:[1,0,0]
	s_nop 0
	v_pk_fma_f32 v[44:45], v[154:155], v[66:67], v[44:45] op_sel_hi:[0,1,1]
	v_pk_fma_f32 v[78:79], v[48:49], v[80:81], v[44:45] op_sel_hi:[0,1,1]
	ds_read_b128 v[44:47], v90 offset:128
	ds_read_b128 v[48:51], v90 offset:144
	ds_read_b128 v[60:63], v90 offset:160
	s_waitcnt lgkmcnt(2)
	v_pk_fma_f32 v[44:45], v[156:157], v[44:45], v[64:65] op_sel_hi:[0,1,1]
	ds_read_b128 v[64:67], v90 offset:176
	v_pk_fma_f32 v[46:47], v[156:157], v[46:47], v[78:79] op_sel_hi:[0,1,1]
	s_waitcnt lgkmcnt(2)
	v_pk_fma_f32 v[44:45], v[156:157], v[48:49], v[44:45] op_sel:[1,0,0]
	v_pk_fma_f32 v[46:47], v[156:157], v[50:51], v[46:47] op_sel:[1,0,0]
	s_waitcnt lgkmcnt(1)
	v_pk_fma_f32 v[44:45], v[158:159], v[60:61], v[44:45] op_sel_hi:[0,1,1]
	v_mov_b32_e32 v48, v159
	v_pk_fma_f32 v[46:47], v[158:159], v[62:63], v[46:47] op_sel_hi:[0,1,1]
	s_waitcnt lgkmcnt(0)
	v_pk_fma_f32 v[44:45], v[48:49], v[64:65], v[44:45] op_sel_hi:[0,1,1]
	v_pk_fma_f32 v[50:51], v[48:49], v[66:67], v[46:47] op_sel_hi:[0,1,1]
	ds_read_b128 v[46:49], v90 offset:192
	ds_read_b128 v[56:59], v90 offset:208
	ds_read_b128 v[60:63], v90 offset:224
	ds_read_b128 v[64:67], v90 offset:240
	s_waitcnt lgkmcnt(3)
	v_pk_fma_f32 v[44:45], v[160:161], v[46:47], v[44:45] op_sel_hi:[0,1,1]
	s_waitcnt lgkmcnt(2)
	v_pk_fma_f32 v[44:45], v[160:161], v[56:57], v[44:45] op_sel:[1,0,0]
	v_mov_b32_e32 v56, v163
	s_waitcnt lgkmcnt(1)
	v_pk_fma_f32 v[44:45], v[162:163], v[60:61], v[44:45] op_sel_hi:[0,1,1]
	s_waitcnt lgkmcnt(0)
	v_pk_fma_f32 v[46:47], v[56:57], v[64:65], v[44:45] op_sel_hi:[0,1,1]
	v_pk_fma_f32 v[44:45], v[160:161], v[48:49], v[50:51] op_sel_hi:[0,1,1]
	v_pk_fma_f32 v[44:45], v[160:161], v[58:59], v[44:45] op_sel:[1,0,0]
	s_nop 0
	v_pk_fma_f32 v[44:45], v[162:163], v[62:63], v[44:45] op_sel_hi:[0,1,1]
	v_pk_fma_f32 v[44:45], v[56:57], v[66:67], v[44:45] op_sel_hi:[0,1,1]
	s_add_u32 s100, s78, 0x1e880000
	s_addc_u32 s101, s79, 0
	global_load_dwordx4 v[148:151], v113, s[100:101]
	s_add_u32 s100, s100, 0x10000
	s_addc_u32 s101, s101, 0
	global_load_dwordx4 v[152:155], v113, s[100:101]
	s_add_u32 s100, s100, 0x10000
	s_addc_u32 s101, s101, 0
	global_load_dwordx4 v[156:159], v113, s[100:101]
	s_add_u32 s100, s100, 0x10000
	s_addc_u32 s101, s101, 0
	global_load_dwordx4 v[160:163], v113, s[100:101]
	s_waitcnt vmcnt(12)
	v_mov_b32_e32 v90, 0x300
	ds_read_b128 v[64:67], v90
	ds_read_b128 v[78:81], v90 offset:16
	ds_read_b128 v[82:85], v90 offset:32
	ds_read_b128 v[86:89], v90 offset:48
	s_waitcnt lgkmcnt(3)
	v_pk_fma_f32 v[46:47], v[164:165], v[64:65], v[46:47] op_sel_hi:[0,1,1]
	v_pk_fma_f32 v[44:45], v[164:165], v[66:67], v[44:45] op_sel_hi:[0,1,1]
	s_waitcnt lgkmcnt(2)
	v_pk_fma_f32 v[46:47], v[164:165], v[78:79], v[46:47] op_sel:[1,0,0]
	v_pk_fma_f32 v[44:45], v[164:165], v[80:81], v[44:45] op_sel:[1,0,0]
	s_waitcnt lgkmcnt(1)
	v_pk_fma_f32 v[46:47], v[166:167], v[82:83], v[46:47] op_sel_hi:[0,1,1]
	v_mov_b32_e32 v64, v167
	v_pk_fma_f32 v[44:45], v[166:167], v[84:85], v[44:45] op_sel_hi:[0,1,1]
	s_waitcnt lgkmcnt(0)
	v_pk_fma_f32 v[78:79], v[64:65], v[86:87], v[46:47] op_sel_hi:[0,1,1]
	v_pk_fma_f32 v[82:83], v[64:65], v[88:89], v[44:45] op_sel_hi:[0,1,1]
	ds_read_b128 v[44:47], v90 offset:64
	ds_read_b128 v[48:51], v90 offset:80
	ds_read_b128 v[64:67], v90 offset:96
	s_waitcnt lgkmcnt(2)
; __device__ void ph_filter_gen(const Params& P, int j, const float* __restrict__ a3, float* __restrict__ kf, float* sl) {
;     ...
;         for (int i = 0; i < 8; ++i) { const int t = tid + NT * i; const float4* ar = (const float4*)(a3 + (size_t)t * 64);
;             float a0 = 0.f, a1 = 0.f, a2 = 0.f, a3v = 0.f;
; #pragma unroll 4
;             for (int jq = 0; jq < 16; ++jq) { const float4 av = ar[jq]; const float ae[4] = {av.x, av.y, av.z, av.w};
; #pragma unroll
;                 for (int e = 0; e < 4; ++e) { const float4 wv = *(const float4*)(sw + (jq * 4 + e) * 4); a0 += ae[e] * wv.x; a1 += ae[e] * wv.y; a2 += ae[e] * wv.z; a3v += ae[e] * wv.w; } }
;             const float dec = expf(-((float)t / (float)(SEQ - 1)) * delta);
	v_pk_fma_f32 v[44:45], v[168:169], v[44:45], v[78:79] op_sel_hi:[0,1,1]
	ds_read_b128 v[78:81], v90 offset:112
	s_waitcnt lgkmcnt(2)
	v_pk_fma_f32 v[44:45], v[168:169], v[48:49], v[44:45] op_sel:[1,0,0]
	v_mov_b32_e32 v48, v171
	s_waitcnt lgkmcnt(1)
	v_pk_fma_f32 v[44:45], v[170:171], v[64:65], v[44:45] op_sel_hi:[0,1,1]
	s_waitcnt lgkmcnt(0)
	v_pk_fma_f32 v[64:65], v[48:49], v[78:79], v[44:45] op_sel_hi:[0,1,1]
	v_pk_fma_f32 v[44:45], v[168:169], v[46:47], v[82:83] op_sel_hi:[0,1,1]
	v_pk_fma_f32 v[44:45], v[168:169], v[50:51], v[44:45] op_sel:[1,0,0]
	s_nop 0
	v_pk_fma_f32 v[44:45], v[170:171], v[66:67], v[44:45] op_sel_hi:[0,1,1]
	v_pk_fma_f32 v[78:79], v[48:49], v[80:81], v[44:45] op_sel_hi:[0,1,1]
	ds_read_b128 v[44:47], v90 offset:128
	ds_read_b128 v[48:51], v90 offset:144
	ds_read_b128 v[60:63], v90 offset:160
	s_waitcnt lgkmcnt(2)
	v_pk_fma_f32 v[44:45], v[172:173], v[44:45], v[64:65] op_sel_hi:[0,1,1]
	ds_read_b128 v[64:67], v90 offset:176
	v_pk_fma_f32 v[46:47], v[172:173], v[46:47], v[78:79] op_sel_hi:[0,1,1]
	s_waitcnt lgkmcnt(2)
	v_pk_fma_f32 v[44:45], v[172:173], v[48:49], v[44:45] op_sel:[1,0,0]
	v_pk_fma_f32 v[46:47], v[172:173], v[50:51], v[46:47] op_sel:[1,0,0]
	s_waitcnt lgkmcnt(1)
	v_pk_fma_f32 v[44:45], v[174:175], v[60:61], v[44:45] op_sel_hi:[0,1,1]
	v_mov_b32_e32 v48, v175
	v_pk_fma_f32 v[46:47], v[174:175], v[62:63], v[46:47] op_sel_hi:[0,1,1]
	s_waitcnt lgkmcnt(0)
	v_pk_fma_f32 v[44:45], v[48:49], v[64:65], v[44:45] op_sel_hi:[0,1,1]
	v_pk_fma_f32 v[50:51], v[48:49], v[66:67], v[46:47] op_sel_hi:[0,1,1]
	ds_read_b128 v[46:49], v90 offset:192
	ds_read_b128 v[56:59], v90 offset:208
	ds_read_b128 v[60:63], v90 offset:224
	ds_read_b128 v[64:67], v90 offset:240
	s_waitcnt lgkmcnt(3)
	v_pk_fma_f32 v[44:45], v[176:177], v[46:47], v[44:45] op_sel_hi:[0,1,1]
	s_waitcnt lgkmcnt(2)
	v_pk_fma_f32 v[44:45], v[176:177], v[56:57], v[44:45] op_sel:[1,0,0]
	v_mov_b32_e32 v56, v179
	s_waitcnt lgkmcnt(1)
	v_pk_fma_f32 v[44:45], v[178:179], v[60:61], v[44:45] op_sel_hi:[0,1,1]
	s_waitcnt lgkmcnt(0)
	v_pk_fma_f32 v[46:47], v[56:57], v[64:65], v[44:45] op_sel_hi:[0,1,1]
	v_pk_fma_f32 v[44:45], v[176:177], v[48:49], v[50:51] op_sel_hi:[0,1,1]
	v_pk_fma_f32 v[44:45], v[176:177], v[58:59], v[44:45] op_sel:[1,0,0]
	s_nop 0
	v_pk_fma_f32 v[44:45], v[178:179], v[62:63], v[44:45] op_sel_hi:[0,1,1]
	v_pk_fma_f32 v[44:45], v[56:57], v[66:67], v[44:45] op_sel_hi:[0,1,1]
	s_add_u32 s100, s78, 0x1e8c0000
	s_addc_u32 s101, s79, 0
	global_load_dwordx4 v[164:167], v113, s[100:101]
	s_add_u32 s100, s100, 0x10000
	s_addc_u32 s101, s101, 0
	global_load_dwordx4 v[168:171], v113, s[100:101]
	s_add_u32 s100, s100, 0x10000
	s_addc_u32 s101, s101, 0
	global_load_dwordx4 v[172:175], v113, s[100:101]
	s_add_u32 s100, s100, 0x10000
	s_addc_u32 s101, s101, 0
	global_load_dwordx4 v[176:179], v113, s[100:101]
	v_mov_b32_e32 v50, 0
	s_mov_b32 s0, 0
	s_mov_b64 s[14:15], 0
	v_mov_b32_e32 v51, v50
	v_mov_b32_e32 v48, v50
	v_mov_b32_e32 v49, v50
.LBB0_227:
	v_lshlrev_b32_e32 v113, 2, v68
	v_add_u32_e32 v113, 0x8000, v113
	s_waitcnt vmcnt(12)
	v_mov_b32_e32 v94, 0
	ds_read_b128 v[78:81], v94
	ds_read_b128 v[82:85], v94 offset:16
	ds_read_b128 v[86:89], v94 offset:32
	ds_read_b128 v[90:93], v94 offset:48
	s_waitcnt lgkmcnt(3)
	v_pk_fma_f32 v[50:51], v[116:117], v[78:79], v[50:51] op_sel_hi:[0,1,1]
	v_pk_fma_f32 v[48:49], v[116:117], v[80:81], v[48:49] op_sel_hi:[0,1,1]
	s_waitcnt lgkmcnt(2)
	v_pk_fma_f32 v[50:51], v[116:117], v[82:83], v[50:51] op_sel:[1,0,0]
	v_pk_fma_f32 v[48:49], v[116:117], v[84:85], v[48:49] op_sel:[1,0,0]
	s_waitcnt lgkmcnt(1)
	v_pk_fma_f32 v[50:51], v[118:119], v[86:87], v[50:51] op_sel_hi:[0,1,1]
	v_mov_b32_e32 v78, v119
	v_pk_fma_f32 v[48:49], v[118:119], v[88:89], v[48:49] op_sel_hi:[0,1,1]
	s_waitcnt lgkmcnt(0)
	v_pk_fma_f32 v[82:83], v[78:79], v[90:91], v[50:51] op_sel_hi:[0,1,1]
	v_pk_fma_f32 v[86:87], v[78:79], v[92:93], v[48:49] op_sel_hi:[0,1,1]
	ds_read_b128 v[48:51], v94 offset:64
	ds_read_b128 v[52:55], v94 offset:80
	ds_read_b128 v[78:81], v94 offset:96
	s_waitcnt lgkmcnt(2)
	v_pk_fma_f32 v[48:49], v[120:121], v[48:49], v[82:83] op_sel_hi:[0,1,1]
	ds_read_b128 v[82:85], v94 offset:112
	s_waitcnt lgkmcnt(2)
	v_pk_fma_f32 v[48:49], v[120:121], v[52:53], v[48:49] op_sel:[1,0,0]
	v_mov_b32_e32 v52, v123
	s_waitcnt lgkmcnt(1)
	v_pk_fma_f32 v[48:49], v[122:123], v[78:79], v[48:49] op_sel_hi:[0,1,1]
	s_waitcnt lgkmcnt(0)
	v_pk_fma_f32 v[78:79], v[52:53], v[82:83], v[48:49] op_sel_hi:[0,1,1]
	v_pk_fma_f32 v[48:49], v[120:121], v[50:51], v[86:87] op_sel_hi:[0,1,1]
	v_pk_fma_f32 v[48:49], v[120:121], v[54:55], v[48:49] op_sel:[1,0,0]
	s_nop 0
	v_pk_fma_f32 v[48:49], v[122:123], v[80:81], v[48:49] op_sel_hi:[0,1,1]
	v_pk_fma_f32 v[82:83], v[52:53], v[84:85], v[48:49] op_sel_hi:[0,1,1]
	ds_read_b128 v[48:51], v94 offset:128
	ds_read_b128 v[52:55], v94 offset:144
	ds_read_b128 v[64:67], v94 offset:160
	s_waitcnt lgkmcnt(2)
	v_pk_fma_f32 v[48:49], v[124:125], v[48:49], v[78:79] op_sel_hi:[0,1,1]
	ds_read_b128 v[78:81], v94 offset:176
	v_pk_fma_f32 v[50:51], v[124:125], v[50:51], v[82:83] op_sel_hi:[0,1,1]
	s_waitcnt lgkmcnt(2)
	v_pk_fma_f32 v[48:49], v[124:125], v[52:53], v[48:49] op_sel:[1,0,0]
	v_pk_fma_f32 v[50:51], v[124:125], v[54:55], v[50:51] op_sel:[1,0,0]
	s_waitcnt lgkmcnt(1)
	v_pk_fma_f32 v[48:49], v[126:127], v[64:65], v[48:49] op_sel_hi:[0,1,1]
	v_mov_b32_e32 v52, v127
	v_pk_fma_f32 v[50:51], v[126:127], v[66:67], v[50:51] op_sel_hi:[0,1,1]
	s_waitcnt lgkmcnt(0)
	v_pk_fma_f32 v[48:49], v[52:53], v[78:79], v[48:49] op_sel_hi:[0,1,1]
	v_pk_fma_f32 v[54:55], v[52:53], v[80:81], v[50:51] op_sel_hi:[0,1,1]
	ds_read_b128 v[50:53], v94 offset:192
	ds_read_b128 v[60:63], v94 offset:208
	ds_read_b128 v[64:67], v94 offset:224
	ds_read_b128 v[78:81], v94 offset:240
	s_waitcnt lgkmcnt(3)
; __device__ void ph_filter_gen(const Params& P, int j, const float* __restrict__ a3, float* __restrict__ kf, float* sl) {
;     ...
;         for (int i = 0; i < 8; ++i) { const int t = tid + NT * i; const float4* ar = (const float4*)(a3 + (size_t)t * 64);
;             float a0 = 0.f, a1 = 0.f, a2 = 0.f, a3v = 0.f;
; #pragma unroll 4
;             for (int jq = 0; jq < 16; ++jq) { const float4 av = ar[jq]; const float ae[4] = {av.x, av.y, av.z, av.w};
; #pragma unroll
;                 for (int e = 0; e < 4; ++e) { const float4 wv = *(const float4*)(sw + (jq * 4 + e) * 4); a0 += ae[e] * wv.x; a1 += ae[e] * wv.y; a2 += ae[e] * wv.z; a3v += ae[e] * wv.w; } }
	v_pk_fma_f32 v[48:49], v[128:129], v[50:51], v[48:49] op_sel_hi:[0,1,1]
	s_waitcnt lgkmcnt(2)
	v_pk_fma_f32 v[48:49], v[128:129], v[60:61], v[48:49] op_sel:[1,0,0]
	v_mov_b32_e32 v60, v131
	s_waitcnt lgkmcnt(1)
	v_pk_fma_f32 v[48:49], v[130:131], v[64:65], v[48:49] op_sel_hi:[0,1,1]
	s_waitcnt lgkmcnt(0)
	v_pk_fma_f32 v[50:51], v[60:61], v[78:79], v[48:49] op_sel_hi:[0,1,1]
	v_pk_fma_f32 v[48:49], v[128:129], v[52:53], v[54:55] op_sel_hi:[0,1,1]
	v_pk_fma_f32 v[48:49], v[128:129], v[62:63], v[48:49] op_sel:[1,0,0]
	s_nop 0
	v_pk_fma_f32 v[48:49], v[130:131], v[66:67], v[48:49] op_sel_hi:[0,1,1]
	v_pk_fma_f32 v[48:49], v[60:61], v[80:81], v[48:49] op_sel_hi:[0,1,1]
	s_add_u32 s100, s78, 0x1e800000
	s_addc_u32 s101, s79, 0
	global_load_dwordx4 v[116:119], v113, s[100:101]
	s_add_u32 s100, s100, 0x10000
	s_addc_u32 s101, s101, 0
	global_load_dwordx4 v[120:123], v113, s[100:101]
	s_add_u32 s100, s100, 0x10000
	s_addc_u32 s101, s101, 0
	global_load_dwordx4 v[124:127], v113, s[100:101]
	s_add_u32 s100, s100, 0x10000
	s_addc_u32 s101, s101, 0
	global_load_dwordx4 v[128:131], v113, s[100:101]
	s_waitcnt vmcnt(12)
	v_mov_b32_e32 v94, 0x100
	ds_read_b128 v[78:81], v94
	ds_read_b128 v[82:85], v94 offset:16
	ds_read_b128 v[86:89], v94 offset:32
	ds_read_b128 v[90:93], v94 offset:48
	s_waitcnt lgkmcnt(3)
	v_pk_fma_f32 v[50:51], v[132:133], v[78:79], v[50:51] op_sel_hi:[0,1,1]
	v_pk_fma_f32 v[48:49], v[132:133], v[80:81], v[48:49] op_sel_hi:[0,1,1]
	s_waitcnt lgkmcnt(2)
	v_pk_fma_f32 v[50:51], v[132:133], v[82:83], v[50:51] op_sel:[1,0,0]
	v_pk_fma_f32 v[48:49], v[132:133], v[84:85], v[48:49] op_sel:[1,0,0]
	s_waitcnt lgkmcnt(1)
	v_pk_fma_f32 v[50:51], v[134:135], v[86:87], v[50:51] op_sel_hi:[0,1,1]
	v_mov_b32_e32 v78, v135
	v_pk_fma_f32 v[48:49], v[134:135], v[88:89], v[48:49] op_sel_hi:[0,1,1]
	s_waitcnt lgkmcnt(0)
	v_pk_fma_f32 v[82:83], v[78:79], v[90:91], v[50:51] op_sel_hi:[0,1,1]
	v_pk_fma_f32 v[86:87], v[78:79], v[92:93], v[48:49] op_sel_hi:[0,1,1]
	ds_read_b128 v[48:51], v94 offset:64
	ds_read_b128 v[52:55], v94 offset:80
	ds_read_b128 v[78:81], v94 offset:96
	s_waitcnt lgkmcnt(2)
	v_pk_fma_f32 v[48:49], v[136:137], v[48:49], v[82:83] op_sel_hi:[0,1,1]
	ds_read_b128 v[82:85], v94 offset:112
	s_waitcnt lgkmcnt(2)
	v_pk_fma_f32 v[48:49], v[136:137], v[52:53], v[48:49] op_sel:[1,0,0]
	v_mov_b32_e32 v52, v139
	s_waitcnt lgkmcnt(1)
	v_pk_fma_f32 v[48:49], v[138:139], v[78:79], v[48:49] op_sel_hi:[0,1,1]
	s_waitcnt lgkmcnt(0)
	v_pk_fma_f32 v[78:79], v[52:53], v[82:83], v[48:49] op_sel_hi:[0,1,1]
	v_pk_fma_f32 v[48:49], v[136:137], v[50:51], v[86:87] op_sel_hi:[0,1,1]
	v_pk_fma_f32 v[48:49], v[136:137], v[54:55], v[48:49] op_sel:[1,0,0]
	s_nop 0
	v_pk_fma_f32 v[48:49], v[138:139], v[80:81], v[48:49] op_sel_hi:[0,1,1]
	v_pk_fma_f32 v[82:83], v[52:53], v[84:85], v[48:49] op_sel_hi:[0,1,1]
	ds_read_b128 v[48:51], v94 offset:128
	ds_read_b128 v[52:55], v94 offset:144
	ds_read_b128 v[64:67], v94 offset:160
	s_waitcnt lgkmcnt(2)
	v_pk_fma_f32 v[48:49], v[140:141], v[48:49], v[78:79] op_sel_hi:[0,1,1]
	ds_read_b128 v[78:81], v94 offset:176
	v_pk_fma_f32 v[50:51], v[140:141], v[50:51], v[82:83] op_sel_hi:[0,1,1]
	s_waitcnt lgkmcnt(2)
	v_pk_fma_f32 v[48:49], v[140:141], v[52:53], v[48:49] op_sel:[1,0,0]
	v_pk_fma_f32 v[50:51], v[140:141], v[54:55], v[50:51] op_sel:[1,0,0]
	s_waitcnt lgkmcnt(1)
	v_pk_fma_f32 v[48:49], v[142:143], v[64:65], v[48:49] op_sel_hi:[0,1,1]
	v_mov_b32_e32 v52, v143
	v_pk_fma_f32 v[50:51], v[142:143], v[66:67], v[50:51] op_sel_hi:[0,1,1]
	s_waitcnt lgkmcnt(0)
	v_pk_fma_f32 v[48:49], v[52:53], v[78:79], v[48:49] op_sel_hi:[0,1,1]
	v_pk_fma_f32 v[54:55], v[52:53], v[80:81], v[50:51] op_sel_hi:[0,1,1]
	ds_read_b128 v[50:53], v94 offset:192
	ds_read_b128 v[60:63], v94 offset:208
	ds_read_b128 v[64:67], v94 offset:224
	ds_read_b128 v[78:81], v94 offset:240
	s_waitcnt lgkmcnt(3)
	v_pk_fma_f32 v[48:49], v[144:145], v[50:51], v[48:49] op_sel_hi:[0,1,1]
	s_waitcnt lgkmcnt(2)
	v_pk_fma_f32 v[48:49], v[144:145], v[60:61], v[48:49] op_sel:[1,0,0]
	v_mov_b32_e32 v60, v147
	s_waitcnt lgkmcnt(1)
	v_pk_fma_f32 v[48:49], v[146:147], v[64:65], v[48:49] op_sel_hi:[0,1,1]
	s_waitcnt lgkmcnt(0)
	v_pk_fma_f32 v[50:51], v[60:61], v[78:79], v[48:49] op_sel_hi:[0,1,1]
	v_pk_fma_f32 v[48:49], v[144:145], v[52:53], v[54:55] op_sel_hi:[0,1,1]
	v_pk_fma_f32 v[48:49], v[144:145], v[62:63], v[48:49] op_sel:[1,0,0]
	s_nop 0
	v_pk_fma_f32 v[48:49], v[146:147], v[66:67], v[48:49] op_sel_hi:[0,1,1]
	v_pk_fma_f32 v[48:49], v[60:61], v[80:81], v[48:49] op_sel_hi:[0,1,1]
	s_add_u32 s100, s78, 0x1e840000
	s_addc_u32 s101, s79, 0
	global_load_dwordx4 v[132:135], v113, s[100:101]
	s_add_u32 s100, s100, 0x10000
	s_addc_u32 s101, s101, 0
	global_load_dwordx4 v[136:139], v113, s[100:101]
	s_add_u32 s100, s100, 0x10000
	s_addc_u32 s101, s101, 0
	global_load_dwordx4 v[140:143], v113, s[100:101]
	s_add_u32 s100, s100, 0x10000
	s_addc_u32 s101, s101, 0
	global_load_dwordx4 v[144:147], v113, s[100:101]
	s_waitcnt vmcnt(12)
	v_mov_b32_e32 v94, 0x200
	ds_read_b128 v[78:81], v94
	ds_read_b128 v[82:85], v94 offset:16
	ds_read_b128 v[86:89], v94 offset:32
	ds_read_b128 v[90:93], v94 offset:48
	s_waitcnt lgkmcnt(3)
	v_pk_fma_f32 v[50:51], v[148:149], v[78:79], v[50:51] op_sel_hi:[0,1,1]
	v_pk_fma_f32 v[48:49], v[148:149], v[80:81], v[48:49] op_sel_hi:[0,1,1]
	s_waitcnt lgkmcnt(2)
	v_pk_fma_f32 v[50:51], v[148:149], v[82:83], v[50:51] op_sel:[1,0,0]
	v_pk_fma_f32 v[48:49], v[148:149], v[84:85], v[48:49] op_sel:[1,0,0]
	s_waitcnt lgkmcnt(1)
	v_pk_fma_f32 v[50:51], v[150:151], v[86:87], v[50:51] op_sel_hi:[0,1,1]
	v_mov_b32_e32 v78, v151
	v_pk_fma_f32 v[48:49], v[150:151], v[88:89], v[48:49] op_sel_hi:[0,1,1]
	s_waitcnt lgkmcnt(0)
; __device__ void ph_filter_gen(const Params& P, int j, const float* __restrict__ a3, float* __restrict__ kf, float* sl) {
;     ...
;         for (int i = 0; i < 8; ++i) { const int t = tid + NT * i; const float4* ar = (const float4*)(a3 + (size_t)t * 64);
;             float a0 = 0.f, a1 = 0.f, a2 = 0.f, a3v = 0.f;
; #pragma unroll 4
;             for (int jq = 0; jq < 16; ++jq) { const float4 av = ar[jq]; const float ae[4] = {av.x, av.y, av.z, av.w};
; #pragma unroll
;                 for (int e = 0; e < 4; ++e) { const float4 wv = *(const float4*)(sw + (jq * 4 + e) * 4); a0 += ae[e] * wv.x; a1 += ae[e] * wv.y; a2 += ae[e] * wv.z; a3v += ae[e] * wv.w; } }
	v_pk_fma_f32 v[82:83], v[78:79], v[90:91], v[50:51] op_sel_hi:[0,1,1]
	v_pk_fma_f32 v[86:87], v[78:79], v[92:93], v[48:49] op_sel_hi:[0,1,1]
	ds_read_b128 v[48:51], v94 offset:64
	ds_read_b128 v[52:55], v94 offset:80
	ds_read_b128 v[78:81], v94 offset:96
	s_waitcnt lgkmcnt(2)
	v_pk_fma_f32 v[48:49], v[152:153], v[48:49], v[82:83] op_sel_hi:[0,1,1]
	ds_read_b128 v[82:85], v94 offset:112
	s_waitcnt lgkmcnt(2)
	v_pk_fma_f32 v[48:49], v[152:153], v[52:53], v[48:49] op_sel:[1,0,0]
	v_mov_b32_e32 v52, v155
	s_waitcnt lgkmcnt(1)
	v_pk_fma_f32 v[48:49], v[154:155], v[78:79], v[48:49] op_sel_hi:[0,1,1]
	s_waitcnt lgkmcnt(0)
	v_pk_fma_f32 v[78:79], v[52:53], v[82:83], v[48:49] op_sel_hi:[0,1,1]
	v_pk_fma_f32 v[48:49], v[152:153], v[50:51], v[86:87] op_sel_hi:[0,1,1]
	v_pk_fma_f32 v[48:49], v[152:153], v[54:55], v[48:49] op_sel:[1,0,0]
	s_nop 0
	v_pk_fma_f32 v[48:49], v[154:155], v[80:81], v[48:49] op_sel_hi:[0,1,1]
	v_pk_fma_f32 v[82:83], v[52:53], v[84:85], v[48:49] op_sel_hi:[0,1,1]
	ds_read_b128 v[48:51], v94 offset:128
	ds_read_b128 v[52:55], v94 offset:144
	ds_read_b128 v[64:67], v94 offset:160
	s_waitcnt lgkmcnt(2)
	v_pk_fma_f32 v[48:49], v[156:157], v[48:49], v[78:79] op_sel_hi:[0,1,1]
	ds_read_b128 v[78:81], v94 offset:176
	v_pk_fma_f32 v[50:51], v[156:157], v[50:51], v[82:83] op_sel_hi:[0,1,1]
	s_waitcnt lgkmcnt(2)
	v_pk_fma_f32 v[48:49], v[156:157], v[52:53], v[48:49] op_sel:[1,0,0]
	v_pk_fma_f32 v[50:51], v[156:157], v[54:55], v[50:51] op_sel:[1,0,0]
	s_waitcnt lgkmcnt(1)
	v_pk_fma_f32 v[48:49], v[158:159], v[64:65], v[48:49] op_sel_hi:[0,1,1]
	v_mov_b32_e32 v52, v159
	v_pk_fma_f32 v[50:51], v[158:159], v[66:67], v[50:51] op_sel_hi:[0,1,1]
	s_waitcnt lgkmcnt(0)
	v_pk_fma_f32 v[48:49], v[52:53], v[78:79], v[48:49] op_sel_hi:[0,1,1]
	v_pk_fma_f32 v[54:55], v[52:53], v[80:81], v[50:51] op_sel_hi:[0,1,1]
	ds_read_b128 v[50:53], v94 offset:192
	ds_read_b128 v[60:63], v94 offset:208
	ds_read_b128 v[64:67], v94 offset:224
	ds_read_b128 v[78:81], v94 offset:240
	s_waitcnt lgkmcnt(3)
	v_pk_fma_f32 v[48:49], v[160:161], v[50:51], v[48:49] op_sel_hi:[0,1,1]
	s_waitcnt lgkmcnt(2)
	v_pk_fma_f32 v[48:49], v[160:161], v[60:61], v[48:49] op_sel:[1,0,0]
	v_mov_b32_e32 v60, v163
	s_waitcnt lgkmcnt(1)
	v_pk_fma_f32 v[48:49], v[162:163], v[64:65], v[48:49] op_sel_hi:[0,1,1]
	s_waitcnt lgkmcnt(0)
	v_pk_fma_f32 v[50:51], v[60:61], v[78:79], v[48:49] op_sel_hi:[0,1,1]
	v_pk_fma_f32 v[48:49], v[160:161], v[52:53], v[54:55] op_sel_hi:[0,1,1]
	v_pk_fma_f32 v[48:49], v[160:161], v[62:63], v[48:49] op_sel:[1,0,0]
	s_nop 0
	v_pk_fma_f32 v[48:49], v[162:163], v[66:67], v[48:49] op_sel_hi:[0,1,1]
	v_pk_fma_f32 v[48:49], v[60:61], v[80:81], v[48:49] op_sel_hi:[0,1,1]
	s_add_u32 s100, s78, 0x1e880000
	s_addc_u32 s101, s79, 0
	global_load_dwordx4 v[148:151], v113, s[100:101]
	s_add_u32 s100, s100, 0x10000
	s_addc_u32 s101, s101, 0
	global_load_dwordx4 v[152:155], v113, s[100:101]
	s_add_u32 s100, s100, 0x10000
	s_addc_u32 s101, s101, 0
	global_load_dwordx4 v[156:159], v113, s[100:101]
	s_add_u32 s100, s100, 0x10000
	s_addc_u32 s101, s101, 0
	global_load_dwordx4 v[160:163], v113, s[100:101]
	s_waitcnt vmcnt(12)
	v_mov_b32_e32 v94, 0x300
	ds_read_b128 v[78:81], v94
	ds_read_b128 v[82:85], v94 offset:16
	ds_read_b128 v[86:89], v94 offset:32
	ds_read_b128 v[90:93], v94 offset:48
	s_waitcnt lgkmcnt(3)
	v_pk_fma_f32 v[50:51], v[164:165], v[78:79], v[50:51] op_sel_hi:[0,1,1]
	v_pk_fma_f32 v[48:49], v[164:165], v[80:81], v[48:49] op_sel_hi:[0,1,1]
	s_waitcnt lgkmcnt(2)
	v_pk_fma_f32 v[50:51], v[164:165], v[82:83], v[50:51] op_sel:[1,0,0]
	v_pk_fma_f32 v[48:49], v[164:165], v[84:85], v[48:49] op_sel:[1,0,0]
	s_waitcnt lgkmcnt(1)
	v_pk_fma_f32 v[50:51], v[166:167], v[86:87], v[50:51] op_sel_hi:[0,1,1]
	v_mov_b32_e32 v78, v167
	v_pk_fma_f32 v[48:49], v[166:167], v[88:89], v[48:49] op_sel_hi:[0,1,1]
	s_waitcnt lgkmcnt(0)
	v_pk_fma_f32 v[82:83], v[78:79], v[90:91], v[50:51] op_sel_hi:[0,1,1]
	v_pk_fma_f32 v[86:87], v[78:79], v[92:93], v[48:49] op_sel_hi:[0,1,1]
	ds_read_b128 v[48:51], v94 offset:64
	ds_read_b128 v[52:55], v94 offset:80
	ds_read_b128 v[78:81], v94 offset:96
	s_waitcnt lgkmcnt(2)
	v_pk_fma_f32 v[48:49], v[168:169], v[48:49], v[82:83] op_sel_hi:[0,1,1]
	ds_read_b128 v[82:85], v94 offset:112
	s_waitcnt lgkmcnt(2)
	v_pk_fma_f32 v[48:49], v[168:169], v[52:53], v[48:49] op_sel:[1,0,0]
	v_mov_b32_e32 v52, v171
	s_waitcnt lgkmcnt(1)
	v_pk_fma_f32 v[48:49], v[170:171], v[78:79], v[48:49] op_sel_hi:[0,1,1]
	s_waitcnt lgkmcnt(0)
	v_pk_fma_f32 v[78:79], v[52:53], v[82:83], v[48:49] op_sel_hi:[0,1,1]
	v_pk_fma_f32 v[48:49], v[168:169], v[50:51], v[86:87] op_sel_hi:[0,1,1]
	v_pk_fma_f32 v[48:49], v[168:169], v[54:55], v[48:49] op_sel:[1,0,0]
	s_nop 0
	v_pk_fma_f32 v[48:49], v[170:171], v[80:81], v[48:49] op_sel_hi:[0,1,1]
	v_pk_fma_f32 v[82:83], v[52:53], v[84:85], v[48:49] op_sel_hi:[0,1,1]
	ds_read_b128 v[48:51], v94 offset:128
	ds_read_b128 v[52:55], v94 offset:144
	ds_read_b128 v[64:67], v94 offset:160
	s_waitcnt lgkmcnt(2)
	v_pk_fma_f32 v[48:49], v[172:173], v[48:49], v[78:79] op_sel_hi:[0,1,1]
	ds_read_b128 v[78:81], v94 offset:176
	v_pk_fma_f32 v[50:51], v[172:173], v[50:51], v[82:83] op_sel_hi:[0,1,1]
	s_waitcnt lgkmcnt(2)
	v_pk_fma_f32 v[48:49], v[172:173], v[52:53], v[48:49] op_sel:[1,0,0]
	v_pk_fma_f32 v[50:51], v[172:173], v[54:55], v[50:51] op_sel:[1,0,0]
	s_waitcnt lgkmcnt(1)
	v_pk_fma_f32 v[48:49], v[174:175], v[64:65], v[48:49] op_sel_hi:[0,1,1]
	v_mov_b32_e32 v52, v175
	v_pk_fma_f32 v[50:51], v[174:175], v[66:67], v[50:51] op_sel_hi:[0,1,1]
	s_waitcnt lgkmcnt(0)
; __device__ void ph_filter_gen(const Params& P, int j, const float* __restrict__ a3, float* __restrict__ kf, float* sl) {
;     ...
;         for (int i = 0; i < 8; ++i) { const int t = tid + NT * i; const float4* ar = (const float4*)(a3 + (size_t)t * 64);
;             float a0 = 0.f, a1 = 0.f, a2 = 0.f, a3v = 0.f;
; #pragma unroll 4
;             for (int jq = 0; jq < 16; ++jq) { const float4 av = ar[jq]; const float ae[4] = {av.x, av.y, av.z, av.w};
; #pragma unroll
;                 for (int e = 0; e < 4; ++e) { const float4 wv = *(const float4*)(sw + (jq * 4 + e) * 4); a0 += ae[e] * wv.x; a1 += ae[e] * wv.y; a2 += ae[e] * wv.z; a3v += ae[e] * wv.w; } }
;             const float dec = expf(-((float)t / (float)(SEQ - 1)) * delta);
	v_pk_fma_f32 v[48:49], v[52:53], v[78:79], v[48:49] op_sel_hi:[0,1,1]
	v_pk_fma_f32 v[54:55], v[52:53], v[80:81], v[50:51] op_sel_hi:[0,1,1]
	ds_read_b128 v[50:53], v94 offset:192
	ds_read_b128 v[60:63], v94 offset:208
	ds_read_b128 v[64:67], v94 offset:224
	ds_read_b128 v[78:81], v94 offset:240
	s_waitcnt lgkmcnt(3)
	v_pk_fma_f32 v[48:49], v[176:177], v[50:51], v[48:49] op_sel_hi:[0,1,1]
	s_waitcnt lgkmcnt(2)
	v_pk_fma_f32 v[48:49], v[176:177], v[60:61], v[48:49] op_sel:[1,0,0]
	v_mov_b32_e32 v60, v179
	s_waitcnt lgkmcnt(1)
	v_pk_fma_f32 v[48:49], v[178:179], v[64:65], v[48:49] op_sel_hi:[0,1,1]
	s_waitcnt lgkmcnt(0)
	v_pk_fma_f32 v[50:51], v[60:61], v[78:79], v[48:49] op_sel_hi:[0,1,1]
	v_pk_fma_f32 v[48:49], v[176:177], v[52:53], v[54:55] op_sel_hi:[0,1,1]
	v_pk_fma_f32 v[48:49], v[176:177], v[62:63], v[48:49] op_sel:[1,0,0]
	s_nop 0
	v_pk_fma_f32 v[48:49], v[178:179], v[66:67], v[48:49] op_sel_hi:[0,1,1]
	v_pk_fma_f32 v[48:49], v[60:61], v[80:81], v[48:49] op_sel_hi:[0,1,1]
	s_add_u32 s100, s78, 0x1e8c0000
	s_addc_u32 s101, s79, 0
	global_load_dwordx4 v[164:167], v113, s[100:101]
	s_add_u32 s100, s100, 0x10000
	s_addc_u32 s101, s101, 0
	global_load_dwordx4 v[168:171], v113, s[100:101]
	s_add_u32 s100, s100, 0x10000
	s_addc_u32 s101, s101, 0
	global_load_dwordx4 v[172:175], v113, s[100:101]
	s_add_u32 s100, s100, 0x10000
	s_addc_u32 s101, s101, 0
	global_load_dwordx4 v[176:179], v113, s[100:101]
	v_mov_b32_e32 v54, 0
	s_mov_b32 s0, 0
	s_mov_b64 s[14:15], 0
	v_mov_b32_e32 v55, v54
	v_mov_b32_e32 v52, v54
	v_mov_b32_e32 v53, v54
.LBB0_229:
	v_lshlrev_b32_e32 v113, 2, v68
	v_add_u32_e32 v113, 0xa000, v113
	s_waitcnt vmcnt(12)
	v_mov_b32_e32 v98, 0
	ds_read_b128 v[82:85], v98
	ds_read_b128 v[86:89], v98 offset:16
	ds_read_b128 v[90:93], v98 offset:32
	ds_read_b128 v[94:97], v98 offset:48
	s_waitcnt lgkmcnt(3)
	v_pk_fma_f32 v[54:55], v[116:117], v[82:83], v[54:55] op_sel_hi:[0,1,1]
	v_pk_fma_f32 v[52:53], v[116:117], v[84:85], v[52:53] op_sel_hi:[0,1,1]
	s_waitcnt lgkmcnt(2)
	v_pk_fma_f32 v[54:55], v[116:117], v[86:87], v[54:55] op_sel:[1,0,0]
	v_pk_fma_f32 v[52:53], v[116:117], v[88:89], v[52:53] op_sel:[1,0,0]
	s_waitcnt lgkmcnt(1)
	v_pk_fma_f32 v[54:55], v[118:119], v[90:91], v[54:55] op_sel_hi:[0,1,1]
	v_mov_b32_e32 v82, v119
	v_pk_fma_f32 v[52:53], v[118:119], v[92:93], v[52:53] op_sel_hi:[0,1,1]
	s_waitcnt lgkmcnt(0)
	v_pk_fma_f32 v[86:87], v[82:83], v[94:95], v[54:55] op_sel_hi:[0,1,1]
	v_pk_fma_f32 v[90:91], v[82:83], v[96:97], v[52:53] op_sel_hi:[0,1,1]
	ds_read_b128 v[52:55], v98 offset:64
	ds_read_b128 v[56:59], v98 offset:80
	ds_read_b128 v[82:85], v98 offset:96
	s_waitcnt lgkmcnt(2)
	v_pk_fma_f32 v[52:53], v[120:121], v[52:53], v[86:87] op_sel_hi:[0,1,1]
	ds_read_b128 v[86:89], v98 offset:112
	s_waitcnt lgkmcnt(2)
	v_pk_fma_f32 v[52:53], v[120:121], v[56:57], v[52:53] op_sel:[1,0,0]
	v_mov_b32_e32 v56, v123
	s_waitcnt lgkmcnt(1)
	v_pk_fma_f32 v[52:53], v[122:123], v[82:83], v[52:53] op_sel_hi:[0,1,1]
	s_waitcnt lgkmcnt(0)
	v_pk_fma_f32 v[82:83], v[56:57], v[86:87], v[52:53] op_sel_hi:[0,1,1]
	v_pk_fma_f32 v[52:53], v[120:121], v[54:55], v[90:91] op_sel_hi:[0,1,1]
	v_pk_fma_f32 v[52:53], v[120:121], v[58:59], v[52:53] op_sel:[1,0,0]
	s_nop 0
	v_pk_fma_f32 v[52:53], v[122:123], v[84:85], v[52:53] op_sel_hi:[0,1,1]
	v_pk_fma_f32 v[86:87], v[56:57], v[88:89], v[52:53] op_sel_hi:[0,1,1]
	ds_read_b128 v[52:55], v98 offset:128
	ds_read_b128 v[56:59], v98 offset:144
	ds_read_b128 v[78:81], v98 offset:160
	s_waitcnt lgkmcnt(2)
	v_pk_fma_f32 v[52:53], v[124:125], v[52:53], v[82:83] op_sel_hi:[0,1,1]
	ds_read_b128 v[82:85], v98 offset:176
	v_pk_fma_f32 v[54:55], v[124:125], v[54:55], v[86:87] op_sel_hi:[0,1,1]
	s_waitcnt lgkmcnt(2)
	v_pk_fma_f32 v[52:53], v[124:125], v[56:57], v[52:53] op_sel:[1,0,0]
	v_pk_fma_f32 v[54:55], v[124:125], v[58:59], v[54:55] op_sel:[1,0,0]
	s_waitcnt lgkmcnt(1)
	v_pk_fma_f32 v[52:53], v[126:127], v[78:79], v[52:53] op_sel_hi:[0,1,1]
	v_mov_b32_e32 v56, v127
	v_pk_fma_f32 v[54:55], v[126:127], v[80:81], v[54:55] op_sel_hi:[0,1,1]
	s_waitcnt lgkmcnt(0)
	v_pk_fma_f32 v[52:53], v[56:57], v[82:83], v[52:53] op_sel_hi:[0,1,1]
	v_pk_fma_f32 v[58:59], v[56:57], v[84:85], v[54:55] op_sel_hi:[0,1,1]
	ds_read_b128 v[54:57], v98 offset:192
	ds_read_b128 v[64:67], v98 offset:208
	ds_read_b128 v[78:81], v98 offset:224
	ds_read_b128 v[82:85], v98 offset:240
	s_waitcnt lgkmcnt(3)
	v_pk_fma_f32 v[52:53], v[128:129], v[54:55], v[52:53] op_sel_hi:[0,1,1]
	s_waitcnt lgkmcnt(2)
	v_pk_fma_f32 v[52:53], v[128:129], v[64:65], v[52:53] op_sel:[1,0,0]
	v_mov_b32_e32 v64, v131
	s_waitcnt lgkmcnt(1)
	v_pk_fma_f32 v[52:53], v[130:131], v[78:79], v[52:53] op_sel_hi:[0,1,1]
	s_waitcnt lgkmcnt(0)
	v_pk_fma_f32 v[54:55], v[64:65], v[82:83], v[52:53] op_sel_hi:[0,1,1]
	v_pk_fma_f32 v[52:53], v[128:129], v[56:57], v[58:59] op_sel_hi:[0,1,1]
	v_pk_fma_f32 v[52:53], v[128:129], v[66:67], v[52:53] op_sel:[1,0,0]
	s_nop 0
	v_pk_fma_f32 v[52:53], v[130:131], v[80:81], v[52:53] op_sel_hi:[0,1,1]
	v_pk_fma_f32 v[52:53], v[64:65], v[84:85], v[52:53] op_sel_hi:[0,1,1]
	s_add_u32 s100, s78, 0x1e800000
	s_addc_u32 s101, s79, 0
	global_load_dwordx4 v[116:119], v113, s[100:101]
	s_add_u32 s100, s100, 0x10000
	s_addc_u32 s101, s101, 0
	global_load_dwordx4 v[120:123], v113, s[100:101]
	s_add_u32 s100, s100, 0x10000
	s_addc_u32 s101, s101, 0
	global_load_dwordx4 v[124:127], v113, s[100:101]
	s_add_u32 s100, s100, 0x10000
	s_addc_u32 s101, s101, 0
	global_load_dwordx4 v[128:131], v113, s[100:101]
	s_waitcnt vmcnt(12)
	v_mov_b32_e32 v98, 0x100
	ds_read_b128 v[82:85], v98
	ds_read_b128 v[86:89], v98 offset:16
	ds_read_b128 v[90:93], v98 offset:32
	ds_read_b128 v[94:97], v98 offset:48
	s_waitcnt lgkmcnt(3)
; __device__ void ph_filter_gen(const Params& P, int j, const float* __restrict__ a3, float* __restrict__ kf, float* sl) {
;     ...
;         for (int i = 0; i < 8; ++i) { const int t = tid + NT * i; const float4* ar = (const float4*)(a3 + (size_t)t * 64);
;             float a0 = 0.f, a1 = 0.f, a2 = 0.f, a3v = 0.f;
; #pragma unroll 4
;             for (int jq = 0; jq < 16; ++jq) { const float4 av = ar[jq]; const float ae[4] = {av.x, av.y, av.z, av.w};
; #pragma unroll
;                 for (int e = 0; e < 4; ++e) { const float4 wv = *(const float4*)(sw + (jq * 4 + e) * 4); a0 += ae[e] * wv.x; a1 += ae[e] * wv.y; a2 += ae[e] * wv.z; a3v += ae[e] * wv.w; } }
	v_pk_fma_f32 v[54:55], v[132:133], v[82:83], v[54:55] op_sel_hi:[0,1,1]
	v_pk_fma_f32 v[52:53], v[132:133], v[84:85], v[52:53] op_sel_hi:[0,1,1]
	s_waitcnt lgkmcnt(2)
	v_pk_fma_f32 v[54:55], v[132:133], v[86:87], v[54:55] op_sel:[1,0,0]
	v_pk_fma_f32 v[52:53], v[132:133], v[88:89], v[52:53] op_sel:[1,0,0]
	s_waitcnt lgkmcnt(1)
	v_pk_fma_f32 v[54:55], v[134:135], v[90:91], v[54:55] op_sel_hi:[0,1,1]
	v_mov_b32_e32 v82, v135
	v_pk_fma_f32 v[52:53], v[134:135], v[92:93], v[52:53] op_sel_hi:[0,1,1]
	s_waitcnt lgkmcnt(0)
	v_pk_fma_f32 v[86:87], v[82:83], v[94:95], v[54:55] op_sel_hi:[0,1,1]
	v_pk_fma_f32 v[90:91], v[82:83], v[96:97], v[52:53] op_sel_hi:[0,1,1]
	ds_read_b128 v[52:55], v98 offset:64
	ds_read_b128 v[56:59], v98 offset:80
	ds_read_b128 v[82:85], v98 offset:96
	s_waitcnt lgkmcnt(2)
	v_pk_fma_f32 v[52:53], v[136:137], v[52:53], v[86:87] op_sel_hi:[0,1,1]
	ds_read_b128 v[86:89], v98 offset:112
	s_waitcnt lgkmcnt(2)
	v_pk_fma_f32 v[52:53], v[136:137], v[56:57], v[52:53] op_sel:[1,0,0]
	v_mov_b32_e32 v56, v139
	s_waitcnt lgkmcnt(1)
	v_pk_fma_f32 v[52:53], v[138:139], v[82:83], v[52:53] op_sel_hi:[0,1,1]
	s_waitcnt lgkmcnt(0)
	v_pk_fma_f32 v[82:83], v[56:57], v[86:87], v[52:53] op_sel_hi:[0,1,1]
	v_pk_fma_f32 v[52:53], v[136:137], v[54:55], v[90:91] op_sel_hi:[0,1,1]
	v_pk_fma_f32 v[52:53], v[136:137], v[58:59], v[52:53] op_sel:[1,0,0]
	s_nop 0
	v_pk_fma_f32 v[52:53], v[138:139], v[84:85], v[52:53] op_sel_hi:[0,1,1]
	v_pk_fma_f32 v[86:87], v[56:57], v[88:89], v[52:53] op_sel_hi:[0,1,1]
	ds_read_b128 v[52:55], v98 offset:128
	ds_read_b128 v[56:59], v98 offset:144
	ds_read_b128 v[78:81], v98 offset:160
	s_waitcnt lgkmcnt(2)
	v_pk_fma_f32 v[52:53], v[140:141], v[52:53], v[82:83] op_sel_hi:[0,1,1]
	ds_read_b128 v[82:85], v98 offset:176
	v_pk_fma_f32 v[54:55], v[140:141], v[54:55], v[86:87] op_sel_hi:[0,1,1]
	s_waitcnt lgkmcnt(2)
	v_pk_fma_f32 v[52:53], v[140:141], v[56:57], v[52:53] op_sel:[1,0,0]
	v_pk_fma_f32 v[54:55], v[140:141], v[58:59], v[54:55] op_sel:[1,0,0]
	s_waitcnt lgkmcnt(1)
	v_pk_fma_f32 v[52:53], v[142:143], v[78:79], v[52:53] op_sel_hi:[0,1,1]
	v_mov_b32_e32 v56, v143
	v_pk_fma_f32 v[54:55], v[142:143], v[80:81], v[54:55] op_sel_hi:[0,1,1]
	s_waitcnt lgkmcnt(0)
	v_pk_fma_f32 v[52:53], v[56:57], v[82:83], v[52:53] op_sel_hi:[0,1,1]
	v_pk_fma_f32 v[58:59], v[56:57], v[84:85], v[54:55] op_sel_hi:[0,1,1]
	ds_read_b128 v[54:57], v98 offset:192
	ds_read_b128 v[64:67], v98 offset:208
	ds_read_b128 v[78:81], v98 offset:224
	ds_read_b128 v[82:85], v98 offset:240
	s_waitcnt lgkmcnt(3)
	v_pk_fma_f32 v[52:53], v[144:145], v[54:55], v[52:53] op_sel_hi:[0,1,1]
	s_waitcnt lgkmcnt(2)
	v_pk_fma_f32 v[52:53], v[144:145], v[64:65], v[52:53] op_sel:[1,0,0]
	v_mov_b32_e32 v64, v147
	s_waitcnt lgkmcnt(1)
	v_pk_fma_f32 v[52:53], v[146:147], v[78:79], v[52:53] op_sel_hi:[0,1,1]
	s_waitcnt lgkmcnt(0)
	v_pk_fma_f32 v[54:55], v[64:65], v[82:83], v[52:53] op_sel_hi:[0,1,1]
	v_pk_fma_f32 v[52:53], v[144:145], v[56:57], v[58:59] op_sel_hi:[0,1,1]
	v_pk_fma_f32 v[52:53], v[144:145], v[66:67], v[52:53] op_sel:[1,0,0]
	s_nop 0
	v_pk_fma_f32 v[52:53], v[146:147], v[80:81], v[52:53] op_sel_hi:[0,1,1]
	v_pk_fma_f32 v[52:53], v[64:65], v[84:85], v[52:53] op_sel_hi:[0,1,1]
	s_add_u32 s100, s78, 0x1e840000
	s_addc_u32 s101, s79, 0
	global_load_dwordx4 v[132:135], v113, s[100:101]
	s_add_u32 s100, s100, 0x10000
	s_addc_u32 s101, s101, 0
	global_load_dwordx4 v[136:139], v113, s[100:101]
	s_add_u32 s100, s100, 0x10000
	s_addc_u32 s101, s101, 0
	global_load_dwordx4 v[140:143], v113, s[100:101]
	s_add_u32 s100, s100, 0x10000
	s_addc_u32 s101, s101, 0
	global_load_dwordx4 v[144:147], v113, s[100:101]
	s_waitcnt vmcnt(12)
	v_mov_b32_e32 v98, 0x200
	ds_read_b128 v[82:85], v98
	ds_read_b128 v[86:89], v98 offset:16
	ds_read_b128 v[90:93], v98 offset:32
	ds_read_b128 v[94:97], v98 offset:48
	s_waitcnt lgkmcnt(3)
	v_pk_fma_f32 v[54:55], v[148:149], v[82:83], v[54:55] op_sel_hi:[0,1,1]
	v_pk_fma_f32 v[52:53], v[148:149], v[84:85], v[52:53] op_sel_hi:[0,1,1]
	s_waitcnt lgkmcnt(2)
	v_pk_fma_f32 v[54:55], v[148:149], v[86:87], v[54:55] op_sel:[1,0,0]
	v_pk_fma_f32 v[52:53], v[148:149], v[88:89], v[52:53] op_sel:[1,0,0]
	s_waitcnt lgkmcnt(1)
	v_pk_fma_f32 v[54:55], v[150:151], v[90:91], v[54:55] op_sel_hi:[0,1,1]
	v_mov_b32_e32 v82, v151
	v_pk_fma_f32 v[52:53], v[150:151], v[92:93], v[52:53] op_sel_hi:[0,1,1]
	s_waitcnt lgkmcnt(0)
	v_pk_fma_f32 v[86:87], v[82:83], v[94:95], v[54:55] op_sel_hi:[0,1,1]
	v_pk_fma_f32 v[90:91], v[82:83], v[96:97], v[52:53] op_sel_hi:[0,1,1]
	ds_read_b128 v[52:55], v98 offset:64
	ds_read_b128 v[56:59], v98 offset:80
	ds_read_b128 v[82:85], v98 offset:96
	s_waitcnt lgkmcnt(2)
	v_pk_fma_f32 v[52:53], v[152:153], v[52:53], v[86:87] op_sel_hi:[0,1,1]
	ds_read_b128 v[86:89], v98 offset:112
	s_waitcnt lgkmcnt(2)
	v_pk_fma_f32 v[52:53], v[152:153], v[56:57], v[52:53] op_sel:[1,0,0]
	v_mov_b32_e32 v56, v155
	s_waitcnt lgkmcnt(1)
	v_pk_fma_f32 v[52:53], v[154:155], v[82:83], v[52:53] op_sel_hi:[0,1,1]
	s_waitcnt lgkmcnt(0)
	v_pk_fma_f32 v[82:83], v[56:57], v[86:87], v[52:53] op_sel_hi:[0,1,1]
	v_pk_fma_f32 v[52:53], v[152:153], v[54:55], v[90:91] op_sel_hi:[0,1,1]
	v_pk_fma_f32 v[52:53], v[152:153], v[58:59], v[52:53] op_sel:[1,0,0]
	s_nop 0
	v_pk_fma_f32 v[52:53], v[154:155], v[84:85], v[52:53] op_sel_hi:[0,1,1]
	v_pk_fma_f32 v[86:87], v[56:57], v[88:89], v[52:53] op_sel_hi:[0,1,1]
	ds_read_b128 v[52:55], v98 offset:128
	ds_read_b128 v[56:59], v98 offset:144
	ds_read_b128 v[78:81], v98 offset:160
	s_waitcnt lgkmcnt(2)
	v_pk_fma_f32 v[52:53], v[156:157], v[52:53], v[82:83] op_sel_hi:[0,1,1]
	ds_read_b128 v[82:85], v98 offset:176
	v_pk_fma_f32 v[54:55], v[156:157], v[54:55], v[86:87] op_sel_hi:[0,1,1]
	s_waitcnt lgkmcnt(2)
; __device__ void ph_filter_gen(const Params& P, int j, const float* __restrict__ a3, float* __restrict__ kf, float* sl) {
;     ...
;         for (int i = 0; i < 8; ++i) { const int t = tid + NT * i; const float4* ar = (const float4*)(a3 + (size_t)t * 64);
;             float a0 = 0.f, a1 = 0.f, a2 = 0.f, a3v = 0.f;
; #pragma unroll 4
;             for (int jq = 0; jq < 16; ++jq) { const float4 av = ar[jq]; const float ae[4] = {av.x, av.y, av.z, av.w};
; #pragma unroll
;                 for (int e = 0; e < 4; ++e) { const float4 wv = *(const float4*)(sw + (jq * 4 + e) * 4); a0 += ae[e] * wv.x; a1 += ae[e] * wv.y; a2 += ae[e] * wv.z; a3v += ae[e] * wv.w; } }
	v_pk_fma_f32 v[52:53], v[156:157], v[56:57], v[52:53] op_sel:[1,0,0]
	v_pk_fma_f32 v[54:55], v[156:157], v[58:59], v[54:55] op_sel:[1,0,0]
	s_waitcnt lgkmcnt(1)
	v_pk_fma_f32 v[52:53], v[158:159], v[78:79], v[52:53] op_sel_hi:[0,1,1]
	v_mov_b32_e32 v56, v159
	v_pk_fma_f32 v[54:55], v[158:159], v[80:81], v[54:55] op_sel_hi:[0,1,1]
	s_waitcnt lgkmcnt(0)
	v_pk_fma_f32 v[52:53], v[56:57], v[82:83], v[52:53] op_sel_hi:[0,1,1]
	v_pk_fma_f32 v[58:59], v[56:57], v[84:85], v[54:55] op_sel_hi:[0,1,1]
	ds_read_b128 v[54:57], v98 offset:192
	ds_read_b128 v[64:67], v98 offset:208
	ds_read_b128 v[78:81], v98 offset:224
	ds_read_b128 v[82:85], v98 offset:240
	s_waitcnt lgkmcnt(3)
	v_pk_fma_f32 v[52:53], v[160:161], v[54:55], v[52:53] op_sel_hi:[0,1,1]
	s_waitcnt lgkmcnt(2)
	v_pk_fma_f32 v[52:53], v[160:161], v[64:65], v[52:53] op_sel:[1,0,0]
	v_mov_b32_e32 v64, v163
	s_waitcnt lgkmcnt(1)
	v_pk_fma_f32 v[52:53], v[162:163], v[78:79], v[52:53] op_sel_hi:[0,1,1]
	s_waitcnt lgkmcnt(0)
	v_pk_fma_f32 v[54:55], v[64:65], v[82:83], v[52:53] op_sel_hi:[0,1,1]
	v_pk_fma_f32 v[52:53], v[160:161], v[56:57], v[58:59] op_sel_hi:[0,1,1]
	v_pk_fma_f32 v[52:53], v[160:161], v[66:67], v[52:53] op_sel:[1,0,0]
	s_nop 0
	v_pk_fma_f32 v[52:53], v[162:163], v[80:81], v[52:53] op_sel_hi:[0,1,1]
	v_pk_fma_f32 v[52:53], v[64:65], v[84:85], v[52:53] op_sel_hi:[0,1,1]
	s_add_u32 s100, s78, 0x1e880000
	s_addc_u32 s101, s79, 0
	global_load_dwordx4 v[148:151], v113, s[100:101]
	s_add_u32 s100, s100, 0x10000
	s_addc_u32 s101, s101, 0
	global_load_dwordx4 v[152:155], v113, s[100:101]
	s_add_u32 s100, s100, 0x10000
	s_addc_u32 s101, s101, 0
	global_load_dwordx4 v[156:159], v113, s[100:101]
	s_add_u32 s100, s100, 0x10000
	s_addc_u32 s101, s101, 0
	global_load_dwordx4 v[160:163], v113, s[100:101]
	s_waitcnt vmcnt(12)
	v_mov_b32_e32 v98, 0x300
	ds_read_b128 v[82:85], v98
	ds_read_b128 v[86:89], v98 offset:16
	ds_read_b128 v[90:93], v98 offset:32
	ds_read_b128 v[94:97], v98 offset:48
	s_waitcnt lgkmcnt(3)
	v_pk_fma_f32 v[54:55], v[164:165], v[82:83], v[54:55] op_sel_hi:[0,1,1]
	v_pk_fma_f32 v[52:53], v[164:165], v[84:85], v[52:53] op_sel_hi:[0,1,1]
	s_waitcnt lgkmcnt(2)
	v_pk_fma_f32 v[54:55], v[164:165], v[86:87], v[54:55] op_sel:[1,0,0]
	v_pk_fma_f32 v[52:53], v[164:165], v[88:89], v[52:53] op_sel:[1,0,0]
	s_waitcnt lgkmcnt(1)
	v_pk_fma_f32 v[54:55], v[166:167], v[90:91], v[54:55] op_sel_hi:[0,1,1]
	v_mov_b32_e32 v82, v167
	v_pk_fma_f32 v[52:53], v[166:167], v[92:93], v[52:53] op_sel_hi:[0,1,1]
	s_waitcnt lgkmcnt(0)
	v_pk_fma_f32 v[86:87], v[82:83], v[94:95], v[54:55] op_sel_hi:[0,1,1]
	v_pk_fma_f32 v[90:91], v[82:83], v[96:97], v[52:53] op_sel_hi:[0,1,1]
	ds_read_b128 v[52:55], v98 offset:64
	ds_read_b128 v[56:59], v98 offset:80
	ds_read_b128 v[82:85], v98 offset:96
	s_waitcnt lgkmcnt(2)
	v_pk_fma_f32 v[52:53], v[168:169], v[52:53], v[86:87] op_sel_hi:[0,1,1]
	ds_read_b128 v[86:89], v98 offset:112
	s_waitcnt lgkmcnt(2)
	v_pk_fma_f32 v[52:53], v[168:169], v[56:57], v[52:53] op_sel:[1,0,0]
	v_mov_b32_e32 v56, v171
	s_waitcnt lgkmcnt(1)
	v_pk_fma_f32 v[52:53], v[170:171], v[82:83], v[52:53] op_sel_hi:[0,1,1]
	s_waitcnt lgkmcnt(0)
	v_pk_fma_f32 v[82:83], v[56:57], v[86:87], v[52:53] op_sel_hi:[0,1,1]
	v_pk_fma_f32 v[52:53], v[168:169], v[54:55], v[90:91] op_sel_hi:[0,1,1]
	v_pk_fma_f32 v[52:53], v[168:169], v[58:59], v[52:53] op_sel:[1,0,0]
	s_nop 0
	v_pk_fma_f32 v[52:53], v[170:171], v[84:85], v[52:53] op_sel_hi:[0,1,1]
	v_pk_fma_f32 v[86:87], v[56:57], v[88:89], v[52:53] op_sel_hi:[0,1,1]
	ds_read_b128 v[52:55], v98 offset:128
	ds_read_b128 v[56:59], v98 offset:144
	ds_read_b128 v[78:81], v98 offset:160
	s_waitcnt lgkmcnt(2)
	v_pk_fma_f32 v[52:53], v[172:173], v[52:53], v[82:83] op_sel_hi:[0,1,1]
	ds_read_b128 v[82:85], v98 offset:176
	v_pk_fma_f32 v[54:55], v[172:173], v[54:55], v[86:87] op_sel_hi:[0,1,1]
	s_waitcnt lgkmcnt(2)
	v_pk_fma_f32 v[52:53], v[172:173], v[56:57], v[52:53] op_sel:[1,0,0]
	v_pk_fma_f32 v[54:55], v[172:173], v[58:59], v[54:55] op_sel:[1,0,0]
	s_waitcnt lgkmcnt(1)
	v_pk_fma_f32 v[52:53], v[174:175], v[78:79], v[52:53] op_sel_hi:[0,1,1]
	v_mov_b32_e32 v56, v175
	v_pk_fma_f32 v[54:55], v[174:175], v[80:81], v[54:55] op_sel_hi:[0,1,1]
	s_waitcnt lgkmcnt(0)
	v_pk_fma_f32 v[52:53], v[56:57], v[82:83], v[52:53] op_sel_hi:[0,1,1]
	v_pk_fma_f32 v[58:59], v[56:57], v[84:85], v[54:55] op_sel_hi:[0,1,1]
	ds_read_b128 v[54:57], v98 offset:192
	ds_read_b128 v[64:67], v98 offset:208
	ds_read_b128 v[78:81], v98 offset:224
	ds_read_b128 v[82:85], v98 offset:240
	s_waitcnt lgkmcnt(3)
	v_pk_fma_f32 v[52:53], v[176:177], v[54:55], v[52:53] op_sel_hi:[0,1,1]
	s_waitcnt lgkmcnt(2)
	v_pk_fma_f32 v[52:53], v[176:177], v[64:65], v[52:53] op_sel:[1,0,0]
	v_mov_b32_e32 v64, v179
	s_waitcnt lgkmcnt(1)
	v_pk_fma_f32 v[52:53], v[178:179], v[78:79], v[52:53] op_sel_hi:[0,1,1]
	s_waitcnt lgkmcnt(0)
	v_pk_fma_f32 v[54:55], v[64:65], v[82:83], v[52:53] op_sel_hi:[0,1,1]
	v_pk_fma_f32 v[52:53], v[176:177], v[56:57], v[58:59] op_sel_hi:[0,1,1]
	v_pk_fma_f32 v[52:53], v[176:177], v[66:67], v[52:53] op_sel:[1,0,0]
	s_nop 0
	v_pk_fma_f32 v[52:53], v[178:179], v[80:81], v[52:53] op_sel_hi:[0,1,1]
	v_pk_fma_f32 v[52:53], v[64:65], v[84:85], v[52:53] op_sel_hi:[0,1,1]
	s_add_u32 s100, s78, 0x1e8c0000
	s_addc_u32 s101, s79, 0
	global_load_dwordx4 v[164:167], v113, s[100:101]
	s_add_u32 s100, s100, 0x10000
	s_addc_u32 s101, s101, 0
	global_load_dwordx4 v[168:171], v113, s[100:101]
	s_add_u32 s100, s100, 0x10000
	s_addc_u32 s101, s101, 0
	global_load_dwordx4 v[172:175], v113, s[100:101]
	s_add_u32 s100, s100, 0x10000
	s_addc_u32 s101, s101, 0
	global_load_dwordx4 v[176:179], v113, s[100:101]
	v_mov_b32_e32 v58, 0
	s_mov_b32 s0, 0
	s_mov_b64 s[14:15], 0
	v_mov_b32_e32 v59, v58
	v_mov_b32_e32 v56, v58
	v_mov_b32_e32 v57, v58
; __device__ void ph_filter_gen(const Params& P, int j, const float* __restrict__ a3, float* __restrict__ kf, float* sl) {
;     ...
;         for (int i = 0; i < 8; ++i) { const int t = tid + NT * i; const float4* ar = (const float4*)(a3 + (size_t)t * 64);
;             float a0 = 0.f, a1 = 0.f, a2 = 0.f, a3v = 0.f;
; #pragma unroll 4
;             for (int jq = 0; jq < 16; ++jq) { const float4 av = ar[jq]; const float ae[4] = {av.x, av.y, av.z, av.w};
; #pragma unroll
;                 for (int e = 0; e < 4; ++e) { const float4 wv = *(const float4*)(sw + (jq * 4 + e) * 4); a0 += ae[e] * wv.x; a1 += ae[e] * wv.y; a2 += ae[e] * wv.z; a3v += ae[e] * wv.w; } }
.LBB0_231:
	v_lshlrev_b32_e32 v113, 2, v68
	v_add_u32_e32 v113, 0xc000, v113
	s_waitcnt vmcnt(12)
	v_mov_b32_e32 v102, 0
	ds_read_b128 v[86:89], v102
	ds_read_b128 v[90:93], v102 offset:16
	ds_read_b128 v[94:97], v102 offset:32
	ds_read_b128 v[98:101], v102 offset:48
	s_waitcnt lgkmcnt(3)
	v_pk_fma_f32 v[58:59], v[116:117], v[86:87], v[58:59] op_sel_hi:[0,1,1]
	v_pk_fma_f32 v[56:57], v[116:117], v[88:89], v[56:57] op_sel_hi:[0,1,1]
	s_waitcnt lgkmcnt(2)
	v_pk_fma_f32 v[58:59], v[116:117], v[90:91], v[58:59] op_sel:[1,0,0]
	v_pk_fma_f32 v[56:57], v[116:117], v[92:93], v[56:57] op_sel:[1,0,0]
	s_waitcnt lgkmcnt(1)
	v_pk_fma_f32 v[58:59], v[118:119], v[94:95], v[58:59] op_sel_hi:[0,1,1]
	v_mov_b32_e32 v86, v119
	v_pk_fma_f32 v[56:57], v[118:119], v[96:97], v[56:57] op_sel_hi:[0,1,1]
	s_waitcnt lgkmcnt(0)
	v_pk_fma_f32 v[90:91], v[86:87], v[98:99], v[58:59] op_sel_hi:[0,1,1]
	v_pk_fma_f32 v[94:95], v[86:87], v[100:101], v[56:57] op_sel_hi:[0,1,1]
	ds_read_b128 v[56:59], v102 offset:64
	ds_read_b128 v[60:63], v102 offset:80
	ds_read_b128 v[86:89], v102 offset:96
	s_waitcnt lgkmcnt(2)
	v_pk_fma_f32 v[56:57], v[120:121], v[56:57], v[90:91] op_sel_hi:[0,1,1]
	ds_read_b128 v[90:93], v102 offset:112
	s_waitcnt lgkmcnt(2)
	v_pk_fma_f32 v[56:57], v[120:121], v[60:61], v[56:57] op_sel:[1,0,0]
	v_mov_b32_e32 v60, v123
	s_waitcnt lgkmcnt(1)
	v_pk_fma_f32 v[56:57], v[122:123], v[86:87], v[56:57] op_sel_hi:[0,1,1]
	s_waitcnt lgkmcnt(0)
	v_pk_fma_f32 v[86:87], v[60:61], v[90:91], v[56:57] op_sel_hi:[0,1,1]
	v_pk_fma_f32 v[56:57], v[120:121], v[58:59], v[94:95] op_sel_hi:[0,1,1]
	v_pk_fma_f32 v[56:57], v[120:121], v[62:63], v[56:57] op_sel:[1,0,0]
	s_nop 0
	v_pk_fma_f32 v[56:57], v[122:123], v[88:89], v[56:57] op_sel_hi:[0,1,1]
	v_pk_fma_f32 v[90:91], v[60:61], v[92:93], v[56:57] op_sel_hi:[0,1,1]
	ds_read_b128 v[56:59], v102 offset:128
	ds_read_b128 v[60:63], v102 offset:144
	ds_read_b128 v[82:85], v102 offset:160
	s_waitcnt lgkmcnt(2)
	v_pk_fma_f32 v[56:57], v[124:125], v[56:57], v[86:87] op_sel_hi:[0,1,1]
	ds_read_b128 v[86:89], v102 offset:176
	v_pk_fma_f32 v[58:59], v[124:125], v[58:59], v[90:91] op_sel_hi:[0,1,1]
	s_waitcnt lgkmcnt(2)
	v_pk_fma_f32 v[56:57], v[124:125], v[60:61], v[56:57] op_sel:[1,0,0]
	v_pk_fma_f32 v[58:59], v[124:125], v[62:63], v[58:59] op_sel:[1,0,0]
	s_waitcnt lgkmcnt(1)
	v_pk_fma_f32 v[56:57], v[126:127], v[82:83], v[56:57] op_sel_hi:[0,1,1]
	v_mov_b32_e32 v60, v127
	v_pk_fma_f32 v[58:59], v[126:127], v[84:85], v[58:59] op_sel_hi:[0,1,1]
	s_waitcnt lgkmcnt(0)
	v_pk_fma_f32 v[56:57], v[60:61], v[86:87], v[56:57] op_sel_hi:[0,1,1]
	v_pk_fma_f32 v[62:63], v[60:61], v[88:89], v[58:59] op_sel_hi:[0,1,1]
	ds_read_b128 v[58:61], v102 offset:192
	ds_read_b128 v[78:81], v102 offset:208
	ds_read_b128 v[82:85], v102 offset:224
	ds_read_b128 v[86:89], v102 offset:240
	s_waitcnt lgkmcnt(3)
	v_pk_fma_f32 v[56:57], v[128:129], v[58:59], v[56:57] op_sel_hi:[0,1,1]
	s_waitcnt lgkmcnt(2)
	v_pk_fma_f32 v[56:57], v[128:129], v[78:79], v[56:57] op_sel:[1,0,0]
	v_mov_b32_e32 v78, v131
	s_waitcnt lgkmcnt(1)
	v_pk_fma_f32 v[56:57], v[130:131], v[82:83], v[56:57] op_sel_hi:[0,1,1]
	s_waitcnt lgkmcnt(0)
	v_pk_fma_f32 v[58:59], v[78:79], v[86:87], v[56:57] op_sel_hi:[0,1,1]
	v_pk_fma_f32 v[56:57], v[128:129], v[60:61], v[62:63] op_sel_hi:[0,1,1]
	v_pk_fma_f32 v[56:57], v[128:129], v[80:81], v[56:57] op_sel:[1,0,0]
	s_nop 0
	v_pk_fma_f32 v[56:57], v[130:131], v[84:85], v[56:57] op_sel_hi:[0,1,1]
	v_pk_fma_f32 v[56:57], v[78:79], v[88:89], v[56:57] op_sel_hi:[0,1,1]
	s_add_u32 s100, s78, 0x1e800000
	s_addc_u32 s101, s79, 0
	global_load_dwordx4 v[116:119], v113, s[100:101]
	s_add_u32 s100, s100, 0x10000
	s_addc_u32 s101, s101, 0
	global_load_dwordx4 v[120:123], v113, s[100:101]
	s_add_u32 s100, s100, 0x10000
	s_addc_u32 s101, s101, 0
	global_load_dwordx4 v[124:127], v113, s[100:101]
	s_add_u32 s100, s100, 0x10000
	s_addc_u32 s101, s101, 0
	global_load_dwordx4 v[128:131], v113, s[100:101]
	s_waitcnt vmcnt(12)
	v_mov_b32_e32 v102, 0x100
	ds_read_b128 v[86:89], v102
	ds_read_b128 v[90:93], v102 offset:16
	ds_read_b128 v[94:97], v102 offset:32
	ds_read_b128 v[98:101], v102 offset:48
	s_waitcnt lgkmcnt(3)
	v_pk_fma_f32 v[58:59], v[132:133], v[86:87], v[58:59] op_sel_hi:[0,1,1]
	v_pk_fma_f32 v[56:57], v[132:133], v[88:89], v[56:57] op_sel_hi:[0,1,1]
	s_waitcnt lgkmcnt(2)
	v_pk_fma_f32 v[58:59], v[132:133], v[90:91], v[58:59] op_sel:[1,0,0]
	v_pk_fma_f32 v[56:57], v[132:133], v[92:93], v[56:57] op_sel:[1,0,0]
	s_waitcnt lgkmcnt(1)
	v_pk_fma_f32 v[58:59], v[134:135], v[94:95], v[58:59] op_sel_hi:[0,1,1]
	v_mov_b32_e32 v86, v135
	v_pk_fma_f32 v[56:57], v[134:135], v[96:97], v[56:57] op_sel_hi:[0,1,1]
	s_waitcnt lgkmcnt(0)
	v_pk_fma_f32 v[90:91], v[86:87], v[98:99], v[58:59] op_sel_hi:[0,1,1]
	v_pk_fma_f32 v[94:95], v[86:87], v[100:101], v[56:57] op_sel_hi:[0,1,1]
	ds_read_b128 v[56:59], v102 offset:64
	ds_read_b128 v[60:63], v102 offset:80
	ds_read_b128 v[86:89], v102 offset:96
	s_waitcnt lgkmcnt(2)
	v_pk_fma_f32 v[56:57], v[136:137], v[56:57], v[90:91] op_sel_hi:[0,1,1]
	ds_read_b128 v[90:93], v102 offset:112
	s_waitcnt lgkmcnt(2)
	v_pk_fma_f32 v[56:57], v[136:137], v[60:61], v[56:57] op_sel:[1,0,0]
	v_mov_b32_e32 v60, v139
	s_waitcnt lgkmcnt(1)
	v_pk_fma_f32 v[56:57], v[138:139], v[86:87], v[56:57] op_sel_hi:[0,1,1]
	s_waitcnt lgkmcnt(0)
	v_pk_fma_f32 v[86:87], v[60:61], v[90:91], v[56:57] op_sel_hi:[0,1,1]
	v_pk_fma_f32 v[56:57], v[136:137], v[58:59], v[94:95] op_sel_hi:[0,1,1]
	v_pk_fma_f32 v[56:57], v[136:137], v[62:63], v[56:57] op_sel:[1,0,0]
	s_nop 0
	v_pk_fma_f32 v[56:57], v[138:139], v[88:89], v[56:57] op_sel_hi:[0,1,1]
	v_pk_fma_f32 v[90:91], v[60:61], v[92:93], v[56:57] op_sel_hi:[0,1,1]
	ds_read_b128 v[56:59], v102 offset:128
	ds_read_b128 v[60:63], v102 offset:144
	ds_read_b128 v[82:85], v102 offset:160
	s_waitcnt lgkmcnt(2)
; __device__ void ph_filter_gen(const Params& P, int j, const float* __restrict__ a3, float* __restrict__ kf, float* sl) {
;     ...
;         for (int i = 0; i < 8; ++i) { const int t = tid + NT * i; const float4* ar = (const float4*)(a3 + (size_t)t * 64);
;             float a0 = 0.f, a1 = 0.f, a2 = 0.f, a3v = 0.f;
; #pragma unroll 4
;             for (int jq = 0; jq < 16; ++jq) { const float4 av = ar[jq]; const float ae[4] = {av.x, av.y, av.z, av.w};
; #pragma unroll
;                 for (int e = 0; e < 4; ++e) { const float4 wv = *(const float4*)(sw + (jq * 4 + e) * 4); a0 += ae[e] * wv.x; a1 += ae[e] * wv.y; a2 += ae[e] * wv.z; a3v += ae[e] * wv.w; } }
;             const float dec = expf(-((float)t / (float)(SEQ - 1)) * delta);
;             hv[i][0] = a0 * dec; hv[i][1] = a1 * dec; hv[i][2] = a2 * dec; hv[i][3] = a3v * dec;
	v_pk_fma_f32 v[56:57], v[140:141], v[56:57], v[86:87] op_sel_hi:[0,1,1]
	ds_read_b128 v[86:89], v102 offset:176
	v_pk_fma_f32 v[58:59], v[140:141], v[58:59], v[90:91] op_sel_hi:[0,1,1]
	s_waitcnt lgkmcnt(2)
	v_pk_fma_f32 v[56:57], v[140:141], v[60:61], v[56:57] op_sel:[1,0,0]
	v_pk_fma_f32 v[58:59], v[140:141], v[62:63], v[58:59] op_sel:[1,0,0]
	s_waitcnt lgkmcnt(1)
	v_pk_fma_f32 v[56:57], v[142:143], v[82:83], v[56:57] op_sel_hi:[0,1,1]
	v_mov_b32_e32 v60, v143
	v_pk_fma_f32 v[58:59], v[142:143], v[84:85], v[58:59] op_sel_hi:[0,1,1]
	s_waitcnt lgkmcnt(0)
	v_pk_fma_f32 v[56:57], v[60:61], v[86:87], v[56:57] op_sel_hi:[0,1,1]
	v_pk_fma_f32 v[62:63], v[60:61], v[88:89], v[58:59] op_sel_hi:[0,1,1]
	ds_read_b128 v[58:61], v102 offset:192
	ds_read_b128 v[78:81], v102 offset:208
	ds_read_b128 v[82:85], v102 offset:224
	ds_read_b128 v[86:89], v102 offset:240
	s_waitcnt lgkmcnt(3)
	v_pk_fma_f32 v[56:57], v[144:145], v[58:59], v[56:57] op_sel_hi:[0,1,1]
	s_waitcnt lgkmcnt(2)
	v_pk_fma_f32 v[56:57], v[144:145], v[78:79], v[56:57] op_sel:[1,0,0]
	v_mov_b32_e32 v78, v147
	s_waitcnt lgkmcnt(1)
	v_pk_fma_f32 v[56:57], v[146:147], v[82:83], v[56:57] op_sel_hi:[0,1,1]
	s_waitcnt lgkmcnt(0)
	v_pk_fma_f32 v[58:59], v[78:79], v[86:87], v[56:57] op_sel_hi:[0,1,1]
	v_pk_fma_f32 v[56:57], v[144:145], v[60:61], v[62:63] op_sel_hi:[0,1,1]
	v_pk_fma_f32 v[56:57], v[144:145], v[80:81], v[56:57] op_sel:[1,0,0]
	s_nop 0
	v_pk_fma_f32 v[56:57], v[146:147], v[84:85], v[56:57] op_sel_hi:[0,1,1]
	v_pk_fma_f32 v[56:57], v[78:79], v[88:89], v[56:57] op_sel_hi:[0,1,1]
	s_add_u32 s100, s78, 0x1e840000
	s_addc_u32 s101, s79, 0
	global_load_dwordx4 v[132:135], v113, s[100:101]
	s_add_u32 s100, s100, 0x10000
	s_addc_u32 s101, s101, 0
	global_load_dwordx4 v[136:139], v113, s[100:101]
	s_add_u32 s100, s100, 0x10000
	s_addc_u32 s101, s101, 0
	global_load_dwordx4 v[140:143], v113, s[100:101]
	s_add_u32 s100, s100, 0x10000
	s_addc_u32 s101, s101, 0
	global_load_dwordx4 v[144:147], v113, s[100:101]
	s_waitcnt vmcnt(12)
	v_mov_b32_e32 v102, 0x200
	ds_read_b128 v[86:89], v102
	ds_read_b128 v[90:93], v102 offset:16
	ds_read_b128 v[94:97], v102 offset:32
	ds_read_b128 v[98:101], v102 offset:48
	s_waitcnt lgkmcnt(3)
	v_pk_fma_f32 v[58:59], v[148:149], v[86:87], v[58:59] op_sel_hi:[0,1,1]
	v_pk_fma_f32 v[56:57], v[148:149], v[88:89], v[56:57] op_sel_hi:[0,1,1]
	s_waitcnt lgkmcnt(2)
	v_pk_fma_f32 v[58:59], v[148:149], v[90:91], v[58:59] op_sel:[1,0,0]
	v_pk_fma_f32 v[56:57], v[148:149], v[92:93], v[56:57] op_sel:[1,0,0]
	s_waitcnt lgkmcnt(1)
	v_pk_fma_f32 v[58:59], v[150:151], v[94:95], v[58:59] op_sel_hi:[0,1,1]
	v_mov_b32_e32 v86, v151
	v_pk_fma_f32 v[56:57], v[150:151], v[96:97], v[56:57] op_sel_hi:[0,1,1]
	s_waitcnt lgkmcnt(0)
	v_pk_fma_f32 v[90:91], v[86:87], v[98:99], v[58:59] op_sel_hi:[0,1,1]
	v_pk_fma_f32 v[94:95], v[86:87], v[100:101], v[56:57] op_sel_hi:[0,1,1]
	ds_read_b128 v[56:59], v102 offset:64
	ds_read_b128 v[60:63], v102 offset:80
	ds_read_b128 v[86:89], v102 offset:96
	s_waitcnt lgkmcnt(2)
	v_pk_fma_f32 v[56:57], v[152:153], v[56:57], v[90:91] op_sel_hi:[0,1,1]
	ds_read_b128 v[90:93], v102 offset:112
	s_waitcnt lgkmcnt(2)
	v_pk_fma_f32 v[56:57], v[152:153], v[60:61], v[56:57] op_sel:[1,0,0]
	v_mov_b32_e32 v60, v155
	s_waitcnt lgkmcnt(1)
	v_pk_fma_f32 v[56:57], v[154:155], v[86:87], v[56:57] op_sel_hi:[0,1,1]
	s_waitcnt lgkmcnt(0)
	v_pk_fma_f32 v[86:87], v[60:61], v[90:91], v[56:57] op_sel_hi:[0,1,1]
	v_pk_fma_f32 v[56:57], v[152:153], v[58:59], v[94:95] op_sel_hi:[0,1,1]
	v_pk_fma_f32 v[56:57], v[152:153], v[62:63], v[56:57] op_sel:[1,0,0]
	s_nop 0
	v_pk_fma_f32 v[56:57], v[154:155], v[88:89], v[56:57] op_sel_hi:[0,1,1]
	v_pk_fma_f32 v[90:91], v[60:61], v[92:93], v[56:57] op_sel_hi:[0,1,1]
	ds_read_b128 v[56:59], v102 offset:128
	ds_read_b128 v[60:63], v102 offset:144
	ds_read_b128 v[82:85], v102 offset:160
	s_waitcnt lgkmcnt(2)
	v_pk_fma_f32 v[56:57], v[156:157], v[56:57], v[86:87] op_sel_hi:[0,1,1]
	ds_read_b128 v[86:89], v102 offset:176
	v_pk_fma_f32 v[58:59], v[156:157], v[58:59], v[90:91] op_sel_hi:[0,1,1]
	s_waitcnt lgkmcnt(2)
	v_pk_fma_f32 v[56:57], v[156:157], v[60:61], v[56:57] op_sel:[1,0,0]
	v_pk_fma_f32 v[58:59], v[156:157], v[62:63], v[58:59] op_sel:[1,0,0]
	s_waitcnt lgkmcnt(1)
	v_pk_fma_f32 v[56:57], v[158:159], v[82:83], v[56:57] op_sel_hi:[0,1,1]
	v_mov_b32_e32 v60, v159
	v_pk_fma_f32 v[58:59], v[158:159], v[84:85], v[58:59] op_sel_hi:[0,1,1]
	s_waitcnt lgkmcnt(0)
	v_pk_fma_f32 v[56:57], v[60:61], v[86:87], v[56:57] op_sel_hi:[0,1,1]
	v_pk_fma_f32 v[62:63], v[60:61], v[88:89], v[58:59] op_sel_hi:[0,1,1]
	ds_read_b128 v[58:61], v102 offset:192
	ds_read_b128 v[78:81], v102 offset:208
	ds_read_b128 v[82:85], v102 offset:224
	ds_read_b128 v[86:89], v102 offset:240
	s_waitcnt lgkmcnt(3)
	v_pk_fma_f32 v[56:57], v[160:161], v[58:59], v[56:57] op_sel_hi:[0,1,1]
	s_waitcnt lgkmcnt(2)
	v_pk_fma_f32 v[56:57], v[160:161], v[78:79], v[56:57] op_sel:[1,0,0]
	v_mov_b32_e32 v78, v163
	s_waitcnt lgkmcnt(1)
	v_pk_fma_f32 v[56:57], v[162:163], v[82:83], v[56:57] op_sel_hi:[0,1,1]
	s_waitcnt lgkmcnt(0)
	v_pk_fma_f32 v[58:59], v[78:79], v[86:87], v[56:57] op_sel_hi:[0,1,1]
	v_pk_fma_f32 v[56:57], v[160:161], v[60:61], v[62:63] op_sel_hi:[0,1,1]
	v_pk_fma_f32 v[56:57], v[160:161], v[80:81], v[56:57] op_sel:[1,0,0]
	s_nop 0
	v_pk_fma_f32 v[56:57], v[162:163], v[84:85], v[56:57] op_sel_hi:[0,1,1]
	v_pk_fma_f32 v[56:57], v[78:79], v[88:89], v[56:57] op_sel_hi:[0,1,1]
	s_add_u32 s100, s78, 0x1e880000
	s_addc_u32 s101, s79, 0
	global_load_dwordx4 v[148:151], v113, s[100:101]
	s_add_u32 s100, s100, 0x10000
	s_addc_u32 s101, s101, 0
	global_load_dwordx4 v[152:155], v113, s[100:101]
	s_add_u32 s100, s100, 0x10000
	s_addc_u32 s101, s101, 0
	global_load_dwordx4 v[156:159], v113, s[100:101]
	s_add_u32 s100, s100, 0x10000
	s_addc_u32 s101, s101, 0
	global_load_dwordx4 v[160:163], v113, s[100:101]
	s_waitcnt vmcnt(12)
; __device__ void ph_filter_gen(const Params& P, int j, const float* __restrict__ a3, float* __restrict__ kf, float* sl) {
;     ...
;         for (int i = 0; i < 8; ++i) { const int t = tid + NT * i; const float4* ar = (const float4*)(a3 + (size_t)t * 64);
;             float a0 = 0.f, a1 = 0.f, a2 = 0.f, a3v = 0.f;
; #pragma unroll 4
;             for (int jq = 0; jq < 16; ++jq) { const float4 av = ar[jq]; const float ae[4] = {av.x, av.y, av.z, av.w};
; #pragma unroll
;                 for (int e = 0; e < 4; ++e) { const float4 wv = *(const float4*)(sw + (jq * 4 + e) * 4); a0 += ae[e] * wv.x; a1 += ae[e] * wv.y; a2 += ae[e] * wv.z; a3v += ae[e] * wv.w; } }
;             const float dec = expf(-((float)t / (float)(SEQ - 1)) * delta);
;             hv[i][0] = a0 * dec; hv[i][1] = a1 * dec; hv[i][2] = a2 * dec; hv[i][3] = a3v * dec;
	v_mov_b32_e32 v102, 0x300
	ds_read_b128 v[86:89], v102
	ds_read_b128 v[90:93], v102 offset:16
	ds_read_b128 v[94:97], v102 offset:32
	ds_read_b128 v[98:101], v102 offset:48
	s_waitcnt lgkmcnt(3)
	v_pk_fma_f32 v[58:59], v[164:165], v[86:87], v[58:59] op_sel_hi:[0,1,1]
	v_pk_fma_f32 v[56:57], v[164:165], v[88:89], v[56:57] op_sel_hi:[0,1,1]
	s_waitcnt lgkmcnt(2)
	v_pk_fma_f32 v[58:59], v[164:165], v[90:91], v[58:59] op_sel:[1,0,0]
	v_pk_fma_f32 v[56:57], v[164:165], v[92:93], v[56:57] op_sel:[1,0,0]
	s_waitcnt lgkmcnt(1)
	v_pk_fma_f32 v[58:59], v[166:167], v[94:95], v[58:59] op_sel_hi:[0,1,1]
	v_mov_b32_e32 v86, v167
	v_pk_fma_f32 v[56:57], v[166:167], v[96:97], v[56:57] op_sel_hi:[0,1,1]
	s_waitcnt lgkmcnt(0)
	v_pk_fma_f32 v[90:91], v[86:87], v[98:99], v[58:59] op_sel_hi:[0,1,1]
	v_pk_fma_f32 v[94:95], v[86:87], v[100:101], v[56:57] op_sel_hi:[0,1,1]
	ds_read_b128 v[56:59], v102 offset:64
	ds_read_b128 v[60:63], v102 offset:80
	ds_read_b128 v[86:89], v102 offset:96
	s_waitcnt lgkmcnt(2)
	v_pk_fma_f32 v[56:57], v[168:169], v[56:57], v[90:91] op_sel_hi:[0,1,1]
	ds_read_b128 v[90:93], v102 offset:112
	s_waitcnt lgkmcnt(2)
	v_pk_fma_f32 v[56:57], v[168:169], v[60:61], v[56:57] op_sel:[1,0,0]
	v_mov_b32_e32 v60, v171
	s_waitcnt lgkmcnt(1)
	v_pk_fma_f32 v[56:57], v[170:171], v[86:87], v[56:57] op_sel_hi:[0,1,1]
	s_waitcnt lgkmcnt(0)
	v_pk_fma_f32 v[86:87], v[60:61], v[90:91], v[56:57] op_sel_hi:[0,1,1]
	v_pk_fma_f32 v[56:57], v[168:169], v[58:59], v[94:95] op_sel_hi:[0,1,1]
	v_pk_fma_f32 v[56:57], v[168:169], v[62:63], v[56:57] op_sel:[1,0,0]
	s_nop 0
	v_pk_fma_f32 v[56:57], v[170:171], v[88:89], v[56:57] op_sel_hi:[0,1,1]
	v_pk_fma_f32 v[90:91], v[60:61], v[92:93], v[56:57] op_sel_hi:[0,1,1]
	ds_read_b128 v[56:59], v102 offset:128
	ds_read_b128 v[60:63], v102 offset:144
	ds_read_b128 v[82:85], v102 offset:160
	s_waitcnt lgkmcnt(2)
	v_pk_fma_f32 v[56:57], v[172:173], v[56:57], v[86:87] op_sel_hi:[0,1,1]
	ds_read_b128 v[86:89], v102 offset:176
	v_pk_fma_f32 v[58:59], v[172:173], v[58:59], v[90:91] op_sel_hi:[0,1,1]
	s_waitcnt lgkmcnt(2)
	v_pk_fma_f32 v[56:57], v[172:173], v[60:61], v[56:57] op_sel:[1,0,0]
	v_pk_fma_f32 v[58:59], v[172:173], v[62:63], v[58:59] op_sel:[1,0,0]
	s_waitcnt lgkmcnt(1)
	v_pk_fma_f32 v[56:57], v[174:175], v[82:83], v[56:57] op_sel_hi:[0,1,1]
	v_mov_b32_e32 v60, v175
	v_pk_fma_f32 v[58:59], v[174:175], v[84:85], v[58:59] op_sel_hi:[0,1,1]
	s_waitcnt lgkmcnt(0)
	v_pk_fma_f32 v[56:57], v[60:61], v[86:87], v[56:57] op_sel_hi:[0,1,1]
	v_pk_fma_f32 v[62:63], v[60:61], v[88:89], v[58:59] op_sel_hi:[0,1,1]
	ds_read_b128 v[58:61], v102 offset:192
	ds_read_b128 v[78:81], v102 offset:208
	ds_read_b128 v[82:85], v102 offset:224
	ds_read_b128 v[86:89], v102 offset:240
	s_waitcnt lgkmcnt(3)
	v_pk_fma_f32 v[56:57], v[176:177], v[58:59], v[56:57] op_sel_hi:[0,1,1]
	s_waitcnt lgkmcnt(2)
	v_pk_fma_f32 v[56:57], v[176:177], v[78:79], v[56:57] op_sel:[1,0,0]
	v_mov_b32_e32 v78, v179
	s_waitcnt lgkmcnt(1)
	v_pk_fma_f32 v[56:57], v[178:179], v[82:83], v[56:57] op_sel_hi:[0,1,1]
	s_waitcnt lgkmcnt(0)
	v_pk_fma_f32 v[58:59], v[78:79], v[86:87], v[56:57] op_sel_hi:[0,1,1]
	v_pk_fma_f32 v[56:57], v[176:177], v[60:61], v[62:63] op_sel_hi:[0,1,1]
	v_pk_fma_f32 v[56:57], v[176:177], v[80:81], v[56:57] op_sel:[1,0,0]
	s_nop 0
	v_pk_fma_f32 v[56:57], v[178:179], v[84:85], v[56:57] op_sel_hi:[0,1,1]
	v_pk_fma_f32 v[56:57], v[78:79], v[88:89], v[56:57] op_sel_hi:[0,1,1]
	s_add_u32 s100, s78, 0x1e8c0000
	s_addc_u32 s101, s79, 0
	global_load_dwordx4 v[164:167], v113, s[100:101]
	s_add_u32 s100, s100, 0x10000
	s_addc_u32 s101, s101, 0
	global_load_dwordx4 v[168:171], v113, s[100:101]
	s_add_u32 s100, s100, 0x10000
	s_addc_u32 s101, s101, 0
	global_load_dwordx4 v[172:175], v113, s[100:101]
	s_add_u32 s100, s100, 0x10000
	s_addc_u32 s101, s101, 0
	global_load_dwordx4 v[176:179], v113, s[100:101]
	v_mov_b32_e32 v62, 0
	s_mov_b32 s0, 0
	s_mov_b64 s[14:15], 0
	v_mov_b32_e32 v63, v62
	v_mov_b32_e32 v60, v62
	v_mov_b32_e32 v61, v62
.LBB0_233:
	v_lshlrev_b32_e32 v113, 2, v68
	v_add_u32_e32 v113, 0xe000, v113
	s_waitcnt vmcnt(12)
	v_mov_b32_e32 v106, 0
	ds_read_b128 v[90:93], v106
	ds_read_b128 v[94:97], v106 offset:16
	ds_read_b128 v[98:101], v106 offset:32
	ds_read_b128 v[102:105], v106 offset:48
	s_waitcnt lgkmcnt(3)
	v_pk_fma_f32 v[62:63], v[116:117], v[90:91], v[62:63] op_sel_hi:[0,1,1]
	v_pk_fma_f32 v[60:61], v[116:117], v[92:93], v[60:61] op_sel_hi:[0,1,1]
	s_waitcnt lgkmcnt(2)
	v_pk_fma_f32 v[62:63], v[116:117], v[94:95], v[62:63] op_sel:[1,0,0]
	v_pk_fma_f32 v[60:61], v[116:117], v[96:97], v[60:61] op_sel:[1,0,0]
	s_waitcnt lgkmcnt(1)
	v_pk_fma_f32 v[62:63], v[118:119], v[98:99], v[62:63] op_sel_hi:[0,1,1]
	v_mov_b32_e32 v90, v119
	v_pk_fma_f32 v[60:61], v[118:119], v[100:101], v[60:61] op_sel_hi:[0,1,1]
	s_waitcnt lgkmcnt(0)
	v_pk_fma_f32 v[94:95], v[90:91], v[102:103], v[62:63] op_sel_hi:[0,1,1]
	v_pk_fma_f32 v[98:99], v[90:91], v[104:105], v[60:61] op_sel_hi:[0,1,1]
	ds_read_b128 v[60:63], v106 offset:64
	ds_read_b128 v[64:67], v106 offset:80
	ds_read_b128 v[90:93], v106 offset:96
	s_waitcnt lgkmcnt(2)
	v_pk_fma_f32 v[60:61], v[120:121], v[60:61], v[94:95] op_sel_hi:[0,1,1]
	ds_read_b128 v[94:97], v106 offset:112
	s_waitcnt lgkmcnt(2)
	v_pk_fma_f32 v[60:61], v[120:121], v[64:65], v[60:61] op_sel:[1,0,0]
	v_mov_b32_e32 v64, v123
	s_waitcnt lgkmcnt(1)
	v_pk_fma_f32 v[60:61], v[122:123], v[90:91], v[60:61] op_sel_hi:[0,1,1]
	s_waitcnt lgkmcnt(0)
; __device__ void ph_filter_gen(const Params& P, int j, const float* __restrict__ a3, float* __restrict__ kf, float* sl) {
;     ...
;         for (int i = 0; i < 8; ++i) { const int t = tid + NT * i; const float4* ar = (const float4*)(a3 + (size_t)t * 64);
;             float a0 = 0.f, a1 = 0.f, a2 = 0.f, a3v = 0.f;
; #pragma unroll 4
;             for (int jq = 0; jq < 16; ++jq) { const float4 av = ar[jq]; const float ae[4] = {av.x, av.y, av.z, av.w};
; #pragma unroll
;                 for (int e = 0; e < 4; ++e) { const float4 wv = *(const float4*)(sw + (jq * 4 + e) * 4); a0 += ae[e] * wv.x; a1 += ae[e] * wv.y; a2 += ae[e] * wv.z; a3v += ae[e] * wv.w; } }
;             const float dec = expf(-((float)t / (float)(SEQ - 1)) * delta);
;             hv[i][0] = a0 * dec; hv[i][1] = a1 * dec; hv[i][2] = a2 * dec; hv[i][3] = a3v * dec;
	v_pk_fma_f32 v[90:91], v[64:65], v[94:95], v[60:61] op_sel_hi:[0,1,1]
	v_pk_fma_f32 v[60:61], v[120:121], v[62:63], v[98:99] op_sel_hi:[0,1,1]
	v_pk_fma_f32 v[60:61], v[120:121], v[66:67], v[60:61] op_sel:[1,0,0]
	s_nop 0
	v_pk_fma_f32 v[60:61], v[122:123], v[92:93], v[60:61] op_sel_hi:[0,1,1]
	v_pk_fma_f32 v[94:95], v[64:65], v[96:97], v[60:61] op_sel_hi:[0,1,1]
	ds_read_b128 v[60:63], v106 offset:128
	ds_read_b128 v[64:67], v106 offset:144
	ds_read_b128 v[86:89], v106 offset:160
	s_waitcnt lgkmcnt(2)
	v_pk_fma_f32 v[60:61], v[124:125], v[60:61], v[90:91] op_sel_hi:[0,1,1]
	ds_read_b128 v[90:93], v106 offset:176
	v_pk_fma_f32 v[62:63], v[124:125], v[62:63], v[94:95] op_sel_hi:[0,1,1]
	s_waitcnt lgkmcnt(2)
	v_pk_fma_f32 v[60:61], v[124:125], v[64:65], v[60:61] op_sel:[1,0,0]
	v_pk_fma_f32 v[62:63], v[124:125], v[66:67], v[62:63] op_sel:[1,0,0]
	s_waitcnt lgkmcnt(1)
	v_pk_fma_f32 v[60:61], v[126:127], v[86:87], v[60:61] op_sel_hi:[0,1,1]
	v_mov_b32_e32 v64, v127
	v_pk_fma_f32 v[62:63], v[126:127], v[88:89], v[62:63] op_sel_hi:[0,1,1]
	s_waitcnt lgkmcnt(0)
	v_pk_fma_f32 v[60:61], v[64:65], v[90:91], v[60:61] op_sel_hi:[0,1,1]
	v_pk_fma_f32 v[66:67], v[64:65], v[92:93], v[62:63] op_sel_hi:[0,1,1]
	ds_read_b128 v[62:65], v106 offset:192
	ds_read_b128 v[82:85], v106 offset:208
	ds_read_b128 v[86:89], v106 offset:224
	ds_read_b128 v[90:93], v106 offset:240
	s_waitcnt lgkmcnt(3)
	v_pk_fma_f32 v[60:61], v[128:129], v[62:63], v[60:61] op_sel_hi:[0,1,1]
	s_waitcnt lgkmcnt(2)
	v_pk_fma_f32 v[60:61], v[128:129], v[82:83], v[60:61] op_sel:[1,0,0]
	v_mov_b32_e32 v82, v131
	s_waitcnt lgkmcnt(1)
	v_pk_fma_f32 v[60:61], v[130:131], v[86:87], v[60:61] op_sel_hi:[0,1,1]
	s_waitcnt lgkmcnt(0)
	v_pk_fma_f32 v[62:63], v[82:83], v[90:91], v[60:61] op_sel_hi:[0,1,1]
	v_pk_fma_f32 v[60:61], v[128:129], v[64:65], v[66:67] op_sel_hi:[0,1,1]
	v_pk_fma_f32 v[60:61], v[128:129], v[84:85], v[60:61] op_sel:[1,0,0]
	s_nop 0
	v_pk_fma_f32 v[60:61], v[130:131], v[88:89], v[60:61] op_sel_hi:[0,1,1]
	v_pk_fma_f32 v[60:61], v[82:83], v[92:93], v[60:61] op_sel_hi:[0,1,1]
	s_add_u32 s100, s78, 0x1e800000
	s_addc_u32 s101, s79, 0
	global_load_dwordx4 v[116:119], v113, s[100:101]
	s_add_u32 s100, s100, 0x10000
	s_addc_u32 s101, s101, 0
	global_load_dwordx4 v[120:123], v113, s[100:101]
	s_add_u32 s100, s100, 0x10000
	s_addc_u32 s101, s101, 0
	global_load_dwordx4 v[124:127], v113, s[100:101]
	s_add_u32 s100, s100, 0x10000
	s_addc_u32 s101, s101, 0
	global_load_dwordx4 v[128:131], v113, s[100:101]
	s_waitcnt vmcnt(12)
	v_mov_b32_e32 v106, 0x100
	ds_read_b128 v[90:93], v106
	ds_read_b128 v[94:97], v106 offset:16
	ds_read_b128 v[98:101], v106 offset:32
	ds_read_b128 v[102:105], v106 offset:48
	s_waitcnt lgkmcnt(3)
	v_pk_fma_f32 v[62:63], v[132:133], v[90:91], v[62:63] op_sel_hi:[0,1,1]
	v_pk_fma_f32 v[60:61], v[132:133], v[92:93], v[60:61] op_sel_hi:[0,1,1]
	s_waitcnt lgkmcnt(2)
	v_pk_fma_f32 v[62:63], v[132:133], v[94:95], v[62:63] op_sel:[1,0,0]
	v_pk_fma_f32 v[60:61], v[132:133], v[96:97], v[60:61] op_sel:[1,0,0]
	s_waitcnt lgkmcnt(1)
	v_pk_fma_f32 v[62:63], v[134:135], v[98:99], v[62:63] op_sel_hi:[0,1,1]
	v_mov_b32_e32 v90, v135
	v_pk_fma_f32 v[60:61], v[134:135], v[100:101], v[60:61] op_sel_hi:[0,1,1]
	s_waitcnt lgkmcnt(0)
	v_pk_fma_f32 v[94:95], v[90:91], v[102:103], v[62:63] op_sel_hi:[0,1,1]
	v_pk_fma_f32 v[98:99], v[90:91], v[104:105], v[60:61] op_sel_hi:[0,1,1]
	ds_read_b128 v[60:63], v106 offset:64
	ds_read_b128 v[64:67], v106 offset:80
	ds_read_b128 v[90:93], v106 offset:96
	s_waitcnt lgkmcnt(2)
	v_pk_fma_f32 v[60:61], v[136:137], v[60:61], v[94:95] op_sel_hi:[0,1,1]
	ds_read_b128 v[94:97], v106 offset:112
	s_waitcnt lgkmcnt(2)
	v_pk_fma_f32 v[60:61], v[136:137], v[64:65], v[60:61] op_sel:[1,0,0]
	v_mov_b32_e32 v64, v139
	s_waitcnt lgkmcnt(1)
	v_pk_fma_f32 v[60:61], v[138:139], v[90:91], v[60:61] op_sel_hi:[0,1,1]
	s_waitcnt lgkmcnt(0)
	v_pk_fma_f32 v[90:91], v[64:65], v[94:95], v[60:61] op_sel_hi:[0,1,1]
	v_pk_fma_f32 v[60:61], v[136:137], v[62:63], v[98:99] op_sel_hi:[0,1,1]
	v_pk_fma_f32 v[60:61], v[136:137], v[66:67], v[60:61] op_sel:[1,0,0]
	s_nop 0
	v_pk_fma_f32 v[60:61], v[138:139], v[92:93], v[60:61] op_sel_hi:[0,1,1]
	v_pk_fma_f32 v[94:95], v[64:65], v[96:97], v[60:61] op_sel_hi:[0,1,1]
	ds_read_b128 v[60:63], v106 offset:128
	ds_read_b128 v[64:67], v106 offset:144
	ds_read_b128 v[86:89], v106 offset:160
	s_waitcnt lgkmcnt(2)
	v_pk_fma_f32 v[60:61], v[140:141], v[60:61], v[90:91] op_sel_hi:[0,1,1]
	ds_read_b128 v[90:93], v106 offset:176
	v_pk_fma_f32 v[62:63], v[140:141], v[62:63], v[94:95] op_sel_hi:[0,1,1]
	s_waitcnt lgkmcnt(2)
	v_pk_fma_f32 v[60:61], v[140:141], v[64:65], v[60:61] op_sel:[1,0,0]
	v_pk_fma_f32 v[62:63], v[140:141], v[66:67], v[62:63] op_sel:[1,0,0]
	s_waitcnt lgkmcnt(1)
	v_pk_fma_f32 v[60:61], v[142:143], v[86:87], v[60:61] op_sel_hi:[0,1,1]
	v_mov_b32_e32 v64, v143
	v_pk_fma_f32 v[62:63], v[142:143], v[88:89], v[62:63] op_sel_hi:[0,1,1]
	s_waitcnt lgkmcnt(0)
	v_pk_fma_f32 v[60:61], v[64:65], v[90:91], v[60:61] op_sel_hi:[0,1,1]
	v_pk_fma_f32 v[66:67], v[64:65], v[92:93], v[62:63] op_sel_hi:[0,1,1]
	ds_read_b128 v[62:65], v106 offset:192
	ds_read_b128 v[82:85], v106 offset:208
	ds_read_b128 v[86:89], v106 offset:224
	ds_read_b128 v[90:93], v106 offset:240
	s_waitcnt lgkmcnt(3)
	v_pk_fma_f32 v[60:61], v[144:145], v[62:63], v[60:61] op_sel_hi:[0,1,1]
	s_waitcnt lgkmcnt(2)
	v_pk_fma_f32 v[60:61], v[144:145], v[82:83], v[60:61] op_sel:[1,0,0]
	v_mov_b32_e32 v82, v147
	s_waitcnt lgkmcnt(1)
	v_pk_fma_f32 v[60:61], v[146:147], v[86:87], v[60:61] op_sel_hi:[0,1,1]
	s_waitcnt lgkmcnt(0)
; __device__ void ph_filter_gen(const Params& P, int j, const float* __restrict__ a3, float* __restrict__ kf, float* sl) {
;     ...
;         for (int i = 0; i < 8; ++i) { const int t = tid + NT * i; const float4* ar = (const float4*)(a3 + (size_t)t * 64);
;             float a0 = 0.f, a1 = 0.f, a2 = 0.f, a3v = 0.f;
; #pragma unroll 4
;             for (int jq = 0; jq < 16; ++jq) { const float4 av = ar[jq]; const float ae[4] = {av.x, av.y, av.z, av.w};
; #pragma unroll
;                 for (int e = 0; e < 4; ++e) { const float4 wv = *(const float4*)(sw + (jq * 4 + e) * 4); a0 += ae[e] * wv.x; a1 += ae[e] * wv.y; a2 += ae[e] * wv.z; a3v += ae[e] * wv.w; } }
;             const float dec = expf(-((float)t / (float)(SEQ - 1)) * delta);
;             hv[i][0] = a0 * dec; hv[i][1] = a1 * dec; hv[i][2] = a2 * dec; hv[i][3] = a3v * dec;
	v_pk_fma_f32 v[62:63], v[82:83], v[90:91], v[60:61] op_sel_hi:[0,1,1]
	v_pk_fma_f32 v[60:61], v[144:145], v[64:65], v[66:67] op_sel_hi:[0,1,1]
	v_pk_fma_f32 v[60:61], v[144:145], v[84:85], v[60:61] op_sel:[1,0,0]
	s_nop 0
	v_pk_fma_f32 v[60:61], v[146:147], v[88:89], v[60:61] op_sel_hi:[0,1,1]
	v_pk_fma_f32 v[60:61], v[82:83], v[92:93], v[60:61] op_sel_hi:[0,1,1]
	s_add_u32 s100, s78, 0x1e840000
	s_addc_u32 s101, s79, 0
	global_load_dwordx4 v[132:135], v113, s[100:101]
	s_add_u32 s100, s100, 0x10000
	s_addc_u32 s101, s101, 0
	global_load_dwordx4 v[136:139], v113, s[100:101]
	s_add_u32 s100, s100, 0x10000
	s_addc_u32 s101, s101, 0
	global_load_dwordx4 v[140:143], v113, s[100:101]
	s_add_u32 s100, s100, 0x10000
	s_addc_u32 s101, s101, 0
	global_load_dwordx4 v[144:147], v113, s[100:101]
	s_waitcnt vmcnt(12)
	v_mov_b32_e32 v106, 0x200
	ds_read_b128 v[90:93], v106
	ds_read_b128 v[94:97], v106 offset:16
	ds_read_b128 v[98:101], v106 offset:32
	ds_read_b128 v[102:105], v106 offset:48
	s_waitcnt lgkmcnt(3)
	v_pk_fma_f32 v[62:63], v[148:149], v[90:91], v[62:63] op_sel_hi:[0,1,1]
	v_pk_fma_f32 v[60:61], v[148:149], v[92:93], v[60:61] op_sel_hi:[0,1,1]
	s_waitcnt lgkmcnt(2)
	v_pk_fma_f32 v[62:63], v[148:149], v[94:95], v[62:63] op_sel:[1,0,0]
	v_pk_fma_f32 v[60:61], v[148:149], v[96:97], v[60:61] op_sel:[1,0,0]
	s_waitcnt lgkmcnt(1)
	v_pk_fma_f32 v[62:63], v[150:151], v[98:99], v[62:63] op_sel_hi:[0,1,1]
	v_mov_b32_e32 v90, v151
	v_pk_fma_f32 v[60:61], v[150:151], v[100:101], v[60:61] op_sel_hi:[0,1,1]
	s_waitcnt lgkmcnt(0)
	v_pk_fma_f32 v[94:95], v[90:91], v[102:103], v[62:63] op_sel_hi:[0,1,1]
	v_pk_fma_f32 v[98:99], v[90:91], v[104:105], v[60:61] op_sel_hi:[0,1,1]
	ds_read_b128 v[60:63], v106 offset:64
	ds_read_b128 v[64:67], v106 offset:80
	ds_read_b128 v[90:93], v106 offset:96
	s_waitcnt lgkmcnt(2)
	v_pk_fma_f32 v[60:61], v[152:153], v[60:61], v[94:95] op_sel_hi:[0,1,1]
	ds_read_b128 v[94:97], v106 offset:112
	s_waitcnt lgkmcnt(2)
	v_pk_fma_f32 v[60:61], v[152:153], v[64:65], v[60:61] op_sel:[1,0,0]
	v_mov_b32_e32 v64, v155
	s_waitcnt lgkmcnt(1)
	v_pk_fma_f32 v[60:61], v[154:155], v[90:91], v[60:61] op_sel_hi:[0,1,1]
	s_waitcnt lgkmcnt(0)
	v_pk_fma_f32 v[90:91], v[64:65], v[94:95], v[60:61] op_sel_hi:[0,1,1]
	v_pk_fma_f32 v[60:61], v[152:153], v[62:63], v[98:99] op_sel_hi:[0,1,1]
	v_pk_fma_f32 v[60:61], v[152:153], v[66:67], v[60:61] op_sel:[1,0,0]
	s_nop 0
	v_pk_fma_f32 v[60:61], v[154:155], v[92:93], v[60:61] op_sel_hi:[0,1,1]
	v_pk_fma_f32 v[94:95], v[64:65], v[96:97], v[60:61] op_sel_hi:[0,1,1]
	ds_read_b128 v[60:63], v106 offset:128
	ds_read_b128 v[64:67], v106 offset:144
	ds_read_b128 v[86:89], v106 offset:160
	s_waitcnt lgkmcnt(2)
	v_pk_fma_f32 v[60:61], v[156:157], v[60:61], v[90:91] op_sel_hi:[0,1,1]
	ds_read_b128 v[90:93], v106 offset:176
	v_pk_fma_f32 v[62:63], v[156:157], v[62:63], v[94:95] op_sel_hi:[0,1,1]
	s_waitcnt lgkmcnt(2)
	v_pk_fma_f32 v[60:61], v[156:157], v[64:65], v[60:61] op_sel:[1,0,0]
	v_pk_fma_f32 v[62:63], v[156:157], v[66:67], v[62:63] op_sel:[1,0,0]
	s_waitcnt lgkmcnt(1)
	v_pk_fma_f32 v[60:61], v[158:159], v[86:87], v[60:61] op_sel_hi:[0,1,1]
	v_mov_b32_e32 v64, v159
	v_pk_fma_f32 v[62:63], v[158:159], v[88:89], v[62:63] op_sel_hi:[0,1,1]
	s_waitcnt lgkmcnt(0)
	v_pk_fma_f32 v[60:61], v[64:65], v[90:91], v[60:61] op_sel_hi:[0,1,1]
	v_pk_fma_f32 v[66:67], v[64:65], v[92:93], v[62:63] op_sel_hi:[0,1,1]
	ds_read_b128 v[62:65], v106 offset:192
	ds_read_b128 v[82:85], v106 offset:208
	ds_read_b128 v[86:89], v106 offset:224
	ds_read_b128 v[90:93], v106 offset:240
	s_waitcnt lgkmcnt(3)
	v_pk_fma_f32 v[60:61], v[160:161], v[62:63], v[60:61] op_sel_hi:[0,1,1]
	s_waitcnt lgkmcnt(2)
	v_pk_fma_f32 v[60:61], v[160:161], v[82:83], v[60:61] op_sel:[1,0,0]
	v_mov_b32_e32 v82, v163
	s_waitcnt lgkmcnt(1)
	v_pk_fma_f32 v[60:61], v[162:163], v[86:87], v[60:61] op_sel_hi:[0,1,1]
	s_waitcnt lgkmcnt(0)
	v_pk_fma_f32 v[62:63], v[82:83], v[90:91], v[60:61] op_sel_hi:[0,1,1]
	v_pk_fma_f32 v[60:61], v[160:161], v[64:65], v[66:67] op_sel_hi:[0,1,1]
	v_pk_fma_f32 v[60:61], v[160:161], v[84:85], v[60:61] op_sel:[1,0,0]
	s_nop 0
	v_pk_fma_f32 v[60:61], v[162:163], v[88:89], v[60:61] op_sel_hi:[0,1,1]
	v_pk_fma_f32 v[60:61], v[82:83], v[92:93], v[60:61] op_sel_hi:[0,1,1]
	s_add_u32 s100, s78, 0x1e880000
	s_addc_u32 s101, s79, 0
	global_load_dwordx4 v[148:151], v113, s[100:101]
	s_add_u32 s100, s100, 0x10000
	s_addc_u32 s101, s101, 0
	global_load_dwordx4 v[152:155], v113, s[100:101]
	s_add_u32 s100, s100, 0x10000
	s_addc_u32 s101, s101, 0
	global_load_dwordx4 v[156:159], v113, s[100:101]
	s_add_u32 s100, s100, 0x10000
	s_addc_u32 s101, s101, 0
	global_load_dwordx4 v[160:163], v113, s[100:101]
	s_waitcnt vmcnt(12)
	v_mov_b32_e32 v106, 0x300
	ds_read_b128 v[90:93], v106
	ds_read_b128 v[94:97], v106 offset:16
	ds_read_b128 v[98:101], v106 offset:32
	ds_read_b128 v[102:105], v106 offset:48
	s_waitcnt lgkmcnt(3)
	v_pk_fma_f32 v[62:63], v[164:165], v[90:91], v[62:63] op_sel_hi:[0,1,1]
	v_pk_fma_f32 v[60:61], v[164:165], v[92:93], v[60:61] op_sel_hi:[0,1,1]
	s_waitcnt lgkmcnt(2)
	v_pk_fma_f32 v[62:63], v[164:165], v[94:95], v[62:63] op_sel:[1,0,0]
	v_pk_fma_f32 v[60:61], v[164:165], v[96:97], v[60:61] op_sel:[1,0,0]
	s_waitcnt lgkmcnt(1)
	v_pk_fma_f32 v[62:63], v[166:167], v[98:99], v[62:63] op_sel_hi:[0,1,1]
	v_mov_b32_e32 v90, v167
	v_pk_fma_f32 v[60:61], v[166:167], v[100:101], v[60:61] op_sel_hi:[0,1,1]
	s_waitcnt lgkmcnt(0)
	v_pk_fma_f32 v[94:95], v[90:91], v[102:103], v[62:63] op_sel_hi:[0,1,1]
	v_pk_fma_f32 v[98:99], v[90:91], v[104:105], v[60:61] op_sel_hi:[0,1,1]
	ds_read_b128 v[60:63], v106 offset:64
	ds_read_b128 v[64:67], v106 offset:80
	ds_read_b128 v[90:93], v106 offset:96
	s_waitcnt lgkmcnt(2)
; __device__ void ph_filter_gen(const Params& P, int j, const float* __restrict__ a3, float* __restrict__ kf, float* sl) {
;     ...
;         for (int i = 0; i < 8; ++i) { const int t = tid + NT * i; const float4* ar = (const float4*)(a3 + (size_t)t * 64);
;             float a0 = 0.f, a1 = 0.f, a2 = 0.f, a3v = 0.f;
; #pragma unroll 4
;             for (int jq = 0; jq < 16; ++jq) { const float4 av = ar[jq]; const float ae[4] = {av.x, av.y, av.z, av.w};
; #pragma unroll
;                 for (int e = 0; e < 4; ++e) { const float4 wv = *(const float4*)(sw + (jq * 4 + e) * 4); a0 += ae[e] * wv.x; a1 += ae[e] * wv.y; a2 += ae[e] * wv.z; a3v += ae[e] * wv.w; } }
;             const float dec = expf(-((float)t / (float)(SEQ - 1)) * delta);
;             hv[i][0] = a0 * dec; hv[i][1] = a1 * dec; hv[i][2] = a2 * dec; hv[i][3] = a3v * dec;
	v_pk_fma_f32 v[60:61], v[168:169], v[60:61], v[94:95] op_sel_hi:[0,1,1]
	ds_read_b128 v[94:97], v106 offset:112
	s_waitcnt lgkmcnt(2)
	v_pk_fma_f32 v[60:61], v[168:169], v[64:65], v[60:61] op_sel:[1,0,0]
	v_mov_b32_e32 v64, v171
	s_waitcnt lgkmcnt(1)
	v_pk_fma_f32 v[60:61], v[170:171], v[90:91], v[60:61] op_sel_hi:[0,1,1]
	s_waitcnt lgkmcnt(0)
	v_pk_fma_f32 v[90:91], v[64:65], v[94:95], v[60:61] op_sel_hi:[0,1,1]
	v_pk_fma_f32 v[60:61], v[168:169], v[62:63], v[98:99] op_sel_hi:[0,1,1]
	v_pk_fma_f32 v[60:61], v[168:169], v[66:67], v[60:61] op_sel:[1,0,0]
	s_nop 0
	v_pk_fma_f32 v[60:61], v[170:171], v[92:93], v[60:61] op_sel_hi:[0,1,1]
	v_pk_fma_f32 v[94:95], v[64:65], v[96:97], v[60:61] op_sel_hi:[0,1,1]
	ds_read_b128 v[60:63], v106 offset:128
	ds_read_b128 v[64:67], v106 offset:144
	ds_read_b128 v[86:89], v106 offset:160
	s_waitcnt lgkmcnt(2)
	v_pk_fma_f32 v[60:61], v[172:173], v[60:61], v[90:91] op_sel_hi:[0,1,1]
	ds_read_b128 v[90:93], v106 offset:176
	v_pk_fma_f32 v[62:63], v[172:173], v[62:63], v[94:95] op_sel_hi:[0,1,1]
	s_waitcnt lgkmcnt(2)
	v_pk_fma_f32 v[60:61], v[172:173], v[64:65], v[60:61] op_sel:[1,0,0]
	v_pk_fma_f32 v[62:63], v[172:173], v[66:67], v[62:63] op_sel:[1,0,0]
	s_waitcnt lgkmcnt(1)
	v_pk_fma_f32 v[60:61], v[174:175], v[86:87], v[60:61] op_sel_hi:[0,1,1]
	v_mov_b32_e32 v64, v175
	v_pk_fma_f32 v[62:63], v[174:175], v[88:89], v[62:63] op_sel_hi:[0,1,1]
	s_waitcnt lgkmcnt(0)
	v_pk_fma_f32 v[60:61], v[64:65], v[90:91], v[60:61] op_sel_hi:[0,1,1]
	v_pk_fma_f32 v[66:67], v[64:65], v[92:93], v[62:63] op_sel_hi:[0,1,1]
	ds_read_b128 v[62:65], v106 offset:192
	ds_read_b128 v[82:85], v106 offset:208
	ds_read_b128 v[86:89], v106 offset:224
	ds_read_b128 v[90:93], v106 offset:240
	s_waitcnt lgkmcnt(3)
	v_pk_fma_f32 v[60:61], v[176:177], v[62:63], v[60:61] op_sel_hi:[0,1,1]
	s_waitcnt lgkmcnt(2)
	v_pk_fma_f32 v[60:61], v[176:177], v[82:83], v[60:61] op_sel:[1,0,0]
	v_mov_b32_e32 v82, v179
	s_waitcnt lgkmcnt(1)
	v_pk_fma_f32 v[60:61], v[178:179], v[86:87], v[60:61] op_sel_hi:[0,1,1]
	s_waitcnt lgkmcnt(0)
	v_pk_fma_f32 v[62:63], v[82:83], v[90:91], v[60:61] op_sel_hi:[0,1,1]
	v_pk_fma_f32 v[60:61], v[176:177], v[64:65], v[66:67] op_sel_hi:[0,1,1]
	v_pk_fma_f32 v[60:61], v[176:177], v[84:85], v[60:61] op_sel:[1,0,0]
	s_nop 0
	v_pk_fma_f32 v[60:61], v[178:179], v[88:89], v[60:61] op_sel_hi:[0,1,1]
	v_pk_fma_f32 v[60:61], v[82:83], v[92:93], v[60:61] op_sel_hi:[0,1,1]
	s_add_u32 s100, s78, 0x1e8c0000
	s_addc_u32 s101, s79, 0
	global_load_dwordx4 v[164:167], v113, s[100:101]
	s_add_u32 s100, s100, 0x10000
	s_addc_u32 s101, s101, 0
	global_load_dwordx4 v[168:171], v113, s[100:101]
	s_add_u32 s100, s100, 0x10000
	s_addc_u32 s101, s101, 0
	global_load_dwordx4 v[172:175], v113, s[100:101]
	s_add_u32 s100, s100, 0x10000
	s_addc_u32 s101, s101, 0
	global_load_dwordx4 v[176:179], v113, s[100:101]
	v_mov_b32_e32 v64, 0
	s_mov_b32 s0, 0
	s_mov_b64 s[14:15], 0
	v_mov_b32_e32 v65, v64
	v_mov_b32_e32 v66, v64
	v_mov_b32_e32 v67, v64
.LBB0_235:
	s_waitcnt vmcnt(12)
	v_mov_b32_e32 v112, 0
	ds_read_b128 v[94:97], v112
	ds_read_b128 v[98:101], v112 offset:16
	ds_read_b128 v[102:105], v112 offset:32
	ds_read_b128 v[106:109], v112 offset:48
	s_waitcnt lgkmcnt(3)
	v_mov_b32_e32 v110, v94
	v_mov_b32_e32 v111, v96
	v_mov_b32_e32 v96, v95
	v_pk_fma_f32 v[66:67], v[116:117], v[110:111], v[66:67] op_sel_hi:[0,1,1]
	s_waitcnt lgkmcnt(2)
	v_mov_b32_e32 v110, v98
	v_mov_b32_e32 v111, v100
	v_pk_fma_f32 v[64:65], v[116:117], v[96:97], v[64:65] op_sel_hi:[0,1,1]
	v_mov_b32_e32 v100, v99
	v_pk_fma_f32 v[66:67], v[116:117], v[110:111], v[66:67] op_sel:[1,0,0]
	s_waitcnt lgkmcnt(1)
	v_mov_b32_e32 v110, v102
	v_mov_b32_e32 v111, v104
	v_pk_fma_f32 v[64:65], v[116:117], v[100:101], v[64:65] op_sel:[1,0,0]
	v_mov_b32_e32 v104, v103
	v_pk_fma_f32 v[66:67], v[118:119], v[110:111], v[66:67] op_sel_hi:[0,1,1]
	v_mov_b32_e32 v94, v119
	s_waitcnt lgkmcnt(0)
	v_mov_b32_e32 v110, v106
	v_mov_b32_e32 v111, v108
	v_pk_fma_f32 v[64:65], v[118:119], v[104:105], v[64:65] op_sel_hi:[0,1,1]
	v_mov_b32_e32 v108, v107
	v_pk_fma_f32 v[110:111], v[94:95], v[110:111], v[66:67] op_sel_hi:[0,1,1]
	v_pk_fma_f32 v[102:103], v[94:95], v[108:109], v[64:65] op_sel_hi:[0,1,1]
	ds_read_b128 v[64:67], v112 offset:64
	ds_read_b128 v[78:81], v112 offset:80
	ds_read_b128 v[94:97], v112 offset:96
	s_waitcnt lgkmcnt(2)
	v_mov_b32_e32 v98, v64
	v_mov_b32_e32 v99, v66
	v_pk_fma_f32 v[98:99], v[120:121], v[98:99], v[110:111] op_sel_hi:[0,1,1]
	s_waitcnt lgkmcnt(1)
	v_mov_b32_e32 v100, v78
	v_mov_b32_e32 v101, v80
	v_pk_fma_f32 v[98:99], v[120:121], v[100:101], v[98:99] op_sel:[1,0,0]
	s_waitcnt lgkmcnt(0)
	v_mov_b32_e32 v100, v94
	v_mov_b32_e32 v101, v96
	v_pk_fma_f32 v[104:105], v[122:123], v[100:101], v[98:99] op_sel_hi:[0,1,1]
	ds_read_b128 v[98:101], v112 offset:112
	v_mov_b32_e32 v66, v65
	v_pk_fma_f32 v[66:67], v[120:121], v[66:67], v[102:103] op_sel_hi:[0,1,1]
	v_mov_b32_e32 v80, v79
	v_pk_fma_f32 v[66:67], v[120:121], v[80:81], v[66:67] op_sel:[1,0,0]
	v_mov_b32_e32 v96, v95
	v_mov_b32_e32 v64, v123
	s_waitcnt lgkmcnt(0)
	v_mov_b32_e32 v106, v98
	v_mov_b32_e32 v107, v100
	v_pk_fma_f32 v[66:67], v[122:123], v[96:97], v[66:67] op_sel_hi:[0,1,1]
	v_mov_b32_e32 v100, v99
	v_pk_fma_f32 v[104:105], v[64:65], v[106:107], v[104:105] op_sel_hi:[0,1,1]
	v_pk_fma_f32 v[98:99], v[64:65], v[100:101], v[66:67] op_sel_hi:[0,1,1]
	ds_read_b128 v[64:67], v112 offset:128
	ds_read_b128 v[78:81], v112 offset:144
	ds_read_b128 v[90:93], v112 offset:160
	s_waitcnt lgkmcnt(2)
	v_mov_b32_e32 v94, v64
	v_mov_b32_e32 v95, v66
	v_pk_fma_f32 v[94:95], v[124:125], v[94:95], v[104:105] op_sel_hi:[0,1,1]
	s_waitcnt lgkmcnt(1)
; __device__ void ph_filter_gen(const Params& P, int j, const float* __restrict__ a3, float* __restrict__ kf, float* sl) {
;     ...
;         for (int i = 0; i < 8; ++i) { const int t = tid + NT * i; const float4* ar = (const float4*)(a3 + (size_t)t * 64);
;             float a0 = 0.f, a1 = 0.f, a2 = 0.f, a3v = 0.f;
; #pragma unroll 4
;             for (int jq = 0; jq < 16; ++jq) { const float4 av = ar[jq]; const float ae[4] = {av.x, av.y, av.z, av.w};
; #pragma unroll
;                 for (int e = 0; e < 4; ++e) { const float4 wv = *(const float4*)(sw + (jq * 4 + e) * 4); a0 += ae[e] * wv.x; a1 += ae[e] * wv.y; a2 += ae[e] * wv.z; a3v += ae[e] * wv.w; } }
;             const float dec = expf(-((float)t / (float)(SEQ - 1)) * delta);
;             hv[i][0] = a0 * dec; hv[i][1] = a1 * dec; hv[i][2] = a2 * dec; hv[i][3] = a3v * dec;
	v_mov_b32_e32 v96, v78
	v_mov_b32_e32 v97, v80
	v_pk_fma_f32 v[94:95], v[124:125], v[96:97], v[94:95] op_sel:[1,0,0]
	s_waitcnt lgkmcnt(0)
	v_mov_b32_e32 v96, v90
	v_mov_b32_e32 v97, v92
	v_pk_fma_f32 v[100:101], v[126:127], v[96:97], v[94:95] op_sel_hi:[0,1,1]
	ds_read_b128 v[94:97], v112 offset:176
	v_mov_b32_e32 v66, v65
	v_pk_fma_f32 v[66:67], v[124:125], v[66:67], v[98:99] op_sel_hi:[0,1,1]
	v_mov_b32_e32 v80, v79
	v_pk_fma_f32 v[66:67], v[124:125], v[80:81], v[66:67] op_sel:[1,0,0]
	v_mov_b32_e32 v92, v91
	v_mov_b32_e32 v64, v127
	v_pk_fma_f32 v[66:67], v[126:127], v[92:93], v[66:67] op_sel_hi:[0,1,1]
	ds_read_b128 v[78:81], v112 offset:192
	ds_read_b128 v[86:89], v112 offset:208
	ds_read_b128 v[90:93], v112 offset:224
	s_waitcnt lgkmcnt(3)
	v_mov_b32_e32 v102, v94
	v_mov_b32_e32 v103, v96
	v_mov_b32_e32 v96, v95
	v_pk_fma_f32 v[100:101], v[64:65], v[102:103], v[100:101] op_sel_hi:[0,1,1]
	v_pk_fma_f32 v[64:65], v[64:65], v[96:97], v[66:67] op_sel_hi:[0,1,1]
	s_waitcnt lgkmcnt(2)
	v_mov_b32_e32 v66, v78
	v_mov_b32_e32 v67, v80
	v_pk_fma_f32 v[66:67], v[128:129], v[66:67], v[100:101] op_sel_hi:[0,1,1]
	s_waitcnt lgkmcnt(1)
	v_mov_b32_e32 v94, v86
	v_mov_b32_e32 v95, v88
	v_pk_fma_f32 v[66:67], v[128:129], v[94:95], v[66:67] op_sel:[1,0,0]
	s_waitcnt lgkmcnt(0)
	v_mov_b32_e32 v94, v90
	v_mov_b32_e32 v95, v92
	v_pk_fma_f32 v[66:67], v[130:131], v[94:95], v[66:67] op_sel_hi:[0,1,1]
	ds_read_b128 v[94:97], v112 offset:240
	v_mov_b32_e32 v80, v79
	v_pk_fma_f32 v[64:65], v[128:129], v[80:81], v[64:65] op_sel_hi:[0,1,1]
	v_mov_b32_e32 v88, v87
	v_pk_fma_f32 v[64:65], v[128:129], v[88:89], v[64:65] op_sel:[1,0,0]
	v_mov_b32_e32 v92, v91
	v_mov_b32_e32 v78, v131
	s_waitcnt lgkmcnt(0)
	v_mov_b32_e32 v98, v94
	v_mov_b32_e32 v99, v96
	v_pk_fma_f32 v[64:65], v[130:131], v[92:93], v[64:65] op_sel_hi:[0,1,1]
	v_mov_b32_e32 v96, v95
	v_pk_fma_f32 v[66:67], v[78:79], v[98:99], v[66:67] op_sel_hi:[0,1,1]
	v_pk_fma_f32 v[64:65], v[78:79], v[96:97], v[64:65] op_sel_hi:[0,1,1]
	s_waitcnt vmcnt(8)
	v_mov_b32_e32 v112, 0x100
	ds_read_b128 v[94:97], v112
	ds_read_b128 v[98:101], v112 offset:16
	ds_read_b128 v[102:105], v112 offset:32
	ds_read_b128 v[106:109], v112 offset:48
	s_waitcnt lgkmcnt(3)
	v_mov_b32_e32 v110, v94
	v_mov_b32_e32 v111, v96
	v_mov_b32_e32 v96, v95
	v_pk_fma_f32 v[66:67], v[132:133], v[110:111], v[66:67] op_sel_hi:[0,1,1]
	s_waitcnt lgkmcnt(2)
	v_mov_b32_e32 v110, v98
	v_mov_b32_e32 v111, v100
	v_pk_fma_f32 v[64:65], v[132:133], v[96:97], v[64:65] op_sel_hi:[0,1,1]
	v_mov_b32_e32 v100, v99
	v_pk_fma_f32 v[66:67], v[132:133], v[110:111], v[66:67] op_sel:[1,0,0]
	s_waitcnt lgkmcnt(1)
	v_mov_b32_e32 v110, v102
	v_mov_b32_e32 v111, v104
	v_pk_fma_f32 v[64:65], v[132:133], v[100:101], v[64:65] op_sel:[1,0,0]
	v_mov_b32_e32 v104, v103
	v_pk_fma_f32 v[66:67], v[134:135], v[110:111], v[66:67] op_sel_hi:[0,1,1]
	v_mov_b32_e32 v94, v135
	s_waitcnt lgkmcnt(0)
	v_mov_b32_e32 v110, v106
	v_mov_b32_e32 v111, v108
	v_pk_fma_f32 v[64:65], v[134:135], v[104:105], v[64:65] op_sel_hi:[0,1,1]
	v_mov_b32_e32 v108, v107
	v_pk_fma_f32 v[110:111], v[94:95], v[110:111], v[66:67] op_sel_hi:[0,1,1]
	v_pk_fma_f32 v[102:103], v[94:95], v[108:109], v[64:65] op_sel_hi:[0,1,1]
	ds_read_b128 v[64:67], v112 offset:64
	ds_read_b128 v[78:81], v112 offset:80
	ds_read_b128 v[94:97], v112 offset:96
	s_waitcnt lgkmcnt(2)
	v_mov_b32_e32 v98, v64
	v_mov_b32_e32 v99, v66
	v_pk_fma_f32 v[98:99], v[136:137], v[98:99], v[110:111] op_sel_hi:[0,1,1]
	s_waitcnt lgkmcnt(1)
	v_mov_b32_e32 v100, v78
	v_mov_b32_e32 v101, v80
	v_pk_fma_f32 v[98:99], v[136:137], v[100:101], v[98:99] op_sel:[1,0,0]
	s_waitcnt lgkmcnt(0)
	v_mov_b32_e32 v100, v94
	v_mov_b32_e32 v101, v96
	v_pk_fma_f32 v[104:105], v[138:139], v[100:101], v[98:99] op_sel_hi:[0,1,1]
	ds_read_b128 v[98:101], v112 offset:112
	v_mov_b32_e32 v66, v65
	v_pk_fma_f32 v[66:67], v[136:137], v[66:67], v[102:103] op_sel_hi:[0,1,1]
	v_mov_b32_e32 v80, v79
	v_pk_fma_f32 v[66:67], v[136:137], v[80:81], v[66:67] op_sel:[1,0,0]
	v_mov_b32_e32 v96, v95
	v_mov_b32_e32 v64, v139
	s_waitcnt lgkmcnt(0)
	v_mov_b32_e32 v106, v98
	v_mov_b32_e32 v107, v100
	v_pk_fma_f32 v[66:67], v[138:139], v[96:97], v[66:67] op_sel_hi:[0,1,1]
	v_mov_b32_e32 v100, v99
	v_pk_fma_f32 v[104:105], v[64:65], v[106:107], v[104:105] op_sel_hi:[0,1,1]
	v_pk_fma_f32 v[98:99], v[64:65], v[100:101], v[66:67] op_sel_hi:[0,1,1]
	ds_read_b128 v[64:67], v112 offset:128
	ds_read_b128 v[78:81], v112 offset:144
	ds_read_b128 v[90:93], v112 offset:160
	s_waitcnt lgkmcnt(2)
	v_mov_b32_e32 v94, v64
	v_mov_b32_e32 v95, v66
	v_pk_fma_f32 v[94:95], v[140:141], v[94:95], v[104:105] op_sel_hi:[0,1,1]
	s_waitcnt lgkmcnt(1)
	v_mov_b32_e32 v96, v78
	v_mov_b32_e32 v97, v80
	v_pk_fma_f32 v[94:95], v[140:141], v[96:97], v[94:95] op_sel:[1,0,0]
	s_waitcnt lgkmcnt(0)
	v_mov_b32_e32 v96, v90
	v_mov_b32_e32 v97, v92
	v_pk_fma_f32 v[100:101], v[142:143], v[96:97], v[94:95] op_sel_hi:[0,1,1]
	ds_read_b128 v[94:97], v112 offset:176
	v_mov_b32_e32 v66, v65
	v_pk_fma_f32 v[66:67], v[140:141], v[66:67], v[98:99] op_sel_hi:[0,1,1]
	v_mov_b32_e32 v80, v79
	v_pk_fma_f32 v[66:67], v[140:141], v[80:81], v[66:67] op_sel:[1,0,0]
	v_mov_b32_e32 v92, v91
	v_mov_b32_e32 v64, v143
	v_pk_fma_f32 v[66:67], v[142:143], v[92:93], v[66:67] op_sel_hi:[0,1,1]
	ds_read_b128 v[78:81], v112 offset:192
	ds_read_b128 v[86:89], v112 offset:208
	ds_read_b128 v[90:93], v112 offset:224
	s_waitcnt lgkmcnt(3)
	v_mov_b32_e32 v102, v94
	v_mov_b32_e32 v103, v96
	v_mov_b32_e32 v96, v95
	v_pk_fma_f32 v[100:101], v[64:65], v[102:103], v[100:101] op_sel_hi:[0,1,1]
	v_pk_fma_f32 v[64:65], v[64:65], v[96:97], v[66:67] op_sel_hi:[0,1,1]
	s_waitcnt lgkmcnt(2)
; __device__ void ph_filter_gen(const Params& P, int j, const float* __restrict__ a3, float* __restrict__ kf, float* sl) {
;     ...
;         for (int i = 0; i < 8; ++i) { const int t = tid + NT * i; const float4* ar = (const float4*)(a3 + (size_t)t * 64);
;             float a0 = 0.f, a1 = 0.f, a2 = 0.f, a3v = 0.f;
; #pragma unroll 4
;             for (int jq = 0; jq < 16; ++jq) { const float4 av = ar[jq]; const float ae[4] = {av.x, av.y, av.z, av.w};
; #pragma unroll
;                 for (int e = 0; e < 4; ++e) { const float4 wv = *(const float4*)(sw + (jq * 4 + e) * 4); a0 += ae[e] * wv.x; a1 += ae[e] * wv.y; a2 += ae[e] * wv.z; a3v += ae[e] * wv.w; } }
;             const float dec = expf(-((float)t / (float)(SEQ - 1)) * delta);
;             hv[i][0] = a0 * dec; hv[i][1] = a1 * dec; hv[i][2] = a2 * dec; hv[i][3] = a3v * dec;
	v_mov_b32_e32 v66, v78
	v_mov_b32_e32 v67, v80
	v_pk_fma_f32 v[66:67], v[144:145], v[66:67], v[100:101] op_sel_hi:[0,1,1]
	s_waitcnt lgkmcnt(1)
	v_mov_b32_e32 v94, v86
	v_mov_b32_e32 v95, v88
	v_pk_fma_f32 v[66:67], v[144:145], v[94:95], v[66:67] op_sel:[1,0,0]
	s_waitcnt lgkmcnt(0)
	v_mov_b32_e32 v94, v90
	v_mov_b32_e32 v95, v92
	v_pk_fma_f32 v[66:67], v[146:147], v[94:95], v[66:67] op_sel_hi:[0,1,1]
	ds_read_b128 v[94:97], v112 offset:240
	v_mov_b32_e32 v80, v79
	v_pk_fma_f32 v[64:65], v[144:145], v[80:81], v[64:65] op_sel_hi:[0,1,1]
	v_mov_b32_e32 v88, v87
	v_pk_fma_f32 v[64:65], v[144:145], v[88:89], v[64:65] op_sel:[1,0,0]
	v_mov_b32_e32 v92, v91
	v_mov_b32_e32 v78, v147
	s_waitcnt lgkmcnt(0)
	v_mov_b32_e32 v98, v94
	v_mov_b32_e32 v99, v96
	v_pk_fma_f32 v[64:65], v[146:147], v[92:93], v[64:65] op_sel_hi:[0,1,1]
	v_mov_b32_e32 v96, v95
	v_pk_fma_f32 v[66:67], v[78:79], v[98:99], v[66:67] op_sel_hi:[0,1,1]
	v_pk_fma_f32 v[64:65], v[78:79], v[96:97], v[64:65] op_sel_hi:[0,1,1]
	s_waitcnt vmcnt(4)
	v_mov_b32_e32 v112, 0x200
	ds_read_b128 v[94:97], v112
	ds_read_b128 v[98:101], v112 offset:16
	ds_read_b128 v[102:105], v112 offset:32
	ds_read_b128 v[106:109], v112 offset:48
	s_waitcnt lgkmcnt(3)
	v_mov_b32_e32 v110, v94
	v_mov_b32_e32 v111, v96
	v_mov_b32_e32 v96, v95
	v_pk_fma_f32 v[66:67], v[148:149], v[110:111], v[66:67] op_sel_hi:[0,1,1]
	s_waitcnt lgkmcnt(2)
	v_mov_b32_e32 v110, v98
	v_mov_b32_e32 v111, v100
	v_pk_fma_f32 v[64:65], v[148:149], v[96:97], v[64:65] op_sel_hi:[0,1,1]
	v_mov_b32_e32 v100, v99
	v_pk_fma_f32 v[66:67], v[148:149], v[110:111], v[66:67] op_sel:[1,0,0]
	s_waitcnt lgkmcnt(1)
	v_mov_b32_e32 v110, v102
	v_mov_b32_e32 v111, v104
	v_pk_fma_f32 v[64:65], v[148:149], v[100:101], v[64:65] op_sel:[1,0,0]
	v_mov_b32_e32 v104, v103
	v_pk_fma_f32 v[66:67], v[150:151], v[110:111], v[66:67] op_sel_hi:[0,1,1]
	v_mov_b32_e32 v94, v151
	s_waitcnt lgkmcnt(0)
	v_mov_b32_e32 v110, v106
	v_mov_b32_e32 v111, v108
	v_pk_fma_f32 v[64:65], v[150:151], v[104:105], v[64:65] op_sel_hi:[0,1,1]
	v_mov_b32_e32 v108, v107
	v_pk_fma_f32 v[110:111], v[94:95], v[110:111], v[66:67] op_sel_hi:[0,1,1]
	v_pk_fma_f32 v[102:103], v[94:95], v[108:109], v[64:65] op_sel_hi:[0,1,1]
	ds_read_b128 v[64:67], v112 offset:64
	ds_read_b128 v[78:81], v112 offset:80
	ds_read_b128 v[94:97], v112 offset:96
	s_waitcnt lgkmcnt(2)
	v_mov_b32_e32 v98, v64
	v_mov_b32_e32 v99, v66
	v_pk_fma_f32 v[98:99], v[152:153], v[98:99], v[110:111] op_sel_hi:[0,1,1]
	s_waitcnt lgkmcnt(1)
	v_mov_b32_e32 v100, v78
	v_mov_b32_e32 v101, v80
	v_pk_fma_f32 v[98:99], v[152:153], v[100:101], v[98:99] op_sel:[1,0,0]
	s_waitcnt lgkmcnt(0)
	v_mov_b32_e32 v100, v94
	v_mov_b32_e32 v101, v96
	v_pk_fma_f32 v[104:105], v[154:155], v[100:101], v[98:99] op_sel_hi:[0,1,1]
	ds_read_b128 v[98:101], v112 offset:112
	v_mov_b32_e32 v66, v65
	v_pk_fma_f32 v[66:67], v[152:153], v[66:67], v[102:103] op_sel_hi:[0,1,1]
	v_mov_b32_e32 v80, v79
	v_pk_fma_f32 v[66:67], v[152:153], v[80:81], v[66:67] op_sel:[1,0,0]
	v_mov_b32_e32 v96, v95
	v_mov_b32_e32 v64, v155
	s_waitcnt lgkmcnt(0)
	v_mov_b32_e32 v106, v98
	v_mov_b32_e32 v107, v100
	v_pk_fma_f32 v[66:67], v[154:155], v[96:97], v[66:67] op_sel_hi:[0,1,1]
	v_mov_b32_e32 v100, v99
	v_pk_fma_f32 v[104:105], v[64:65], v[106:107], v[104:105] op_sel_hi:[0,1,1]
	v_pk_fma_f32 v[98:99], v[64:65], v[100:101], v[66:67] op_sel_hi:[0,1,1]
	ds_read_b128 v[64:67], v112 offset:128
	ds_read_b128 v[78:81], v112 offset:144
	ds_read_b128 v[90:93], v112 offset:160
	s_waitcnt lgkmcnt(2)
	v_mov_b32_e32 v94, v64
	v_mov_b32_e32 v95, v66
	v_pk_fma_f32 v[94:95], v[156:157], v[94:95], v[104:105] op_sel_hi:[0,1,1]
	s_waitcnt lgkmcnt(1)
	v_mov_b32_e32 v96, v78
	v_mov_b32_e32 v97, v80
	v_pk_fma_f32 v[94:95], v[156:157], v[96:97], v[94:95] op_sel:[1,0,0]
	s_waitcnt lgkmcnt(0)
	v_mov_b32_e32 v96, v90
	v_mov_b32_e32 v97, v92
	v_pk_fma_f32 v[100:101], v[158:159], v[96:97], v[94:95] op_sel_hi:[0,1,1]
	ds_read_b128 v[94:97], v112 offset:176
	v_mov_b32_e32 v66, v65
	v_pk_fma_f32 v[66:67], v[156:157], v[66:67], v[98:99] op_sel_hi:[0,1,1]
	v_mov_b32_e32 v80, v79
	v_pk_fma_f32 v[66:67], v[156:157], v[80:81], v[66:67] op_sel:[1,0,0]
	v_mov_b32_e32 v92, v91
	v_mov_b32_e32 v64, v159
	v_pk_fma_f32 v[66:67], v[158:159], v[92:93], v[66:67] op_sel_hi:[0,1,1]
	ds_read_b128 v[78:81], v112 offset:192
	ds_read_b128 v[86:89], v112 offset:208
	ds_read_b128 v[90:93], v112 offset:224
	s_waitcnt lgkmcnt(3)
	v_mov_b32_e32 v102, v94
	v_mov_b32_e32 v103, v96
	v_mov_b32_e32 v96, v95
	v_pk_fma_f32 v[100:101], v[64:65], v[102:103], v[100:101] op_sel_hi:[0,1,1]
	v_pk_fma_f32 v[64:65], v[64:65], v[96:97], v[66:67] op_sel_hi:[0,1,1]
	s_waitcnt lgkmcnt(2)
	v_mov_b32_e32 v66, v78
	v_mov_b32_e32 v67, v80
	v_pk_fma_f32 v[66:67], v[160:161], v[66:67], v[100:101] op_sel_hi:[0,1,1]
	s_waitcnt lgkmcnt(1)
	v_mov_b32_e32 v94, v86
	v_mov_b32_e32 v95, v88
	v_pk_fma_f32 v[66:67], v[160:161], v[94:95], v[66:67] op_sel:[1,0,0]
	s_waitcnt lgkmcnt(0)
	v_mov_b32_e32 v94, v90
	v_mov_b32_e32 v95, v92
	v_pk_fma_f32 v[66:67], v[162:163], v[94:95], v[66:67] op_sel_hi:[0,1,1]
	ds_read_b128 v[94:97], v112 offset:240
	v_mov_b32_e32 v80, v79
	v_pk_fma_f32 v[64:65], v[160:161], v[80:81], v[64:65] op_sel_hi:[0,1,1]
	v_mov_b32_e32 v88, v87
	v_pk_fma_f32 v[64:65], v[160:161], v[88:89], v[64:65] op_sel:[1,0,0]
	v_mov_b32_e32 v92, v91
	v_mov_b32_e32 v78, v163
	s_waitcnt lgkmcnt(0)
	v_mov_b32_e32 v98, v94
	v_mov_b32_e32 v99, v96
	v_pk_fma_f32 v[64:65], v[162:163], v[92:93], v[64:65] op_sel_hi:[0,1,1]
	v_mov_b32_e32 v96, v95
	v_pk_fma_f32 v[66:67], v[78:79], v[98:99], v[66:67] op_sel_hi:[0,1,1]
	v_pk_fma_f32 v[64:65], v[78:79], v[96:97], v[64:65] op_sel_hi:[0,1,1]
	s_waitcnt vmcnt(0)
; __device__ void ph_filter_gen(const Params& P, int j, const float* __restrict__ a3, float* __restrict__ kf, float* sl) {
;     ...
;         for (int i = 0; i < 8; ++i) { const int t = tid + NT * i; const float4* ar = (const float4*)(a3 + (size_t)t * 64);
;             float a0 = 0.f, a1 = 0.f, a2 = 0.f, a3v = 0.f;
; #pragma unroll 4
;             for (int jq = 0; jq < 16; ++jq) { const float4 av = ar[jq]; const float ae[4] = {av.x, av.y, av.z, av.w};
; #pragma unroll
;                 for (int e = 0; e < 4; ++e) { const float4 wv = *(const float4*)(sw + (jq * 4 + e) * 4); a0 += ae[e] * wv.x; a1 += ae[e] * wv.y; a2 += ae[e] * wv.z; a3v += ae[e] * wv.w; } }
;             const float dec = expf(-((float)t / (float)(SEQ - 1)) * delta);
;             hv[i][0] = a0 * dec; hv[i][1] = a1 * dec; hv[i][2] = a2 * dec; hv[i][3] = a3v * dec;
	v_mov_b32_e32 v112, 0x300
	ds_read_b128 v[94:97], v112
	ds_read_b128 v[98:101], v112 offset:16
	ds_read_b128 v[102:105], v112 offset:32
	ds_read_b128 v[106:109], v112 offset:48
	s_waitcnt lgkmcnt(3)
	v_mov_b32_e32 v110, v94
	v_mov_b32_e32 v111, v96
	v_mov_b32_e32 v96, v95
	v_pk_fma_f32 v[66:67], v[164:165], v[110:111], v[66:67] op_sel_hi:[0,1,1]
	s_waitcnt lgkmcnt(2)
	v_mov_b32_e32 v110, v98
	v_mov_b32_e32 v111, v100
	v_pk_fma_f32 v[64:65], v[164:165], v[96:97], v[64:65] op_sel_hi:[0,1,1]
	v_mov_b32_e32 v100, v99
	v_pk_fma_f32 v[66:67], v[164:165], v[110:111], v[66:67] op_sel:[1,0,0]
	s_waitcnt lgkmcnt(1)
	v_mov_b32_e32 v110, v102
	v_mov_b32_e32 v111, v104
	v_pk_fma_f32 v[64:65], v[164:165], v[100:101], v[64:65] op_sel:[1,0,0]
	v_mov_b32_e32 v104, v103
	v_pk_fma_f32 v[66:67], v[166:167], v[110:111], v[66:67] op_sel_hi:[0,1,1]
	v_mov_b32_e32 v94, v167
	s_waitcnt lgkmcnt(0)
	v_mov_b32_e32 v110, v106
	v_mov_b32_e32 v111, v108
	v_pk_fma_f32 v[64:65], v[166:167], v[104:105], v[64:65] op_sel_hi:[0,1,1]
	v_mov_b32_e32 v108, v107
	v_pk_fma_f32 v[110:111], v[94:95], v[110:111], v[66:67] op_sel_hi:[0,1,1]
	v_pk_fma_f32 v[102:103], v[94:95], v[108:109], v[64:65] op_sel_hi:[0,1,1]
	ds_read_b128 v[64:67], v112 offset:64
	ds_read_b128 v[78:81], v112 offset:80
	ds_read_b128 v[94:97], v112 offset:96
	s_waitcnt lgkmcnt(2)
	v_mov_b32_e32 v98, v64
	v_mov_b32_e32 v99, v66
	v_pk_fma_f32 v[98:99], v[168:169], v[98:99], v[110:111] op_sel_hi:[0,1,1]
	s_waitcnt lgkmcnt(1)
	v_mov_b32_e32 v100, v78
	v_mov_b32_e32 v101, v80
	v_pk_fma_f32 v[98:99], v[168:169], v[100:101], v[98:99] op_sel:[1,0,0]
	s_waitcnt lgkmcnt(0)
	v_mov_b32_e32 v100, v94
	v_mov_b32_e32 v101, v96
	v_pk_fma_f32 v[104:105], v[170:171], v[100:101], v[98:99] op_sel_hi:[0,1,1]
	ds_read_b128 v[98:101], v112 offset:112
	v_mov_b32_e32 v66, v65
	v_pk_fma_f32 v[66:67], v[168:169], v[66:67], v[102:103] op_sel_hi:[0,1,1]
	v_mov_b32_e32 v80, v79
	v_pk_fma_f32 v[66:67], v[168:169], v[80:81], v[66:67] op_sel:[1,0,0]
	v_mov_b32_e32 v96, v95
	v_mov_b32_e32 v64, v171
	s_waitcnt lgkmcnt(0)
	v_mov_b32_e32 v106, v98
	v_mov_b32_e32 v107, v100
	v_pk_fma_f32 v[66:67], v[170:171], v[96:97], v[66:67] op_sel_hi:[0,1,1]
	v_mov_b32_e32 v100, v99
	v_pk_fma_f32 v[104:105], v[64:65], v[106:107], v[104:105] op_sel_hi:[0,1,1]
	v_pk_fma_f32 v[98:99], v[64:65], v[100:101], v[66:67] op_sel_hi:[0,1,1]
	ds_read_b128 v[64:67], v112 offset:128
	ds_read_b128 v[78:81], v112 offset:144
	ds_read_b128 v[90:93], v112 offset:160
	s_waitcnt lgkmcnt(2)
	v_mov_b32_e32 v94, v64
	v_mov_b32_e32 v95, v66
	v_pk_fma_f32 v[94:95], v[172:173], v[94:95], v[104:105] op_sel_hi:[0,1,1]
	s_waitcnt lgkmcnt(1)
	v_mov_b32_e32 v96, v78
	v_mov_b32_e32 v97, v80
	v_pk_fma_f32 v[94:95], v[172:173], v[96:97], v[94:95] op_sel:[1,0,0]
	s_waitcnt lgkmcnt(0)
	v_mov_b32_e32 v96, v90
	v_mov_b32_e32 v97, v92
	v_pk_fma_f32 v[100:101], v[174:175], v[96:97], v[94:95] op_sel_hi:[0,1,1]
	ds_read_b128 v[94:97], v112 offset:176
	v_mov_b32_e32 v66, v65
	v_pk_fma_f32 v[66:67], v[172:173], v[66:67], v[98:99] op_sel_hi:[0,1,1]
	v_mov_b32_e32 v80, v79
	v_pk_fma_f32 v[66:67], v[172:173], v[80:81], v[66:67] op_sel:[1,0,0]
	v_mov_b32_e32 v92, v91
	v_mov_b32_e32 v64, v175
	v_pk_fma_f32 v[66:67], v[174:175], v[92:93], v[66:67] op_sel_hi:[0,1,1]
	ds_read_b128 v[78:81], v112 offset:192
	ds_read_b128 v[86:89], v112 offset:208
	ds_read_b128 v[90:93], v112 offset:224
	s_waitcnt lgkmcnt(3)
	v_mov_b32_e32 v102, v94
	v_mov_b32_e32 v103, v96
	v_mov_b32_e32 v96, v95
	v_pk_fma_f32 v[100:101], v[64:65], v[102:103], v[100:101] op_sel_hi:[0,1,1]
	v_pk_fma_f32 v[64:65], v[64:65], v[96:97], v[66:67] op_sel_hi:[0,1,1]
	s_waitcnt lgkmcnt(2)
	v_mov_b32_e32 v66, v78
	v_mov_b32_e32 v67, v80
	v_pk_fma_f32 v[66:67], v[176:177], v[66:67], v[100:101] op_sel_hi:[0,1,1]
	s_waitcnt lgkmcnt(1)
	v_mov_b32_e32 v94, v86
	v_mov_b32_e32 v95, v88
	v_pk_fma_f32 v[66:67], v[176:177], v[94:95], v[66:67] op_sel:[1,0,0]
	s_waitcnt lgkmcnt(0)
	v_mov_b32_e32 v94, v90
	v_mov_b32_e32 v95, v92
	v_pk_fma_f32 v[66:67], v[178:179], v[94:95], v[66:67] op_sel_hi:[0,1,1]
	ds_read_b128 v[94:97], v112 offset:240
	v_mov_b32_e32 v80, v79
	v_pk_fma_f32 v[64:65], v[176:177], v[80:81], v[64:65] op_sel_hi:[0,1,1]
	v_mov_b32_e32 v88, v87
	v_pk_fma_f32 v[64:65], v[176:177], v[88:89], v[64:65] op_sel:[1,0,0]
	v_mov_b32_e32 v92, v91
	v_mov_b32_e32 v78, v179
	s_waitcnt lgkmcnt(0)
; __device__ void ph_filter_gen(const Params& P, int j, const float* __restrict__ a3, float* __restrict__ kf, float* sl) {
;     ...
;             const float dec = expf(-((float)t / (float)(SEQ - 1)) * delta);
;             hv[i][0] = a0 * dec; hv[i][1] = a1 * dec; hv[i][2] = a2 * dec; hv[i][3] = a3v * dec;
;             n0 += fabsf(hv[i][0]) + (t >= 1 ? fabsf(hv[i][1]) : 0.f); n1 += fabsf(hv[i][2]) + (t >= 1 ? fabsf(hv[i][3]) : 0.f); }
;         n0 = wave_sum(n0); n1 = wave_sum(n1);
	v_mov_b32_e32 v98, v94
	v_mov_b32_e32 v99, v96
	v_pk_fma_f32 v[64:65], v[178:179], v[92:93], v[64:65] op_sel_hi:[0,1,1]
	v_mov_b32_e32 v96, v95
	v_pk_fma_f32 v[66:67], v[78:79], v[98:99], v[66:67] op_sel_hi:[0,1,1]
	v_pk_fma_f32 v[64:65], v[78:79], v[96:97], v[64:65] op_sel_hi:[0,1,1]
	v_cvt_f32_i32_e32 v78, s38
	v_mov_b32_e32 v79, 0xc0447cbd
	s_mov_b32 s0, 0xc2ce8ed0
	s_mov_b32 s1, 0x42b17218
	v_fmamk_f32 v91, v78, 0xbc44ade8, v79
	v_mul_f32_e64 v78, v69, |v91|
	v_mul_f32_e32 v79, 0x3fb8aa3b, v78
	v_fma_f32 v80, v78, s92, -v79
	v_rndne_f32_e32 v81, v79
	v_fmac_f32_e32 v80, 0x32a5705f, v78
	v_sub_f32_e32 v79, v79, v81
	v_add_f32_e32 v79, v79, v80
	v_cvt_i32_f32_e32 v81, v81
	v_exp_f32_e32 v79, v79
	v_cmp_ngt_f32_e32 vcc, s0, v78
	v_mul_f32_e64 v80, v70, |v91|
	v_ldexp_f32 v79, v79, v81
	v_cndmask_b32_e32 v79, 0, v79, vcc
	v_cmp_nlt_f32_e32 vcc, s1, v78
	s_nop 1
	v_cndmask_b32_e32 v82, v244, v79, vcc
	v_mul_f32_e32 v79, v82, v39
	v_mul_f32_e32 v39, 0x3fb8aa3b, v80
	v_fma_f32 v78, v80, s92, -v39
	v_rndne_f32_e32 v81, v39
	v_fmac_f32_e32 v78, 0x32a5705f, v80
	v_sub_f32_e32 v39, v39, v81
	v_add_f32_e32 v39, v39, v78
	v_exp_f32_e32 v39, v39
	v_cvt_i32_f32_e32 v78, v81
	v_cmp_ngt_f32_e32 vcc, s0, v80
	v_cndmask_b32_e64 v81, 0, |v79|, s[46:47]
	v_mul_f32_e32 v85, v82, v38
	v_ldexp_f32 v39, v39, v78
	v_cndmask_b32_e32 v39, 0, v39, vcc
	v_cmp_nlt_f32_e32 vcc, s1, v80
	v_add_f32_e64 v38, |v85|, v81
	v_mul_f32_e32 v86, v82, v37
	v_cndmask_b32_e32 v39, v244, v39, vcc
	v_mul_f32_e32 v83, v39, v42
	v_mul_f32_e64 v42, v71, |v91|
	v_mul_f32_e32 v80, v39, v43
	v_mul_f32_e32 v43, 0x3fb8aa3b, v42
	v_fma_f32 v78, v42, s92, -v43
	v_rndne_f32_e32 v81, v43
	v_fmac_f32_e32 v78, 0x32a5705f, v42
	v_sub_f32_e32 v43, v43, v81
	v_add_f32_e32 v43, v43, v78
	v_exp_f32_e32 v43, v43
	v_cvt_i32_f32_e32 v78, v81
	v_cmp_ngt_f32_e32 vcc, s0, v42
	v_cndmask_b32_e64 v81, 0, |v80|, s[48:49]
	v_add_f32_e64 v81, |v83|, v81
	v_ldexp_f32 v43, v43, v78
	v_cndmask_b32_e32 v43, 0, v43, vcc
	v_cmp_nlt_f32_e32 vcc, s1, v42
	v_add_f32_e32 v38, v38, v81
	v_cndmask_b32_e64 v37, 0, |v86|, s[46:47]
	v_cndmask_b32_e32 v42, v244, v43, vcc
	v_mul_f32_e64 v43, v72, |v91|
	v_mul_f32_e32 v84, v42, v46
	v_mul_f32_e32 v46, 0x3fb8aa3b, v43
	v_mul_f32_e32 v78, v42, v47
	v_fma_f32 v47, v43, s92, -v46
	v_rndne_f32_e32 v81, v46
	v_fmac_f32_e32 v47, 0x32a5705f, v43
	v_sub_f32_e32 v46, v46, v81
	v_add_f32_e32 v46, v46, v47
	v_exp_f32_e32 v46, v46
	v_cvt_i32_f32_e32 v47, v81
	v_cmp_ngt_f32_e32 vcc, s0, v43
	v_cndmask_b32_e64 v81, 0, |v78|, s[50:51]
	v_add_f32_e64 v81, |v84|, v81
	v_ldexp_f32 v46, v46, v47
	v_cndmask_b32_e32 v46, 0, v46, vcc
	v_cmp_nlt_f32_e32 vcc, s1, v43
	v_mul_f32_e64 v47, v73, |v91|
	v_add_f32_e32 v38, v38, v81
	v_cndmask_b32_e32 v43, v244, v46, vcc
	v_mul_f32_e32 v81, v43, v50
	v_mul_f32_e32 v50, v43, v51
	v_mul_f32_e32 v51, 0x3fb8aa3b, v47
	v_fma_f32 v87, v47, s92, -v51
	v_rndne_f32_e32 v88, v51
	v_fmac_f32_e32 v87, 0x32a5705f, v47
	v_sub_f32_e32 v51, v51, v88
	v_add_f32_e32 v51, v51, v87
	v_exp_f32_e32 v51, v51
	v_cvt_i32_f32_e32 v87, v88
	v_cndmask_b32_e64 v46, 0, |v50|, s[52:53]
	v_add_f32_e64 v46, |v81|, v46
	v_mul_f32_e32 v90, v82, v36
	v_add_f32_e64 v36, |v90|, v37
	v_add_f32_e32 v37, v38, v46
	v_ldexp_f32 v38, v51, v87
	v_cmp_ngt_f32_e32 vcc, s0, v47
	v_mul_f32_e32 v88, v39, v40
	v_mul_f32_e64 v40, v74, |v91|
	v_cndmask_b32_e32 v38, 0, v38, vcc
	v_cmp_nlt_f32_e32 vcc, s1, v47
	v_mul_f32_e32 v87, v39, v41
	v_mul_f32_e32 v41, 0x3fb8aa3b, v40
	v_cndmask_b32_e32 v38, v244, v38, vcc
	v_mul_f32_e32 v47, v38, v55
	v_fma_f32 v51, v40, s92, -v41
	v_rndne_f32_e32 v55, v41
	v_fmac_f32_e32 v51, 0x32a5705f, v40
	v_sub_f32_e32 v41, v41, v55
	v_add_f32_e32 v41, v41, v51
	v_exp_f32_e32 v41, v41
	v_cvt_i32_f32_e32 v51, v55
	v_cndmask_b32_e64 v39, 0, |v87|, s[48:49]
	v_add_f32_e64 v39, |v88|, v39
	v_add_f32_e32 v36, v36, v39
	v_ldexp_f32 v39, v41, v51
	v_cmp_ngt_f32_e32 vcc, s0, v40
	v_mul_f32_e32 v82, v38, v52
	v_mul_f32_e32 v89, v42, v44
	v_cndmask_b32_e32 v39, 0, v39, vcc
	v_cmp_nlt_f32_e32 vcc, s1, v40
	v_mul_f32_e32 v54, v38, v54
	v_cndmask_b32_e64 v46, 0, |v47|, s[54:55]
	v_cndmask_b32_e32 v39, v244, v39, vcc
	v_mul_f32_e32 v52, v39, v58
	v_mul_f32_e32 v58, v42, v45
	v_cndmask_b32_e64 v41, 0, |v58|, s[50:51]
	v_add_f32_e64 v41, |v89|, v41
	v_mul_f32_e64 v42, v75, |v91|
	v_add_f32_e32 v41, v36, v41
	v_mul_f32_e32 v36, 0x3fb8aa3b, v42
	v_fma_f32 v44, v42, s92, -v36
	v_rndne_f32_e32 v45, v36
	v_fmac_f32_e32 v44, 0x32a5705f, v42
	v_sub_f32_e32 v36, v36, v45
	v_add_f32_e32 v36, v36, v44
	v_add_f32_e64 v46, |v54|, v46
	v_exp_f32_e32 v44, v36
	v_cvt_i32_f32_e32 v45, v45
	v_add_f32_e32 v37, v37, v46
	v_mul_f32_e32 v46, v39, v59
	v_cndmask_b32_e64 v40, 0, |v46|, s[56:57]
	v_mul_f32_e32 v55, v38, v53
	v_add_f32_e64 v40, |v52|, v40
	v_cndmask_b32_e64 v38, 0, |v55|, s[54:55]
	v_add_f32_e64 v36, |v82|, v38
	v_add_f32_e32 v38, v37, v40
	v_ldexp_f32 v37, v44, v45
	v_cmp_ngt_f32_e32 vcc, s0, v42
	v_mul_f32_e32 v53, v39, v56
	v_mul_f32_e32 v56, v43, v49
	v_cndmask_b32_e32 v37, 0, v37, vcc
	v_cmp_nlt_f32_e32 vcc, s1, v42
	v_mul_f32_e32 v59, v43, v48
	v_mul_f32_e32 v48, v39, v57
	v_cndmask_b32_e32 v92, v244, v37, vcc
	v_mul_f32_e32 v44, v92, v63
	v_mul_f32_e32 v51, v92, v62
	v_cndmask_b32_e64 v37, 0, |v44|, s[58:59]
	v_add_f32_e64 v40, |v51|, v37
	v_cndmask_b32_e64 v37, 0, |v56|, s[52:53]
	v_add_f32_e64 v42, |v59|, v37
	v_mul_f32_e64 v39, v76, |v91|
	v_cndmask_b32_e64 v37, 0, |v48|, s[56:57]
	v_add_f32_e32 v42, v41, v42
	v_and_b32_e32 v43, 0x7fffffff, v53
	v_mul_f32_e32 v41, 0x3fb8aa3b, v39
	v_pk_add_f32 v[36:37], v[42:43], v[36:37]
	v_fma_f32 v42, v39, s92, -v41
	v_rndne_f32_e32 v43, v41
	v_fmac_f32_e32 v42, 0x32a5705f, v39
	v_sub_f32_e32 v41, v41, v43
	v_add_f32_e32 v41, v41, v42
	v_exp_f32_e32 v42, v41
	v_cvt_i32_f32_e32 v43, v43
	v_pk_add_f32 v[36:37], v[36:37], v[36:37] op_sel_hi:[0,1]
	v_cmp_ngt_f32_e32 vcc, s0, v39
	v_mul_f32_e32 v45, v92, v61
	v_ldexp_f32 v36, v42, v43
	v_cndmask_b32_e32 v36, 0, v36, vcc
	v_cmp_nlt_f32_e32 vcc, s1, v39
	v_mov_b32_e32 v39, v239
	v_cndmask_b32_e64 v61, 0, |v45|, s[58:59]
	v_lshlrev_b32_e32 v57, 2, v39
	v_mov_b32_e32 v39, v239
	v_mul_f32_e32 v49, v92, v60
	v_add_f32_e64 v41, |v49|, v61
	v_cndmask_b32_e32 v36, v244, v36, vcc
	v_lshlrev_b32_e32 v63, 2, v39
	v_mov_b32_e32 v39, v37
	v_pk_add_f32 v[40:41], v[38:39], v[40:41]
	v_pk_mul_f32 v[38:39], v[36:37], v[66:67] op_sel_hi:[0,1]
	v_pk_mul_f32 v[36:37], v[36:37], v[64:65] op_sel_hi:[0,1]
	v_and_b32_e32 v43, 0x7fffffff, v39
	v_and_b32_e32 v42, 0x7fffffff, v38
	v_cndmask_b32_e64 v61, 0, |v37|, s[60:61]
	v_cndmask_b32_e64 v60, 0, |v36|, s[60:61]
	v_pk_add_f32 v[42:43], v[42:43], v[60:61]
	v_xor_b32_e32 v62, 0x80, v57
	v_xor_b32_e32 v91, 0x80, v63
	v_pk_add_f32 v[40:41], v[40:41], v[42:43]
	ds_bpermute_b32 v42, v62, v40
	ds_bpermute_b32 v43, v91, v41
	v_xor_b32_e32 v60, 64, v57
	v_xor_b32_e32 v61, 64, v63
	s_waitcnt lgkmcnt(0)
; __device__ __forceinline__ int olane() { int l = __builtin_amdgcn_mbcnt_hi(-1, __builtin_amdgcn_mbcnt_lo(-1, 0)); asm volatile("" : "+v"(l)); return l; }
; __device__ __forceinline__ float bperm_f(int addr, float v) { return __uint_as_float((unsigned)__builtin_amdgcn_ds_bpermute(addr, (int)__float_as_uint(v))); }
; __device__ __forceinline__ float wave_sum(float v) { const int l = olane();
; #pragma unroll
;     for (int o = 32; o >= 1; o >>= 1) v += bperm_f((l ^ o) << 2, v);
;     return v; }
; __device__ void ph_filter_gen(const Params& P, int j, const float* __restrict__ a3, float* __restrict__ kf, float* sl) {
;     ...
;         n0 = wave_sum(n0); n1 = wave_sum(n1);
;         if (lane == 0) { red[wid * 2] = n0; red[wid * 2 + 1] = n1; }
	v_pk_add_f32 v[40:41], v[40:41], v[42:43]
	ds_bpermute_b32 v42, v60, v40
	ds_bpermute_b32 v43, v61, v41
	v_xor_b32_e32 v60, 32, v57
	v_xor_b32_e32 v61, 32, v63
	s_waitcnt lgkmcnt(0)
	v_pk_add_f32 v[40:41], v[40:41], v[42:43]
	ds_bpermute_b32 v42, v60, v40
	ds_bpermute_b32 v43, v61, v41
	v_xor_b32_e32 v60, 16, v57
	v_xor_b32_e32 v61, 16, v63
	s_waitcnt lgkmcnt(0)
	v_pk_add_f32 v[40:41], v[40:41], v[42:43]
	ds_bpermute_b32 v42, v60, v40
	ds_bpermute_b32 v43, v61, v41
	v_xor_b32_e32 v60, 8, v57
	v_xor_b32_e32 v61, 8, v63
	v_xor_b32_e32 v57, 4, v57
	s_waitcnt lgkmcnt(0)
	v_pk_add_f32 v[40:41], v[40:41], v[42:43]
	ds_bpermute_b32 v42, v60, v40
	ds_bpermute_b32 v43, v61, v41
	s_waitcnt lgkmcnt(0)
	v_pk_add_f32 v[40:41], v[40:41], v[42:43]
	v_xor_b32_e32 v43, 4, v63
	ds_bpermute_b32 v42, v57, v40
	ds_bpermute_b32 v43, v43, v41
	s_and_saveexec_b64 s[10:11], s[42:43]
	s_cbranch_execz .LBB0_238
	s_waitcnt lgkmcnt(0)
	v_pk_add_f32 v[40:41], v[40:41], v[42:43]
	ds_write2_b32 v77, v40, v41 offset1:1

; __device__ __forceinline__ uint4 ntld_u4(const void* p) { const ntu4_t v = __builtin_nontemporal_load((const ntu4_t*)p); return make_uint4(v.x, v.y, v.z, v.w); }
; __device__ void ph_transpose_ya(const bf16_t* __restrict__ yaT, bf16_t* __restrict__ yA, bf16_t* sl) {
;     ...
;     int tile = blockIdx.x; if (tile >= 16 * 512) return;
;     uint4 v = ntld_u4(yaT + (size_t)((tile & 15) * 64 + cc) * T_TOK + (tile >> 4) * 64 + t8 * 8);
;     for (;;) {
;         const int c0 = (tile & 15) * 64, t0 = (tile >> 4) * 64;
;         { const bf16_t* e = (const bf16_t*)&v;
; #pragma unroll
;           for (int jx = 0; jx < 8; ++jx) sl[cc * 66 + t8 * 8 + jx] = e[jx]; }
;         __syncthreads();
;         const int tn = tile + gridDim.x; const bool more = tn < 16 * 512;
;         if (more) v = ntld_u4(yaT + (size_t)((tn & 15) * 64 + cc) * T_TOK + (tn >> 4) * 64 + t8 * 8);
.LBB0_480:
	s_and_b64 vcc, exec, s[40:41]
	v_readlane_b32 s17, v254, 63
	v_readlane_b32 s18, v255, 2
	s_cbranch_vccnz .LBB0_488
	v_readlane_b32 s0, v254, 12
	v_readlane_b32 s1, v254, 13
	v_mov_b32_e32 v0, v195
	s_andn2_b64 vcc, exec, s[0:1]
	s_waitcnt vmcnt(0)
	s_barrier
	s_cbranch_vccnz .LBB0_488
	v_ashrrev_i32_e32 v4, 3, v0
	v_readlane_b32 s0, v254, 16
	v_lshlrev_b32_e32 v0, 3, v0
	v_and_b32_e32 v8, 56, v0
	v_add_u32_e32 v2, s0, v4
	v_ashrrev_i32_e32 v3, 31, v2
	v_readlane_b32 s0, v254, 19
	v_lshlrev_b64 v[2:3], 16, v[2:3]
	v_readlane_b32 s1, v254, 20
	v_lshlrev_b32_e32 v192, 1, v8
	v_mul_u32_u24_e32 v6, 0x42, v8
	v_lshl_add_u64 v[2:3], s[0:1], 0, v[2:3]
	v_lshl_add_u64 v[0:1], v[2:3], 0, v[192:193]
	global_load_dwordx4 v[0:3], v[0:1], off nt
	s_movk_i32 s0, 0x84
	v_mul_lo_u32 v5, v4, s0
	v_lshlrev_b32_e32 v7, 1, v4
	v_lshlrev_b32_e32 v9, 1, v6
	v_add3_u32 v5, 0, v5, v192
	v_add3_u32 v6, 0, v7, v9
	v_add3_u32 v7, 0, v9, v7
	v_lshlrev_b32_e32 v192, 1, v8
	v_readlane_b32 s14, v254, 14
	v_readlane_b32 s15, v254, 15
	s_mov_b32 s0, s2
	s_waitcnt vmcnt(0)
	s_branch .LBB0_484

; __device__ __forceinline__ uint4 ntld_u4(const void* p) { const ntu4_t v = __builtin_nontemporal_load((const ntu4_t*)p); return make_uint4(v.x, v.y, v.z, v.w); }
; __device__ void ph_transpose_ya(const bf16_t* __restrict__ yaT, bf16_t* __restrict__ yA, bf16_t* sl) {
;     ...
;         const int c0 = (tile & 15) * 64, t0 = (tile >> 4) * 64;
;         { const bf16_t* e = (const bf16_t*)&v;
; #pragma unroll
;           for (int jx = 0; jx < 8; ++jx) sl[cc * 66 + t8 * 8 + jx] = e[jx]; }
;         __syncthreads();
;         const int tn = tile + gridDim.x; const bool more = tn < 16 * 512;
;         if (more) v = ntld_u4(yaT + (size_t)((tn & 15) * 64 + cc) * T_TOK + (tn >> 4) * 64 + t8 * 8);
;         { const int tt = tid >> 3, c8 = tid & 7; unsigned w[4];
; #pragma unroll
;           for (int jx = 0; jx < 4; ++jx) w[jx] = (unsigned)sl[(c8 * 8 + 2 * jx) * 66 + tt] | ((unsigned)sl[(c8 * 8 + 2 * jx + 1) * 66 + tt] << 16);
;           *(uint4*)(yA + (size_t)(t0 + tt) * DM + c0 + c8 * 8) = make_uint4(w[0], w[1], w[2], w[3]); }
;         asm volatile("s_waitcnt lgkmcnt(0)\n\ts_barrier" ::: "memory");
.LBB0_484:
	s_add_i32 s0, s0, s22
	s_cmpk_gt_i32 s0, 0x1fff
	s_cselect_b64 s[6:7], -1, 0
	s_cmpk_lt_i32 s0, 0x2000
	s_mov_b64 s[10:11], -1
	s_waitcnt vmcnt(1)
	ds_write2_b32 v5, v0, v1 offset1:1
	ds_write2_b32 v5, v2, v3 offset0:2 offset1:3
	s_waitcnt lgkmcnt(0)
	s_barrier
	s_cbranch_scc1 .LBB0_486
	s_add_i32 s1, s15, s18
	s_add_i32 s12, s14, s17
	s_mov_b64 s[10:11], 0
